# de-serialized load chains: sample-attn Q frags preloaded to regs; P4 epilogue tile loads batched; past-cache conversion loads batched
# speedup vs baseline: 1.0195x; 1.0195x over previous
; DEV u16 f2bf(float f) { return (u16)(pk2bf(f, 0.f) & 0xffffu); }
; DEV void cache_item(const Params& p, int l, int item, unsigned char* smem) {
;     ...
;     for (int e = tid; e < 64 * 128; e += NT) {
;       int key = e >> 7, d = e & 127;
;       float v = src[(size_t)key * 256 + dh * 128 + d];
;       s[key * 129 + d] = v;
;       SKV[(size_t)(kt * 64 + key) * 320 + dh * 128 + d] = f2bf(v);
;     }
.LBB0_782:
	v_ashrrev_i32_e32 v56, 7, v16
	v_ashrrev_i32_e32 v57, 31, v56
	v_lshlrev_b64 v[60:61], 10, v[56:57]
	v_lshl_add_u64 v[60:61], v[12:13], 0, v[60:61]
	v_mad_u64_u32 v[58:59], s[36:37], v56, s23, v[224:225]
	v_add_u32_e32 v54, s12, v56
	v_mad_i64_i32 v[54:55], s[36:37], v54, s22, v[14:15]
	global_load_dword v64, v[60:61], off
	global_load_dword v65, v[60:61], off offset:2048
	v_add_co_u32_e32 v60, vcc, 0x1000, v60
	s_nop 1
	v_addc_co_u32_e32 v61, vcc, 0, v61, vcc
	global_load_dword v66, v[60:61], off
	global_load_dword v67, v[60:61], off offset:2048
	v_add_co_u32_e32 v60, vcc, 0x1000, v60
	s_nop 1
	v_addc_co_u32_e32 v61, vcc, 0, v61, vcc
	global_load_dword v68, v[60:61], off
	global_load_dword v69, v[60:61], off offset:2048
	v_add_co_u32_e32 v60, vcc, 0x1000, v60
	s_nop 1
	v_addc_co_u32_e32 v61, vcc, 0, v61, vcc
	global_load_dword v70, v[60:61], off
	global_load_dword v71, v[60:61], off offset:2048
	v_add_co_u32_e32 v60, vcc, 0x1000, v60
	s_nop 1
	v_addc_co_u32_e32 v61, vcc, 0, v61, vcc
	global_load_dword v72, v[60:61], off
	global_load_dword v73, v[60:61], off offset:2048
	v_add_co_u32_e32 v60, vcc, 0x1000, v60
	s_nop 1
	v_addc_co_u32_e32 v61, vcc, 0, v61, vcc
	global_load_dword v74, v[60:61], off
	global_load_dword v75, v[60:61], off offset:2048
	v_add_co_u32_e32 v60, vcc, 0x1000, v60
	s_nop 1
	v_addc_co_u32_e32 v61, vcc, 0, v61, vcc
	global_load_dword v76, v[60:61], off
	global_load_dword v77, v[60:61], off offset:2048
	v_add_co_u32_e32 v60, vcc, 0x1000, v60
	s_nop 1
	v_addc_co_u32_e32 v61, vcc, 0, v61, vcc
	global_load_dword v78, v[60:61], off
	global_load_dword v79, v[60:61], off offset:2048
	v_add_co_u32_e32 v60, vcc, 0x1000, v60
	s_nop 1
	v_addc_co_u32_e32 v61, vcc, 0, v61, vcc
	global_load_dword v80, v[60:61], off
	global_load_dword v81, v[60:61], off offset:2048
	v_add_co_u32_e32 v60, vcc, 0x1000, v60
	s_nop 1
	v_addc_co_u32_e32 v61, vcc, 0, v61, vcc
	global_load_dword v82, v[60:61], off
	global_load_dword v83, v[60:61], off offset:2048
	v_add_co_u32_e32 v60, vcc, 0x1000, v60
	s_nop 1
	v_addc_co_u32_e32 v61, vcc, 0, v61, vcc
	global_load_dword v84, v[60:61], off
	global_load_dword v85, v[60:61], off offset:2048
	v_add_co_u32_e32 v60, vcc, 0x1000, v60
	s_nop 1
	v_addc_co_u32_e32 v61, vcc, 0, v61, vcc
	global_load_dword v86, v[60:61], off
	global_load_dword v87, v[60:61], off offset:2048
	v_add_co_u32_e32 v60, vcc, 0x1000, v60
	s_nop 1
	v_addc_co_u32_e32 v61, vcc, 0, v61, vcc
	global_load_dword v88, v[60:61], off
	global_load_dword v89, v[60:61], off offset:2048
	v_add_co_u32_e32 v60, vcc, 0x1000, v60
	s_nop 1
	v_addc_co_u32_e32 v61, vcc, 0, v61, vcc
	global_load_dword v90, v[60:61], off
	global_load_dword v91, v[60:61], off offset:2048
	v_add_co_u32_e32 v60, vcc, 0x1000, v60
	s_nop 1
	v_addc_co_u32_e32 v61, vcc, 0, v61, vcc
	global_load_dword v92, v[60:61], off
	global_load_dword v93, v[60:61], off offset:2048
	v_add_co_u32_e32 v60, vcc, 0x1000, v60
	s_nop 1
	v_addc_co_u32_e32 v61, vcc, 0, v61, vcc
	global_load_dword v94, v[60:61], off
	global_load_dword v95, v[60:61], off offset:2048
	s_waitcnt vmcnt(31)
	ds_write_b32 v58, v64
	s_waitcnt vmcnt(30)
	ds_write_b32 v58, v65 offset:1032
	s_waitcnt vmcnt(29)
	ds_write_b32 v58, v66 offset:2064
	s_waitcnt vmcnt(28)
	ds_write_b32 v58, v67 offset:3096
	s_waitcnt vmcnt(27)
	ds_write_b32 v58, v68 offset:4128
	s_waitcnt vmcnt(26)
	ds_write_b32 v58, v69 offset:5160
	s_waitcnt vmcnt(25)
	ds_write_b32 v58, v70 offset:6192
	s_waitcnt vmcnt(24)
	ds_write_b32 v58, v71 offset:7224
	s_waitcnt vmcnt(23)
	ds_write_b32 v58, v72 offset:8256
	s_waitcnt vmcnt(22)
	ds_write_b32 v58, v73 offset:9288
	s_waitcnt vmcnt(21)
	ds_write_b32 v58, v74 offset:10320
	s_waitcnt vmcnt(20)
	ds_write_b32 v58, v75 offset:11352
	s_waitcnt vmcnt(19)
	ds_write_b32 v58, v76 offset:12384
	s_waitcnt vmcnt(18)
	ds_write_b32 v58, v77 offset:13416
	s_waitcnt vmcnt(17)
	ds_write_b32 v58, v78 offset:14448
	s_waitcnt vmcnt(16)
	ds_write_b32 v58, v79 offset:15480
	s_waitcnt vmcnt(15)
	ds_write_b32 v58, v80 offset:16512
	s_waitcnt vmcnt(14)
	ds_write_b32 v58, v81 offset:17544
	s_waitcnt vmcnt(13)
	ds_write_b32 v58, v82 offset:18576
	s_waitcnt vmcnt(12)
	ds_write_b32 v58, v83 offset:19608
	s_waitcnt vmcnt(11)
; DEV u16 f2bf(float f) { return (u16)(pk2bf(f, 0.f) & 0xffffu); }
; DEV void cache_item(const Params& p, int l, int item, unsigned char* smem) {
;     ...
;     for (int e = tid; e < 64 * 128; e += NT) {
;       int key = e >> 7, d = e & 127;
;       float v = src[(size_t)key * 256 + dh * 128 + d];
;       s[key * 129 + d] = v;
;       SKV[(size_t)(kt * 64 + key) * 320 + dh * 128 + d] = f2bf(v);
;     }
	ds_write_b32 v58, v84 offset:20640
	s_waitcnt vmcnt(10)
	ds_write_b32 v58, v85 offset:21672
	s_waitcnt vmcnt(9)
	ds_write_b32 v58, v86 offset:22704
	s_waitcnt vmcnt(8)
	ds_write_b32 v58, v87 offset:23736
	s_waitcnt vmcnt(7)
	ds_write_b32 v58, v88 offset:24768
	s_waitcnt vmcnt(6)
	ds_write_b32 v58, v89 offset:25800
	s_waitcnt vmcnt(5)
	ds_write_b32 v58, v90 offset:26832
	s_waitcnt vmcnt(4)
	ds_write_b32 v58, v91 offset:27864
	s_waitcnt vmcnt(3)
	ds_write_b32 v58, v92 offset:28896
	s_waitcnt vmcnt(2)
	ds_write_b32 v58, v93 offset:29928
	s_waitcnt vmcnt(1)
	ds_write_b32 v58, v94 offset:30960
	s_waitcnt vmcnt(0)
	ds_write_b32 v58, v95 offset:31992
	v_cvt_pk_bf16_f32 v53, v64, v65
	global_store_short v[54:55], v53, off
	global_store_short_d16_hi v[54:55], v53, off offset:1280
	v_add_co_u32_e32 v54, vcc, 0xa00, v54
	s_nop 1
	v_addc_co_u32_e32 v55, vcc, 0, v55, vcc
	v_cvt_pk_bf16_f32 v53, v66, v67
	global_store_short v[54:55], v53, off
	global_store_short_d16_hi v[54:55], v53, off offset:1280
	v_add_co_u32_e32 v54, vcc, 0xa00, v54
	s_nop 1
	v_addc_co_u32_e32 v55, vcc, 0, v55, vcc
	v_cvt_pk_bf16_f32 v53, v68, v69
	global_store_short v[54:55], v53, off
	global_store_short_d16_hi v[54:55], v53, off offset:1280
	v_add_co_u32_e32 v54, vcc, 0xa00, v54
	s_nop 1
	v_addc_co_u32_e32 v55, vcc, 0, v55, vcc
	v_cvt_pk_bf16_f32 v53, v70, v71
	global_store_short v[54:55], v53, off
	global_store_short_d16_hi v[54:55], v53, off offset:1280
	v_add_co_u32_e32 v54, vcc, 0xa00, v54
	s_nop 1
	v_addc_co_u32_e32 v55, vcc, 0, v55, vcc
	v_cvt_pk_bf16_f32 v53, v72, v73
	global_store_short v[54:55], v53, off
	global_store_short_d16_hi v[54:55], v53, off offset:1280
	v_add_co_u32_e32 v54, vcc, 0xa00, v54
	s_nop 1
	v_addc_co_u32_e32 v55, vcc, 0, v55, vcc
	v_cvt_pk_bf16_f32 v53, v74, v75
	global_store_short v[54:55], v53, off
	global_store_short_d16_hi v[54:55], v53, off offset:1280
	v_add_co_u32_e32 v54, vcc, 0xa00, v54
	s_nop 1
	v_addc_co_u32_e32 v55, vcc, 0, v55, vcc
	v_cvt_pk_bf16_f32 v53, v76, v77
	global_store_short v[54:55], v53, off
	global_store_short_d16_hi v[54:55], v53, off offset:1280
	v_add_co_u32_e32 v54, vcc, 0xa00, v54
	s_nop 1
	v_addc_co_u32_e32 v55, vcc, 0, v55, vcc
	v_cvt_pk_bf16_f32 v53, v78, v79
	global_store_short v[54:55], v53, off
	global_store_short_d16_hi v[54:55], v53, off offset:1280
	v_add_co_u32_e32 v54, vcc, 0xa00, v54
	s_nop 1
	v_addc_co_u32_e32 v55, vcc, 0, v55, vcc
	v_cvt_pk_bf16_f32 v53, v80, v81
	global_store_short v[54:55], v53, off
	global_store_short_d16_hi v[54:55], v53, off offset:1280
	v_add_co_u32_e32 v54, vcc, 0xa00, v54
	s_nop 1
	v_addc_co_u32_e32 v55, vcc, 0, v55, vcc
	v_cvt_pk_bf16_f32 v53, v82, v83
	global_store_short v[54:55], v53, off
	global_store_short_d16_hi v[54:55], v53, off offset:1280
	v_add_co_u32_e32 v54, vcc, 0xa00, v54
	s_nop 1
	v_addc_co_u32_e32 v55, vcc, 0, v55, vcc
	v_cvt_pk_bf16_f32 v53, v84, v85
	global_store_short v[54:55], v53, off
	global_store_short_d16_hi v[54:55], v53, off offset:1280
	v_add_co_u32_e32 v54, vcc, 0xa00, v54
	s_nop 1
	v_addc_co_u32_e32 v55, vcc, 0, v55, vcc
	v_cvt_pk_bf16_f32 v53, v86, v87
	global_store_short v[54:55], v53, off
	global_store_short_d16_hi v[54:55], v53, off offset:1280
	v_add_co_u32_e32 v54, vcc, 0xa00, v54
	s_nop 1
	v_addc_co_u32_e32 v55, vcc, 0, v55, vcc
	v_cvt_pk_bf16_f32 v53, v88, v89
	global_store_short v[54:55], v53, off
	global_store_short_d16_hi v[54:55], v53, off offset:1280
	v_add_co_u32_e32 v54, vcc, 0xa00, v54
	s_nop 1
	v_addc_co_u32_e32 v55, vcc, 0, v55, vcc
	v_cvt_pk_bf16_f32 v53, v90, v91
	global_store_short v[54:55], v53, off
	global_store_short_d16_hi v[54:55], v53, off offset:1280
	v_add_co_u32_e32 v54, vcc, 0xa00, v54
	s_nop 1
	v_addc_co_u32_e32 v55, vcc, 0, v55, vcc
	v_cvt_pk_bf16_f32 v53, v92, v93
	global_store_short v[54:55], v53, off
	global_store_short_d16_hi v[54:55], v53, off offset:1280
	v_add_co_u32_e32 v54, vcc, 0xa00, v54
	s_nop 1
	v_addc_co_u32_e32 v55, vcc, 0, v55, vcc
	v_cvt_pk_bf16_f32 v53, v94, v95
	global_store_short v[54:55], v53, off
	global_store_short_d16_hi v[54:55], v53, off offset:1280
	s_mov_b64 s[92:93], exec
	s_or_b64 exec, exec, s[92:93]
	s_orn2_b64 s[36:37], s[6:7], exec
	v_mov_b32_e32 v1, v52

; DEV u16 f2bf(float f) { return (u16)(pk2bf(f, 0.f) & 0xffffu); }
; DEV void cache_item(const Params& p, int l, int item, unsigned char* smem) {
;     ...
;   for (int e = tid; e < 64 * 64; e += NT) {
;     int key = e >> 6, d = e & 63;
;     SKV[(size_t)(kt * 64 + key) * 320 + 256 + d] = f2bf(srck[(size_t)key * 64 + d]);
;   }
.LBB0_791:
	v_ashrrev_i32_e32 v12, 6, v2
	v_ashrrev_i32_e32 v13, 31, v12
	v_lshlrev_b64 v[16:17], 8, v[12:13]
	v_lshl_add_u64 v[16:17], v[6:7], 0, v[16:17]
	v_add_u32_e32 v10, s12, v12
	v_mad_i64_i32 v[10:11], s[14:15], v10, s22, v[4:5]
	global_load_dword v64, v[16:17], off
	global_load_dword v65, v[16:17], off offset:1024
	global_load_dword v66, v[16:17], off offset:2048
	global_load_dword v67, v[16:17], off offset:3072
	v_add_co_u32_e32 v16, vcc, 0x1000, v16
	s_nop 1
	v_addc_co_u32_e32 v17, vcc, 0, v17, vcc
	global_load_dword v68, v[16:17], off
	global_load_dword v69, v[16:17], off offset:1024
	global_load_dword v70, v[16:17], off offset:2048
	global_load_dword v71, v[16:17], off offset:3072
	v_add_co_u32_e32 v16, vcc, 0x1000, v16
	s_nop 1
	v_addc_co_u32_e32 v17, vcc, 0, v17, vcc
	global_load_dword v72, v[16:17], off
	global_load_dword v73, v[16:17], off offset:1024
	global_load_dword v74, v[16:17], off offset:2048
	global_load_dword v75, v[16:17], off offset:3072
	v_add_co_u32_e32 v16, vcc, 0x1000, v16
	s_nop 1
	v_addc_co_u32_e32 v17, vcc, 0, v17, vcc
	global_load_dword v76, v[16:17], off
	global_load_dword v77, v[16:17], off offset:1024
	global_load_dword v78, v[16:17], off offset:2048
	global_load_dword v79, v[16:17], off offset:3072
	s_waitcnt vmcnt(14)
	v_cvt_pk_bf16_f32 v14, v64, v65
	global_store_short v[10:11], v14, off offset:512
	global_store_short_d16_hi v[10:11], v14, off offset:3072
	v_add_co_u32_e32 v10, vcc, 0x1400, v10
	s_nop 1
	v_addc_co_u32_e32 v11, vcc, 0, v11, vcc
	s_waitcnt vmcnt(14)
	v_cvt_pk_bf16_f32 v14, v66, v67
	global_store_short v[10:11], v14, off offset:512
	global_store_short_d16_hi v[10:11], v14, off offset:3072
	v_add_co_u32_e32 v10, vcc, 0x1400, v10
	s_nop 1
	v_addc_co_u32_e32 v11, vcc, 0, v11, vcc
	s_waitcnt vmcnt(14)
	v_cvt_pk_bf16_f32 v14, v68, v69
	global_store_short v[10:11], v14, off offset:512
	global_store_short_d16_hi v[10:11], v14, off offset:3072
	v_add_co_u32_e32 v10, vcc, 0x1400, v10
	s_nop 1
	v_addc_co_u32_e32 v11, vcc, 0, v11, vcc
	s_waitcnt vmcnt(14)
	v_cvt_pk_bf16_f32 v14, v70, v71
	global_store_short v[10:11], v14, off offset:512
	global_store_short_d16_hi v[10:11], v14, off offset:3072
	v_add_co_u32_e32 v10, vcc, 0x1400, v10
	s_nop 1
	v_addc_co_u32_e32 v11, vcc, 0, v11, vcc
	s_waitcnt vmcnt(14)
	v_cvt_pk_bf16_f32 v14, v72, v73
	global_store_short v[10:11], v14, off offset:512
	global_store_short_d16_hi v[10:11], v14, off offset:3072
	v_add_co_u32_e32 v10, vcc, 0x1400, v10
	s_nop 1
	v_addc_co_u32_e32 v11, vcc, 0, v11, vcc
	s_waitcnt vmcnt(14)
	v_cvt_pk_bf16_f32 v14, v74, v75
	global_store_short v[10:11], v14, off offset:512
	global_store_short_d16_hi v[10:11], v14, off offset:3072
	v_add_co_u32_e32 v10, vcc, 0x1400, v10
	s_nop 1
	v_addc_co_u32_e32 v11, vcc, 0, v11, vcc
	s_waitcnt vmcnt(14)
	v_cvt_pk_bf16_f32 v14, v76, v77
	global_store_short v[10:11], v14, off offset:512
	global_store_short_d16_hi v[10:11], v14, off offset:3072
	v_add_co_u32_e32 v10, vcc, 0x1400, v10
	s_nop 1
	v_addc_co_u32_e32 v11, vcc, 0, v11, vcc
	s_waitcnt vmcnt(14)
	v_cvt_pk_bf16_f32 v14, v78, v79
	global_store_short v[10:11], v14, off offset:512
	global_store_short_d16_hi v[10:11], v14, off offset:3072
	s_mov_b64 s[6:7], exec
	s_or_b64 exec, exec, s[6:7]
	v_cmp_ne_u32_e32 vcc, v1, v8
	v_lshl_add_u32 v4, v8, 8, v0
	s_orn2_b64 s[6:7], vcc, exec

; template <int DK, bool PF>
; DEV void attn_item(const u16* __restrict__ qrow, const u16* __restrict__ ka, int ldka, const u16* __restrict__ kb, int ldkb,
;                    const u16* __restrict__ vt, int ldvt, int ntiles, int my_tiles, int kvlen, u16* orow,
;                    unsigned char* smem) {
;     ...
;   const int tid = TIDX(), lane = tid & 63, hh = lane >> 5, l31 = lane & 31;
;   constexpr bool QREG = (DK <= 192);
;   bf16x8 qf[DK / 16];
;   if (QREG) {
; #pragma unroll
;     for (int ks = 0; ks < DK / 16; ++ks) qf[ks] = *(const bf16x8*)(qrow + ks * 16 + hh * 8);
;   }
;   f32x16 o[4];
; #pragma unroll
;   for (int d = 0; d < 4; ++d)
; #pragma unroll
;     for (int r = 0; r < 16; ++r) o[d][r] = 0.f;
;   float mrun = -1e30f, lrun = 0.f;
;   constexpr int CA = DKA / 32;
;   bf16x8 rk[CA + 2], rv[4];
;   const int skey = tid >> 2, sq = tid & 3;
;   const u16* gka = ka + (size_t)skey * ldka + sq * CA * 8;
;   const u16* gkb = kb + (size_t)skey * ldkb + sq * 16;
;   const u16* gv = vt + (size_t)(tid >> 1) * ldvt + (tid & 1) * 32;
;   u16* lka = sK + skey * KST + sq * CA * 8;
;   u16* lkb = sK + skey * KST + DKA + sq * 16;
;   u16* lv = sV + (tid >> 1) * VST + (tid & 1) * 32;
.LBB0_996:
	s_cmpk_lt_i32 s12, 0x100
	s_cbranch_scc1 .LBB0_995
	s_add_i32 s0, s12, 0xffffff00
	s_lshr_b32 s96, s0, 1
	s_lshl_b64 s[0:1], s[96:97], 4
	v_or_b32_e32 v120, s0, v112
	s_movk_i32 s0, 0x1400
	v_mad_u64_u32 v[0:1], s[4:5], v120, s0, v[114:115]
	v_mov_b32_e32 v2, 0x1400
	s_mul_i32 s0, s96, 0x14a000
	v_mov_b32_e32 v121, s1
	v_mad_u32_u24 v1, s1, v2, v1
	s_mul_hi_u32 s1, s96, 0x14a000
	s_add_u32 s0, s8, s0
	s_addc_u32 s1, s9, s1
	s_lshl_b32 s6, s12, 7
	s_lshl_b64 s[4:5], s[96:97], 8
	s_and_b32 s13, s6, 0x80
	s_or_b32 s4, s4, s13
	s_mul_i32 s6, s4, 0x1080
	s_mul_hi_u32 s4, s4, 0x1080
	s_mulk_i32 s5, 0x1080
	s_add_i32 s5, s4, s5
	v_mov_b32_e32 v6, v232
	s_add_u32 s4, s10, s6
	v_mov_b64_e32 v[2:3], s[0:1]
	v_ashrrev_i32_e32 v8, 2, v6
	v_and_b32_e32 v9, 3, v6
	s_addc_u32 s5, s11, s5
	v_mad_i64_i32 v[2:3], s[0:1], v8, s22, v[2:3]
	v_lshlrev_b32_e32 v224, 7, v9
	v_lshlrev_b32_e32 v4, 5, v9
	v_mov_b32_e32 v5, v225
	v_lshl_add_u64 v[122:123], v[2:3], 0, v[224:225]
	v_lshl_add_u64 v[124:125], v[2:3], 0, v[4:5]
	v_ashrrev_i32_e32 v10, 1, v6
	v_mov_b64_e32 v[2:3], s[4:5]
	v_lshlrev_b32_e32 v4, 6, v6
	v_bfe_u32 v7, v6, 5, 1
	v_mad_i64_i32 v[2:3], s[0:1], v10, s67, v[2:3]
	v_and_b32_e32 v4, 64, v4
	v_lshl_add_u64 v[126:127], v[2:3], 0, v[4:5]
	s_waitcnt vmcnt(10)
	v_mad_u64_u32 v[128:129], s[0:1], v8, s51, v[224:225]
	v_mul_i32_i24_e32 v2, 0xffffffa0, v9
	v_lshlrev_b32_e32 v224, 4, v7
	v_mov_b32_e32 v48, v225
	v_mov_b32_e32 v49, v225
	v_and_b32_e32 v119, 31, v6
	v_mad_u64_u32 v[130:131], s[0:1], v10, s52, v[4:5]
	v_lshlrev_b32_e32 v118, 3, v7
	s_waitcnt vmcnt(9)
	v_lshl_add_u64 v[132:133], v[0:1], 0, v[224:225]
	v_mov_b32_e32 v50, v225
	v_mov_b32_e32 v51, v225
	v_mov_b32_e32 v52, v225
	v_mov_b32_e32 v53, v225
	v_mov_b32_e32 v54, v225
	v_mov_b32_e32 v55, v225
	v_mov_b32_e32 v56, v225
	v_mov_b32_e32 v57, v225
	v_mov_b32_e32 v58, v225
	v_mov_b32_e32 v59, v225
	v_mov_b32_e32 v60, v225
	v_mov_b32_e32 v61, v225
	v_mov_b32_e32 v62, v225
	v_mov_b32_e32 v63, v225
	v_add_u32_e32 v137, v128, v2
	v_mov_b64_e32 v[32:33], v[48:49]
	v_mov_b64_e32 v[16:17], v[48:49]
	v_mov_b64_e32 v[0:1], v[48:49]
	v_mad_u32_u24 v131, v119, s52, v118
	s_mov_b32 s16, 0
	v_mov_b32_e32 v139, 0xf149f2ca
	v_mov_b32_e32 v129, 0
	v_mov_b64_e32 v[34:35], v[50:51]
	v_mov_b64_e32 v[36:37], v[52:53]
	v_mov_b64_e32 v[38:39], v[54:55]
	v_mov_b64_e32 v[40:41], v[56:57]
	v_mov_b64_e32 v[42:43], v[58:59]
	v_mov_b64_e32 v[44:45], v[60:61]
	v_mov_b64_e32 v[46:47], v[62:63]
	v_mov_b64_e32 v[18:19], v[50:51]
	v_mov_b64_e32 v[20:21], v[52:53]
	v_mov_b64_e32 v[22:23], v[54:55]
	v_mov_b64_e32 v[24:25], v[56:57]
	v_mov_b64_e32 v[26:27], v[58:59]
	v_mov_b64_e32 v[28:29], v[60:61]
	v_mov_b64_e32 v[30:31], v[62:63]
	v_mov_b64_e32 v[2:3], v[50:51]
	v_mov_b64_e32 v[4:5], v[52:53]
	v_mov_b64_e32 v[6:7], v[54:55]
	v_mov_b64_e32 v[8:9], v[56:57]
	v_mov_b64_e32 v[10:11], v[58:59]
	v_mov_b64_e32 v[12:13], v[60:61]
	v_mov_b64_e32 v[14:15], v[62:63]
	global_load_dwordx4 v[148:151], v[132:133], off offset:0
	global_load_dwordx4 v[152:155], v[132:133], off offset:32
	global_load_dwordx4 v[156:159], v[132:133], off offset:64
	global_load_dwordx4 v[160:163], v[132:133], off offset:96
	global_load_dwordx4 v[164:167], v[132:133], off offset:128
	global_load_dwordx4 v[168:171], v[132:133], off offset:160
	global_load_dwordx4 v[172:175], v[132:133], off offset:192
	global_load_dwordx4 v[176:179], v[132:133], off offset:224
	global_load_dwordx4 v[180:183], v[132:133], off offset:256
	global_load_dwordx4 v[184:187], v[132:133], off offset:288
	global_load_dwordx4 v[188:191], v[132:133], off offset:320
	global_load_dwordx4 v[192:195], v[132:133], off offset:352
	global_load_dwordx4 v[196:199], v[132:133], off offset:384
	global_load_dwordx4 v[200:203], v[132:133], off offset:416
	global_load_dwordx4 v[204:207], v[132:133], off offset:448
	global_load_dwordx4 v[208:211], v[132:133], off offset:480
	global_load_dwordx4 v[212:215], v[132:133], off offset:512
	global_load_dwordx4 v[216:219], v[132:133], off offset:544
	global_load_dwordx4 v[220:223], v[132:133], off offset:576
	global_load_dwordx4 v[226:229], v[132:133], off offset:608
	s_branch .LBB0_999

; template <int DK, bool PF>
; DEV void attn_item(const u16* __restrict__ qrow, const u16* __restrict__ ka, int ldka, const u16* __restrict__ kb, int ldkb,
;                    const u16* __restrict__ vt, int ldvt, int ntiles, int my_tiles, int kvlen, u16* orow,
;                    unsigned char* smem) {
;     ...
;         const u16* kp = sK + (mi * 32 + l31) * KST + hh * 8;
;         constexpr int KB = QREG ? 12 : 4;
; #pragma unroll
;         for (int k0 = 0; k0 < DK / 16; k0 += KB) {
;           bf16x8 kf[KB];
; #pragma unroll
;           for (int i = 0; i < KB; ++i) kf[i] = *(const bf16x8*)(kp + (k0 + i) * 16);
;           __builtin_amdgcn_sched_barrier(0);
; #pragma unroll
;           for (int i = 0; i < KB; ++i) {
;             bf16x8 qv;
;             if (QREG) qv = qf[k0 + i];
;             else qv = *(const bf16x8*)(qp + (k0 + i) * 16);
;             s = __builtin_amdgcn_mfma_f32_32x32x16_bf16(kf[i], qv, s, 0, 0, 0);
;           }
;         }
;         bf16x8 vf[8];
;         {
;           const u16* vp = sV + l31 * VST + mi * 32 + 4 * hh;
; #pragma unroll
;           for (int oc = 0; oc < 2; ++oc)
; #pragma unroll
;             for (int d = 0; d < 4; ++d) {
;               union { bf16x8 v; uint2 u[2]; } cv;
;               cv.u[0] = *(const uint2*)(vp + d * 32 * VST + oc * 16);
;               cv.u[1] = *(const uint2*)(vp + d * 32 * VST + oc * 16 + 8);
;               vf[oc * 4 + d] = cv.v;
;             }
;           __builtin_amdgcn_sched_barrier(0);
;         }
;         if (key0 + 64 > kvlen) {
; #pragma unroll
;           for (int r = 0; r < 16; ++r) {
;             int key = key0 + mi * 32 + (r & 3) + 8 * (r >> 2) + 4 * hh;
;             if (key >= kvlen) s[r] = -1e30f;
;           }
;         }
.LBB0_1001:
	v_or_b32_e32 v64, s17, v119
	v_mad_u32_u24 v100, v64, s51, v224
	ds_read_b128 v[64:67], v100
	ds_read_b128 v[80:83], v100 offset:32
	ds_read_b128 v[84:87], v100 offset:64
	ds_read_b128 v[88:91], v100 offset:96
	s_waitcnt vmcnt(0) lgkmcnt(0)
	v_mfma_f32_32x32x16_bf16 v[64:79], v[64:67], v[148:151], 0
	v_mfma_f32_32x32x16_bf16 v[64:79], v[80:83], v[152:155], v[64:79]
	s_waitcnt vmcnt(0) lgkmcnt(0)
	v_mfma_f32_32x32x16_bf16 v[64:79], v[84:87], v[156:159], v[64:79]
	s_waitcnt vmcnt(0) lgkmcnt(0)
	v_mfma_f32_32x32x16_bf16 v[64:79], v[88:91], v[160:163], v[64:79]
	ds_read_b128 v[80:83], v100 offset:128
	ds_read_b128 v[84:87], v100 offset:160
	ds_read_b128 v[88:91], v100 offset:192
	ds_read_b128 v[92:95], v100 offset:224
	s_waitcnt vmcnt(0) lgkmcnt(0)
	v_mfma_f32_32x32x16_bf16 v[64:79], v[80:83], v[164:167], v[64:79]
	s_waitcnt vmcnt(0) lgkmcnt(0)
	v_mfma_f32_32x32x16_bf16 v[64:79], v[84:87], v[168:171], v[64:79]
	s_waitcnt vmcnt(0) lgkmcnt(0)
	v_mfma_f32_32x32x16_bf16 v[64:79], v[88:91], v[172:175], v[64:79]
	s_waitcnt vmcnt(0) lgkmcnt(0)
	v_mfma_f32_32x32x16_bf16 v[64:79], v[92:95], v[176:179], v[64:79]
	ds_read_b128 v[80:83], v100 offset:256
	ds_read_b128 v[84:87], v100 offset:288
	ds_read_b128 v[88:91], v100 offset:320
	ds_read_b128 v[92:95], v100 offset:352
	s_waitcnt vmcnt(0) lgkmcnt(0)
	v_mfma_f32_32x32x16_bf16 v[64:79], v[80:83], v[180:183], v[64:79]
	s_waitcnt vmcnt(0) lgkmcnt(0)
	v_mfma_f32_32x32x16_bf16 v[64:79], v[84:87], v[184:187], v[64:79]
	s_waitcnt vmcnt(0) lgkmcnt(0)
	v_mfma_f32_32x32x16_bf16 v[64:79], v[88:91], v[188:191], v[64:79]
	s_waitcnt vmcnt(0) lgkmcnt(0)
	v_mfma_f32_32x32x16_bf16 v[64:79], v[92:95], v[192:195], v[64:79]
	ds_read_b128 v[80:83], v100 offset:384
	ds_read_b128 v[84:87], v100 offset:416
	ds_read_b128 v[88:91], v100 offset:448
	ds_read_b128 v[92:95], v100 offset:480
	s_waitcnt vmcnt(0) lgkmcnt(0)
	v_mfma_f32_32x32x16_bf16 v[64:79], v[80:83], v[196:199], v[64:79]
	s_waitcnt vmcnt(0) lgkmcnt(0)
	v_mfma_f32_32x32x16_bf16 v[64:79], v[84:87], v[200:203], v[64:79]
	s_waitcnt vmcnt(0) lgkmcnt(0)
	v_mfma_f32_32x32x16_bf16 v[64:79], v[88:91], v[204:207], v[64:79]
	s_waitcnt vmcnt(0) lgkmcnt(0)
	v_mfma_f32_32x32x16_bf16 v[64:79], v[92:95], v[208:211], v[64:79]
	ds_read_b128 v[80:83], v100 offset:512
	ds_read_b128 v[84:87], v100 offset:544
	ds_read_b128 v[92:95], v100 offset:576
	ds_read_b128 v[140:143], v100 offset:608
	s_waitcnt vmcnt(0) lgkmcnt(0)
	v_mfma_f32_32x32x16_bf16 v[64:79], v[80:83], v[212:215], v[64:79]
	v_mfma_f32_32x32x16_bf16 v[64:79], v[84:87], v[216:219], v[64:79]
	v_lshl_add_u32 v84, s17, 1, v131
	v_add_u32_e32 v85, 0xa000, v84
	ds_read2_b64 v[104:107], v85 offset0:128 offset1:130
	ds_read2_b64 v[88:91], v85 offset0:132 offset1:134
	v_add_u32_e32 v85, 0xb000, v84
	ds_read2_b64 v[108:111], v85 offset0:160 offset1:162
	s_waitcnt vmcnt(0) lgkmcnt(0)
	v_mfma_f32_32x32x16_bf16 v[64:79], v[92:95], v[220:223], v[64:79]
	v_add_u32_e32 v80, 0xc000, v84
	v_add_u32_e32 v81, 0xd000, v84
	ds_read2_b64 v[100:103], v80 offset0:192 offset1:194
	ds_read2_b64 v[96:99], v81 offset0:224 offset1:226
	ds_read2_b64 v[92:95], v85 offset0:164 offset1:166
	ds_read2_b64 v[84:87], v80 offset0:196 offset1:198
	ds_read2_b64 v[80:83], v81 offset0:228 offset1:230
	v_mfma_f32_32x32x16_bf16 v[64:79], v[140:143], v[226:229], v[64:79]
	s_andn2_b64 vcc, exec, s[0:1]
	s_cbranch_vccnz .LBB0_1003
	s_nop 9
	v_mov_b32_e32 v72, 0xf149f2ca
	v_cndmask_b32_e64 v64, v64, v72, s[6:7]
	v_cndmask_b32_e64 v65, v65, v72, s[6:7]
	v_cndmask_b32_e64 v66, v66, v72, s[6:7]
	v_cndmask_b32_e64 v67, v67, v72, s[6:7]
	v_cndmask_b32_e64 v68, v68, v72, s[6:7]
	v_cndmask_b32_e64 v69, v69, v72, s[6:7]
	v_cndmask_b32_e64 v70, v70, v72, s[6:7]
	v_cndmask_b32_e64 v71, v71, v72, s[6:7]
	v_mov_b32_e32 v73, v72
	v_mov_b32_e32 v74, v72
	v_mov_b32_e32 v75, v72
	v_mov_b32_e32 v76, v72
	v_mov_b32_e32 v77, v72
	v_mov_b32_e32 v78, v72
	v_mov_b32_e32 v79, v72

; DEV u16 f2bf(float f) { return (u16)(pk2bf(f, 0.f) & 0xffffu); }
; DEV float bf2f(u16 h) { return __uint_as_float(((unsigned)h) << 16); }
; DEV float siluf_(float x) { return x / (1.0f + __expf(-x)); }
; template <int MI>
; DEV void tile_load_t(unsigned char* smem, const u16* src, size_t lds_) {
;   u16* sC = (u16*)smem;
;   const int tid_ = TIDX();
; #pragma unroll
;   for (int i = 0; i < MI * 4; ++i) {
;     const int c = tid_ + 256 * i, row = c >> 4, cc = (c & 15) * 8;
;     *(bf16x8*)(sC + row * LDC + cc) = __builtin_nontemporal_load((const bf16x8*)(src + (size_t)row * lds_ + cc));
;   }
;   __syncthreads();
; template <int MI>
; DEV void p4_tile(const Params& p, int l, int m0, int nt, unsigned char* smem) {
;     ...
;     gemm_mm<MI>(acc, H + (size_t)m0 * 1024, 1024, WL + WO_G + (size_t)(1024 + nt * 128) * 1024, 1024, 1024, smem);
;     tile_load_t<MI>(smem, Q + (size_t)m0 * 1536 + nt * 192, 1536);
;     acc_foreach_t<MI>([&](int mi, int ni, int r, int row, int col) __attribute__((always_inline)) {
;       sC[row * LDC + col] = f2bf(bf2f(sC[row * LDC + col]) * siluf_(acc[mi][ni][r]));
.LBB0_1211:
	s_mul_hi_i32 s1, s0, 0xc00
	s_mulk_i32 s0, 0xc00
	s_add_u32 s0, s19, s0
	s_addc_u32 s1, s36, s1
	s_mul_i32 s6, s37, 0x180
	s_waitcnt vmcnt(8)
	v_mov_b32_e32 v136, v232
	s_barrier
	s_add_u32 s0, s0, s6
	s_addc_u32 s1, s1, 0
	v_lshlrev_b32_e32 v128, 4, v136
	v_and_b32_e32 v224, 0xf0, v128
	v_lshl_add_u64 v[128:129], s[0:1], 0, v[224:225]
	v_ashrrev_i32_e32 v134, 4, v136
	v_mad_i64_i32 v[204:205], s[0:1], v134, s41, v[128:129]
	v_mad_u64_u32 v[206:207], s[0:1], v134, s42, v[224:225]
	s_lshl_b32 s0, s41, 4
	s_mov_b32 s1, 0
	global_load_dwordx4 v[140:143], v[204:205], off nt
	v_lshl_add_u64 v[204:205], v[204:205], 0, s[0:1]
	global_load_dwordx4 v[144:147], v[204:205], off nt
	v_lshl_add_u64 v[204:205], v[204:205], 0, s[0:1]
	global_load_dwordx4 v[148:151], v[204:205], off nt
	v_lshl_add_u64 v[204:205], v[204:205], 0, s[0:1]
	global_load_dwordx4 v[152:155], v[204:205], off nt
	v_lshl_add_u64 v[204:205], v[204:205], 0, s[0:1]
	global_load_dwordx4 v[156:159], v[204:205], off nt
	v_lshl_add_u64 v[204:205], v[204:205], 0, s[0:1]
	global_load_dwordx4 v[160:163], v[204:205], off nt
	v_lshl_add_u64 v[204:205], v[204:205], 0, s[0:1]
	global_load_dwordx4 v[164:167], v[204:205], off nt
	v_lshl_add_u64 v[204:205], v[204:205], 0, s[0:1]
	global_load_dwordx4 v[168:171], v[204:205], off nt
	v_lshl_add_u64 v[204:205], v[204:205], 0, s[0:1]
	global_load_dwordx4 v[172:175], v[204:205], off nt
	v_lshl_add_u64 v[204:205], v[204:205], 0, s[0:1]
	global_load_dwordx4 v[176:179], v[204:205], off nt
	v_lshl_add_u64 v[204:205], v[204:205], 0, s[0:1]
	global_load_dwordx4 v[180:183], v[204:205], off nt
	v_lshl_add_u64 v[204:205], v[204:205], 0, s[0:1]
	global_load_dwordx4 v[184:187], v[204:205], off nt
	v_lshl_add_u64 v[204:205], v[204:205], 0, s[0:1]
	global_load_dwordx4 v[188:191], v[204:205], off nt
	v_lshl_add_u64 v[204:205], v[204:205], 0, s[0:1]
	global_load_dwordx4 v[192:195], v[204:205], off nt
	v_lshl_add_u64 v[204:205], v[204:205], 0, s[0:1]
	global_load_dwordx4 v[196:199], v[204:205], off nt
	v_lshl_add_u64 v[204:205], v[204:205], 0, s[0:1]
	global_load_dwordx4 v[200:203], v[204:205], off nt
	s_waitcnt vmcnt(15)
	ds_write_b128 v206, v[140:143]
	s_waitcnt vmcnt(14)
	ds_write_b128 v206, v[144:147] offset:4352
	s_waitcnt vmcnt(13)
	ds_write_b128 v206, v[148:151] offset:8704
	s_waitcnt vmcnt(12)
	ds_write_b128 v206, v[152:155] offset:13056
	s_waitcnt vmcnt(11)
	ds_write_b128 v206, v[156:159] offset:17408
	s_waitcnt vmcnt(10)
	ds_write_b128 v206, v[160:163] offset:21760
	s_waitcnt vmcnt(9)
	ds_write_b128 v206, v[164:167] offset:26112
	s_waitcnt vmcnt(8)
	ds_write_b128 v206, v[168:171] offset:30464
	s_waitcnt vmcnt(7)
	ds_write_b128 v206, v[172:175] offset:34816
	s_waitcnt vmcnt(6)
	ds_write_b128 v206, v[176:179] offset:39168
	s_waitcnt vmcnt(5)
	ds_write_b128 v206, v[180:183] offset:43520
	s_waitcnt vmcnt(4)
	ds_write_b128 v206, v[184:187] offset:47872
	s_waitcnt vmcnt(3)
	ds_write_b128 v206, v[188:191] offset:52224
	s_waitcnt vmcnt(2)
	ds_write_b128 v206, v[192:195] offset:56576
	s_waitcnt vmcnt(1)
	ds_write_b128 v206, v[196:199] offset:60928
	s_waitcnt vmcnt(0)
	ds_write_b128 v206, v[200:203] offset:65280
	v_mov_b32_e32 v128, v232
	s_waitcnt lgkmcnt(0)
	s_barrier
	s_nop 0
	v_and_b32_e32 v129, 0xfffff80, v128
	v_lshrrev_b32_e32 v130, 3, v128
	v_and_or_b32 v129, v130, 4, v129
	v_mul_f32_e32 v130, 0xbfb8aa3b, v112
	v_exp_f32_e32 v130, v130
	v_and_b32_e32 v128, 0x5f, v128
	v_mul_lo_u32 v129, v129, s42
	v_lshl_add_u32 v128, v128, 1, v129
	v_add_f32_e32 v130, 1.0, v130
	v_div_scale_f32 v131, s[0:1], v130, v130, v112
	v_rcp_f32_e32 v132, v131
	ds_read_u16 v129, v128
	v_fma_f32 v133, -v131, v132, 1.0
	v_fmac_f32_e32 v132, v133, v132
	v_div_scale_f32 v133, vcc, v112, v130, v112
	v_mul_f32_e32 v134, v133, v132
	v_fma_f32 v135, -v131, v134, v133
	v_fmac_f32_e32 v134, v135, v132
	v_fma_f32 v131, -v131, v134, v133
	v_div_fmas_f32 v131, v131, v132, v134
	s_waitcnt lgkmcnt(0)
	v_lshlrev_b32_e32 v129, 16, v129
	v_div_fixup_f32 v112, v131, v130, v112
	v_mul_f32_e32 v112, v112, v129
	v_mul_f32_e32 v129, 0xbfb8aa3b, v113
	v_exp_f32_e32 v129, v129
	v_cvt_pk_bf16_f32 v112, v112, s0
	ds_write_b16 v128, v112
	ds_read_u16 v112, v128 offset:272
	v_add_f32_e32 v129, 1.0, v129
	v_div_scale_f32 v130, s[0:1], v129, v129, v113
	v_rcp_f32_e32 v131, v130
	s_waitcnt lgkmcnt(0)
	v_lshlrev_b32_e32 v112, 16, v112
	v_fma_f32 v132, -v130, v131, 1.0
	v_fmac_f32_e32 v131, v132, v131
	v_div_scale_f32 v132, vcc, v113, v129, v113
	v_mul_f32_e32 v133, v132, v131
	v_fma_f32 v134, -v130, v133, v132
	v_fmac_f32_e32 v133, v134, v131
	v_fma_f32 v130, -v130, v133, v132
	v_div_fmas_f32 v130, v130, v131, v133
	v_div_fixup_f32 v113, v130, v129, v113
	v_mul_f32_e32 v112, v113, v112
	v_mul_f32_e32 v113, 0xbfb8aa3b, v114
	v_exp_f32_e32 v113, v113
	v_cvt_pk_bf16_f32 v112, v112, s0
	ds_write_b16 v128, v112 offset:272
	ds_read_u16 v112, v128 offset:544
	v_add_f32_e32 v113, 1.0, v113
	v_div_scale_f32 v129, s[0:1], v113, v113, v114
	v_rcp_f32_e32 v130, v129
	s_waitcnt lgkmcnt(0)
	v_lshlrev_b32_e32 v112, 16, v112
	v_fma_f32 v131, -v129, v130, 1.0
	v_fmac_f32_e32 v130, v131, v130
	v_div_scale_f32 v131, vcc, v114, v113, v114
	v_mul_f32_e32 v132, v131, v130
	v_fma_f32 v133, -v129, v132, v131
	v_fmac_f32_e32 v132, v133, v130
	v_fma_f32 v129, -v129, v132, v131
	v_div_fmas_f32 v129, v129, v130, v132
	v_div_fixup_f32 v113, v129, v113, v114
	v_mul_f32_e32 v112, v113, v112
	v_mul_f32_e32 v113, 0xbfb8aa3b, v115
	v_exp_f32_e32 v113, v113
	v_cvt_pk_bf16_f32 v112, v112, s0
	ds_write_b16 v128, v112 offset:544
	ds_read_u16 v112, v128 offset:816
	v_add_f32_e32 v113, 1.0, v113
	v_div_scale_f32 v114, s[0:1], v113, v113, v115
	v_rcp_f32_e32 v129, v114
	s_waitcnt lgkmcnt(0)
; DEV u16 f2bf(float f) { return (u16)(pk2bf(f, 0.f) & 0xffffu); }
; DEV float bf2f(u16 h) { return __uint_as_float(((unsigned)h) << 16); }
; DEV float siluf_(float x) { return x / (1.0f + __expf(-x)); }
; template <int MI>
; DEV void p4_tile(const Params& p, int l, int m0, int nt, unsigned char* smem) {
;     ...
;     acc_foreach_t<MI>([&](int mi, int ni, int r, int row, int col) __attribute__((always_inline)) {
;       sC[row * LDC + col] = f2bf(bf2f(sC[row * LDC + col]) * siluf_(acc[mi][ni][r]));
;     });
	v_lshlrev_b32_e32 v112, 16, v112
	v_fma_f32 v130, -v114, v129, 1.0
	v_fmac_f32_e32 v129, v130, v129
	v_div_scale_f32 v130, vcc, v115, v113, v115
	v_mul_f32_e32 v131, v130, v129
	v_fma_f32 v132, -v114, v131, v130
	v_fmac_f32_e32 v131, v132, v129
	v_fma_f32 v114, -v114, v131, v130
	v_div_fmas_f32 v114, v114, v129, v131
	v_div_fixup_f32 v113, v114, v113, v115
	v_mul_f32_e32 v112, v113, v112
	v_mul_f32_e32 v113, 0xbfb8aa3b, v116
	v_exp_f32_e32 v113, v113
	v_cvt_pk_bf16_f32 v112, v112, s0
	ds_write_b16 v128, v112 offset:816
	ds_read_u16 v112, v128 offset:2176
	v_add_f32_e32 v113, 1.0, v113
	v_div_scale_f32 v114, s[0:1], v113, v113, v116
	v_rcp_f32_e32 v115, v114
	s_waitcnt lgkmcnt(0)
	v_lshlrev_b32_e32 v112, 16, v112
	v_fma_f32 v129, -v114, v115, 1.0
	v_fmac_f32_e32 v115, v129, v115
	v_div_scale_f32 v129, vcc, v116, v113, v116
	v_mul_f32_e32 v130, v129, v115
	v_fma_f32 v131, -v114, v130, v129
	v_fmac_f32_e32 v130, v131, v115
	v_fma_f32 v114, -v114, v130, v129
	v_div_fmas_f32 v114, v114, v115, v130
	v_div_fixup_f32 v113, v114, v113, v116
	v_mul_f32_e32 v112, v113, v112
	v_mul_f32_e32 v113, 0xbfb8aa3b, v117
	v_exp_f32_e32 v113, v113
	v_cvt_pk_bf16_f32 v112, v112, s0
	ds_write_b16 v128, v112 offset:2176
	ds_read_u16 v112, v128 offset:2448
	v_add_f32_e32 v113, 1.0, v113
	v_div_scale_f32 v114, s[0:1], v113, v113, v117
	v_rcp_f32_e32 v115, v114
	s_waitcnt lgkmcnt(0)
	v_lshlrev_b32_e32 v112, 16, v112
	v_fma_f32 v116, -v114, v115, 1.0
	v_fmac_f32_e32 v115, v116, v115
	v_div_scale_f32 v116, vcc, v117, v113, v117
	v_mul_f32_e32 v129, v116, v115
	v_fma_f32 v130, -v114, v129, v116
	v_fmac_f32_e32 v129, v130, v115
	v_fma_f32 v114, -v114, v129, v116
	v_div_fmas_f32 v114, v114, v115, v129
	v_div_fixup_f32 v113, v114, v113, v117
	v_mul_f32_e32 v112, v113, v112
	v_mul_f32_e32 v113, 0xbfb8aa3b, v118
	v_exp_f32_e32 v113, v113
	v_cvt_pk_bf16_f32 v112, v112, s0
	ds_write_b16 v128, v112 offset:2448
	ds_read_u16 v112, v128 offset:2720
	v_add_f32_e32 v113, 1.0, v113
	v_div_scale_f32 v114, s[0:1], v113, v113, v118
	v_rcp_f32_e32 v115, v114
	s_waitcnt lgkmcnt(0)
	v_lshlrev_b32_e32 v112, 16, v112
	v_fma_f32 v116, -v114, v115, 1.0
	v_fmac_f32_e32 v115, v116, v115
	v_div_scale_f32 v116, vcc, v118, v113, v118
	v_mul_f32_e32 v117, v116, v115
	v_fma_f32 v129, -v114, v117, v116
	v_fmac_f32_e32 v117, v129, v115
	v_fma_f32 v114, -v114, v117, v116
	v_div_fmas_f32 v114, v114, v115, v117
	v_div_fixup_f32 v113, v114, v113, v118
	v_mul_f32_e32 v112, v113, v112
	v_mul_f32_e32 v113, 0xbfb8aa3b, v119
	v_exp_f32_e32 v113, v113
	v_cvt_pk_bf16_f32 v112, v112, s0
	ds_write_b16 v128, v112 offset:2720
	ds_read_u16 v112, v128 offset:2992
	v_add_f32_e32 v113, 1.0, v113
	v_div_scale_f32 v114, s[0:1], v113, v113, v119
	v_rcp_f32_e32 v115, v114
	s_waitcnt lgkmcnt(0)
	v_lshlrev_b32_e32 v112, 16, v112
	v_fma_f32 v116, -v114, v115, 1.0
	v_fmac_f32_e32 v115, v116, v115
	v_div_scale_f32 v116, vcc, v119, v113, v119
	v_mul_f32_e32 v117, v116, v115
	v_fma_f32 v118, -v114, v117, v116
	v_fmac_f32_e32 v117, v118, v115
	v_fma_f32 v114, -v114, v117, v116
	v_div_fmas_f32 v114, v114, v115, v117
	v_div_fixup_f32 v113, v114, v113, v119
	v_mul_f32_e32 v112, v113, v112
	v_mul_f32_e32 v113, 0xbfb8aa3b, v120
	v_exp_f32_e32 v113, v113
	v_cvt_pk_bf16_f32 v112, v112, s0
	ds_write_b16 v128, v112 offset:2992
	ds_read_u16 v112, v128 offset:4352
	v_add_f32_e32 v113, 1.0, v113
	v_div_scale_f32 v114, s[0:1], v113, v113, v120
	v_rcp_f32_e32 v115, v114
	s_waitcnt lgkmcnt(0)
	v_lshlrev_b32_e32 v112, 16, v112
	v_fma_f32 v116, -v114, v115, 1.0
	v_fmac_f32_e32 v115, v116, v115
	v_div_scale_f32 v116, vcc, v120, v113, v120
	v_mul_f32_e32 v117, v116, v115
	v_fma_f32 v118, -v114, v117, v116
	v_fmac_f32_e32 v117, v118, v115
	v_fma_f32 v114, -v114, v117, v116
	v_div_fmas_f32 v114, v114, v115, v117
	v_div_fixup_f32 v113, v114, v113, v120
	v_mul_f32_e32 v112, v113, v112
	v_mul_f32_e32 v113, 0xbfb8aa3b, v121
	v_exp_f32_e32 v113, v113
	v_cvt_pk_bf16_f32 v112, v112, s0
	ds_write_b16 v128, v112 offset:4352
	ds_read_u16 v112, v128 offset:4624
	v_add_f32_e32 v113, 1.0, v113
	v_div_scale_f32 v114, s[0:1], v113, v113, v121
	v_rcp_f32_e32 v115, v114
	s_waitcnt lgkmcnt(0)
	v_lshlrev_b32_e32 v112, 16, v112
	v_fma_f32 v116, -v114, v115, 1.0
	v_fmac_f32_e32 v115, v116, v115
	v_div_scale_f32 v116, vcc, v121, v113, v121
	v_mul_f32_e32 v117, v116, v115
	v_fma_f32 v118, -v114, v117, v116
	v_fmac_f32_e32 v117, v118, v115
	v_fma_f32 v114, -v114, v117, v116
	v_div_fmas_f32 v114, v114, v115, v117
	v_div_fixup_f32 v113, v114, v113, v121
	v_mul_f32_e32 v112, v113, v112
	v_mul_f32_e32 v113, 0xbfb8aa3b, v122
	v_exp_f32_e32 v113, v113
	v_cvt_pk_bf16_f32 v112, v112, s0
	ds_write_b16 v128, v112 offset:4624
	ds_read_u16 v112, v128 offset:4896
	v_add_f32_e32 v113, 1.0, v113
	v_div_scale_f32 v114, s[0:1], v113, v113, v122
	v_rcp_f32_e32 v115, v114
	s_waitcnt lgkmcnt(0)
	v_lshlrev_b32_e32 v112, 16, v112
	v_fma_f32 v116, -v114, v115, 1.0
	v_fmac_f32_e32 v115, v116, v115
	v_div_scale_f32 v116, vcc, v122, v113, v122
	v_mul_f32_e32 v117, v116, v115
	v_fma_f32 v118, -v114, v117, v116
	v_fmac_f32_e32 v117, v118, v115
	v_fma_f32 v114, -v114, v117, v116
	v_div_fmas_f32 v114, v114, v115, v117
	v_div_fixup_f32 v113, v114, v113, v122
	v_mul_f32_e32 v112, v113, v112
	v_mul_f32_e32 v113, 0xbfb8aa3b, v123
	v_exp_f32_e32 v113, v113
	v_cvt_pk_bf16_f32 v112, v112, s0
	ds_write_b16 v128, v112 offset:4896
	ds_read_u16 v112, v128 offset:5168
	v_add_f32_e32 v113, 1.0, v113
	v_div_scale_f32 v114, s[0:1], v113, v113, v123
	v_rcp_f32_e32 v115, v114
	s_waitcnt lgkmcnt(0)
; DEV u16 f2bf(float f) { return (u16)(pk2bf(f, 0.f) & 0xffffu); }
; DEV float bf2f(u16 h) { return __uint_as_float(((unsigned)h) << 16); }
; DEV float siluf_(float x) { return x / (1.0f + __expf(-x)); }
; template <int MI>
; DEV void p4_tile(const Params& p, int l, int m0, int nt, unsigned char* smem) {
;     ...
;     acc_foreach_t<MI>([&](int mi, int ni, int r, int row, int col) __attribute__((always_inline)) {
;       sC[row * LDC + col] = f2bf(bf2f(sC[row * LDC + col]) * siluf_(acc[mi][ni][r]));
;     });
	v_lshlrev_b32_e32 v112, 16, v112
	v_fma_f32 v116, -v114, v115, 1.0
	v_fmac_f32_e32 v115, v116, v115
	v_div_scale_f32 v116, vcc, v123, v113, v123
	v_mul_f32_e32 v117, v116, v115
	v_fma_f32 v118, -v114, v117, v116
	v_fmac_f32_e32 v117, v118, v115
	v_fma_f32 v114, -v114, v117, v116
	v_div_fmas_f32 v114, v114, v115, v117
	v_div_fixup_f32 v113, v114, v113, v123
	v_mul_f32_e32 v112, v113, v112
	v_mul_f32_e32 v113, 0xbfb8aa3b, v124
	v_exp_f32_e32 v113, v113
	v_cvt_pk_bf16_f32 v112, v112, s0
	ds_write_b16 v128, v112 offset:5168
	ds_read_u16 v112, v128 offset:6528
	v_add_f32_e32 v113, 1.0, v113
	v_div_scale_f32 v114, s[0:1], v113, v113, v124
	v_rcp_f32_e32 v115, v114
	s_waitcnt lgkmcnt(0)
	v_lshlrev_b32_e32 v112, 16, v112
	v_fma_f32 v116, -v114, v115, 1.0
	v_fmac_f32_e32 v115, v116, v115
	v_div_scale_f32 v116, vcc, v124, v113, v124
	v_mul_f32_e32 v117, v116, v115
	v_fma_f32 v118, -v114, v117, v116
	v_fmac_f32_e32 v117, v118, v115
	v_fma_f32 v114, -v114, v117, v116
	v_div_fmas_f32 v114, v114, v115, v117
	v_div_fixup_f32 v113, v114, v113, v124
	v_mul_f32_e32 v112, v113, v112
	v_mul_f32_e32 v113, 0xbfb8aa3b, v125
	v_exp_f32_e32 v113, v113
	v_cvt_pk_bf16_f32 v112, v112, s0
	ds_write_b16 v128, v112 offset:6528
	ds_read_u16 v112, v128 offset:6800
	v_add_f32_e32 v113, 1.0, v113
	v_div_scale_f32 v114, s[0:1], v113, v113, v125
	v_rcp_f32_e32 v115, v114
	s_waitcnt lgkmcnt(0)
	v_lshlrev_b32_e32 v112, 16, v112
	v_fma_f32 v116, -v114, v115, 1.0
	v_fmac_f32_e32 v115, v116, v115
	v_div_scale_f32 v116, vcc, v125, v113, v125
	v_mul_f32_e32 v117, v116, v115
	v_fma_f32 v118, -v114, v117, v116
	v_fmac_f32_e32 v117, v118, v115
	v_fma_f32 v114, -v114, v117, v116
	v_div_fmas_f32 v114, v114, v115, v117
	v_div_fixup_f32 v113, v114, v113, v125
	v_mul_f32_e32 v112, v113, v112
	v_mul_f32_e32 v113, 0xbfb8aa3b, v126
	v_exp_f32_e32 v113, v113
	v_cvt_pk_bf16_f32 v112, v112, s0
	ds_write_b16 v128, v112 offset:6800
	ds_read_u16 v112, v128 offset:7072
	v_add_f32_e32 v113, 1.0, v113
	v_div_scale_f32 v114, s[0:1], v113, v113, v126
	v_rcp_f32_e32 v115, v114
	s_waitcnt lgkmcnt(0)
	v_lshlrev_b32_e32 v112, 16, v112
	v_fma_f32 v116, -v114, v115, 1.0
	v_fmac_f32_e32 v115, v116, v115
	v_div_scale_f32 v116, vcc, v126, v113, v126
	v_mul_f32_e32 v117, v116, v115
	v_fma_f32 v118, -v114, v117, v116
	v_fmac_f32_e32 v117, v118, v115
	v_fma_f32 v114, -v114, v117, v116
	v_div_fmas_f32 v114, v114, v115, v117
	v_div_fixup_f32 v113, v114, v113, v126
	v_mul_f32_e32 v112, v113, v112
	v_mul_f32_e32 v113, 0xbfb8aa3b, v127
	v_exp_f32_e32 v113, v113
	v_cvt_pk_bf16_f32 v112, v112, s0
	ds_write_b16 v128, v112 offset:7072
	ds_read_u16 v112, v128 offset:7344
	v_add_f32_e32 v113, 1.0, v113
	v_div_scale_f32 v114, s[0:1], v113, v113, v127
	v_rcp_f32_e32 v115, v114
	s_waitcnt lgkmcnt(0)
	v_lshlrev_b32_e32 v112, 16, v112
	v_fma_f32 v116, -v114, v115, 1.0
	v_fmac_f32_e32 v115, v116, v115
	v_div_scale_f32 v116, vcc, v127, v113, v127
	v_mul_f32_e32 v117, v116, v115
	v_fma_f32 v118, -v114, v117, v116
	v_fmac_f32_e32 v117, v118, v115
	v_fma_f32 v114, -v114, v117, v116
	v_div_fmas_f32 v114, v114, v115, v117
	v_div_fixup_f32 v113, v114, v113, v127
	v_mul_f32_e32 v112, v113, v112
	v_mul_f32_e32 v113, 0xbfb8aa3b, v96
	v_exp_f32_e32 v113, v113
	v_cvt_pk_bf16_f32 v112, v112, s0
	ds_write_b16 v128, v112 offset:7344
	ds_read_u16 v112, v128 offset:64
	v_add_f32_e32 v113, 1.0, v113
	v_div_scale_f32 v114, s[0:1], v113, v113, v96
	v_rcp_f32_e32 v115, v114
	s_waitcnt lgkmcnt(0)
	v_lshlrev_b32_e32 v112, 16, v112
	v_fma_f32 v116, -v114, v115, 1.0
	v_fmac_f32_e32 v115, v116, v115
	v_div_scale_f32 v116, vcc, v96, v113, v96
	v_mul_f32_e32 v117, v116, v115
	v_fma_f32 v118, -v114, v117, v116
	v_fmac_f32_e32 v117, v118, v115
	v_fma_f32 v114, -v114, v117, v116
	v_div_fmas_f32 v114, v114, v115, v117
	v_div_fixup_f32 v96, v114, v113, v96
	v_mul_f32_e32 v96, v96, v112
	v_mul_f32_e32 v112, 0xbfb8aa3b, v97
	v_exp_f32_e32 v112, v112
	v_cvt_pk_bf16_f32 v96, v96, s0
	ds_write_b16 v128, v96 offset:64
	ds_read_u16 v96, v128 offset:336
	v_add_f32_e32 v112, 1.0, v112
	v_div_scale_f32 v113, s[0:1], v112, v112, v97
	v_rcp_f32_e32 v114, v113
	s_waitcnt lgkmcnt(0)
	v_lshlrev_b32_e32 v96, 16, v96
	v_fma_f32 v115, -v113, v114, 1.0
	v_fmac_f32_e32 v114, v115, v114
	v_div_scale_f32 v115, vcc, v97, v112, v97
	v_mul_f32_e32 v116, v115, v114
	v_fma_f32 v117, -v113, v116, v115
	v_fmac_f32_e32 v116, v117, v114
	v_fma_f32 v113, -v113, v116, v115
	v_div_fmas_f32 v113, v113, v114, v116
	v_div_fixup_f32 v97, v113, v112, v97
	v_mul_f32_e32 v96, v97, v96
	v_mul_f32_e32 v97, 0xbfb8aa3b, v98
	v_exp_f32_e32 v97, v97
	v_cvt_pk_bf16_f32 v96, v96, s0
	ds_write_b16 v128, v96 offset:336
	ds_read_u16 v96, v128 offset:608
	v_add_f32_e32 v97, 1.0, v97
	v_div_scale_f32 v112, s[0:1], v97, v97, v98
	v_rcp_f32_e32 v113, v112
	s_waitcnt lgkmcnt(0)
	v_lshlrev_b32_e32 v96, 16, v96
	v_fma_f32 v114, -v112, v113, 1.0
	v_fmac_f32_e32 v113, v114, v113
	v_div_scale_f32 v114, vcc, v98, v97, v98
	v_mul_f32_e32 v115, v114, v113
	v_fma_f32 v116, -v112, v115, v114
	v_fmac_f32_e32 v115, v116, v113
	v_fma_f32 v112, -v112, v115, v114
	v_div_fmas_f32 v112, v112, v113, v115
	v_div_fixup_f32 v97, v112, v97, v98
	v_mul_f32_e32 v96, v97, v96
	v_mul_f32_e32 v97, 0xbfb8aa3b, v99
	v_exp_f32_e32 v97, v97
	v_cvt_pk_bf16_f32 v96, v96, s0
	ds_write_b16 v128, v96 offset:608
	ds_read_u16 v96, v128 offset:880
	v_add_f32_e32 v97, 1.0, v97
	v_div_scale_f32 v98, s[0:1], v97, v97, v99
	v_rcp_f32_e32 v112, v98
	s_waitcnt lgkmcnt(0)
; DEV u16 f2bf(float f) { return (u16)(pk2bf(f, 0.f) & 0xffffu); }
; DEV float bf2f(u16 h) { return __uint_as_float(((unsigned)h) << 16); }
; DEV float siluf_(float x) { return x / (1.0f + __expf(-x)); }
; template <int MI>
; DEV void p4_tile(const Params& p, int l, int m0, int nt, unsigned char* smem) {
;     ...
;     acc_foreach_t<MI>([&](int mi, int ni, int r, int row, int col) __attribute__((always_inline)) {
;       sC[row * LDC + col] = f2bf(bf2f(sC[row * LDC + col]) * siluf_(acc[mi][ni][r]));
;     });
	v_lshlrev_b32_e32 v96, 16, v96
	v_fma_f32 v113, -v98, v112, 1.0
	v_fmac_f32_e32 v112, v113, v112
	v_div_scale_f32 v113, vcc, v99, v97, v99
	v_mul_f32_e32 v114, v113, v112
	v_fma_f32 v115, -v98, v114, v113
	v_fmac_f32_e32 v114, v115, v112
	v_fma_f32 v98, -v98, v114, v113
	v_div_fmas_f32 v98, v98, v112, v114
	v_div_fixup_f32 v97, v98, v97, v99
	v_mul_f32_e32 v96, v97, v96
	v_mul_f32_e32 v97, 0xbfb8aa3b, v100
	v_exp_f32_e32 v97, v97
	v_cvt_pk_bf16_f32 v96, v96, s0
	ds_write_b16 v128, v96 offset:880
	ds_read_u16 v96, v128 offset:2240
	v_add_f32_e32 v97, 1.0, v97
	v_div_scale_f32 v98, s[0:1], v97, v97, v100
	v_rcp_f32_e32 v99, v98
	s_waitcnt lgkmcnt(0)
	v_lshlrev_b32_e32 v96, 16, v96
	v_fma_f32 v112, -v98, v99, 1.0
	v_fmac_f32_e32 v99, v112, v99
	v_div_scale_f32 v112, vcc, v100, v97, v100
	v_mul_f32_e32 v113, v112, v99
	v_fma_f32 v114, -v98, v113, v112
	v_fmac_f32_e32 v113, v114, v99
	v_fma_f32 v98, -v98, v113, v112
	v_div_fmas_f32 v98, v98, v99, v113
	v_div_fixup_f32 v97, v98, v97, v100
	v_mul_f32_e32 v96, v97, v96
	v_mul_f32_e32 v97, 0xbfb8aa3b, v101
	v_exp_f32_e32 v97, v97
	v_cvt_pk_bf16_f32 v96, v96, s0
	ds_write_b16 v128, v96 offset:2240
	ds_read_u16 v96, v128 offset:2512
	v_add_f32_e32 v97, 1.0, v97
	v_div_scale_f32 v98, s[0:1], v97, v97, v101
	v_rcp_f32_e32 v99, v98
	s_waitcnt lgkmcnt(0)
	v_lshlrev_b32_e32 v96, 16, v96
	v_fma_f32 v100, -v98, v99, 1.0
	v_fmac_f32_e32 v99, v100, v99
	v_div_scale_f32 v100, vcc, v101, v97, v101
	v_mul_f32_e32 v112, v100, v99
	v_fma_f32 v113, -v98, v112, v100
	v_fmac_f32_e32 v112, v113, v99
	v_fma_f32 v98, -v98, v112, v100
	v_div_fmas_f32 v98, v98, v99, v112
	v_div_fixup_f32 v97, v98, v97, v101
	v_mul_f32_e32 v96, v97, v96
	v_mul_f32_e32 v97, 0xbfb8aa3b, v102
	v_exp_f32_e32 v97, v97
	v_cvt_pk_bf16_f32 v96, v96, s0
	ds_write_b16 v128, v96 offset:2512
	ds_read_u16 v96, v128 offset:2784
	v_add_f32_e32 v97, 1.0, v97
	v_div_scale_f32 v98, s[0:1], v97, v97, v102
	v_rcp_f32_e32 v99, v98
	s_waitcnt lgkmcnt(0)
	v_lshlrev_b32_e32 v96, 16, v96
	v_fma_f32 v100, -v98, v99, 1.0
	v_fmac_f32_e32 v99, v100, v99
	v_div_scale_f32 v100, vcc, v102, v97, v102
	v_mul_f32_e32 v101, v100, v99
	v_fma_f32 v112, -v98, v101, v100
	v_fmac_f32_e32 v101, v112, v99
	v_fma_f32 v98, -v98, v101, v100
	v_div_fmas_f32 v98, v98, v99, v101
	v_div_fixup_f32 v97, v98, v97, v102
	v_mul_f32_e32 v96, v97, v96
	v_mul_f32_e32 v97, 0xbfb8aa3b, v103
	v_exp_f32_e32 v97, v97
	v_cvt_pk_bf16_f32 v96, v96, s0
	ds_write_b16 v128, v96 offset:2784
	ds_read_u16 v96, v128 offset:3056
	v_add_f32_e32 v97, 1.0, v97
	v_div_scale_f32 v98, s[0:1], v97, v97, v103
	v_rcp_f32_e32 v99, v98
	s_waitcnt lgkmcnt(0)
	v_lshlrev_b32_e32 v96, 16, v96
	v_fma_f32 v100, -v98, v99, 1.0
	v_fmac_f32_e32 v99, v100, v99
	v_div_scale_f32 v100, vcc, v103, v97, v103
	v_mul_f32_e32 v101, v100, v99
	v_fma_f32 v102, -v98, v101, v100
	v_fmac_f32_e32 v101, v102, v99
	v_fma_f32 v98, -v98, v101, v100
	v_div_fmas_f32 v98, v98, v99, v101
	v_div_fixup_f32 v97, v98, v97, v103
	v_mul_f32_e32 v96, v97, v96
	v_mul_f32_e32 v97, 0xbfb8aa3b, v104
	v_exp_f32_e32 v97, v97
	v_cvt_pk_bf16_f32 v96, v96, s0
	ds_write_b16 v128, v96 offset:3056
	ds_read_u16 v96, v128 offset:4416
	v_add_f32_e32 v97, 1.0, v97
	v_div_scale_f32 v98, s[0:1], v97, v97, v104
	v_rcp_f32_e32 v99, v98
	s_waitcnt lgkmcnt(0)
	v_lshlrev_b32_e32 v96, 16, v96
	v_fma_f32 v100, -v98, v99, 1.0
	v_fmac_f32_e32 v99, v100, v99
	v_div_scale_f32 v100, vcc, v104, v97, v104
	v_mul_f32_e32 v101, v100, v99
	v_fma_f32 v102, -v98, v101, v100
	v_fmac_f32_e32 v101, v102, v99
	v_fma_f32 v98, -v98, v101, v100
	v_div_fmas_f32 v98, v98, v99, v101
	v_div_fixup_f32 v97, v98, v97, v104
	v_mul_f32_e32 v96, v97, v96
	v_mul_f32_e32 v97, 0xbfb8aa3b, v105
	v_exp_f32_e32 v97, v97
	v_cvt_pk_bf16_f32 v96, v96, s0
	ds_write_b16 v128, v96 offset:4416
	ds_read_u16 v96, v128 offset:4688
	v_add_f32_e32 v97, 1.0, v97
	v_div_scale_f32 v98, s[0:1], v97, v97, v105
	v_rcp_f32_e32 v99, v98
	s_waitcnt lgkmcnt(0)
	v_lshlrev_b32_e32 v96, 16, v96
	v_fma_f32 v100, -v98, v99, 1.0
	v_fmac_f32_e32 v99, v100, v99
	v_div_scale_f32 v100, vcc, v105, v97, v105
	v_mul_f32_e32 v101, v100, v99
	v_fma_f32 v102, -v98, v101, v100
	v_fmac_f32_e32 v101, v102, v99
	v_fma_f32 v98, -v98, v101, v100
	v_div_fmas_f32 v98, v98, v99, v101
	v_div_fixup_f32 v97, v98, v97, v105
	v_mul_f32_e32 v96, v97, v96
	v_mul_f32_e32 v97, 0xbfb8aa3b, v106
	v_exp_f32_e32 v97, v97
	v_cvt_pk_bf16_f32 v96, v96, s0
	ds_write_b16 v128, v96 offset:4688
	ds_read_u16 v96, v128 offset:4960
	v_add_f32_e32 v97, 1.0, v97
	v_div_scale_f32 v98, s[0:1], v97, v97, v106
	v_rcp_f32_e32 v99, v98
	s_waitcnt lgkmcnt(0)
	v_lshlrev_b32_e32 v96, 16, v96
	v_fma_f32 v100, -v98, v99, 1.0
	v_fmac_f32_e32 v99, v100, v99
	v_div_scale_f32 v100, vcc, v106, v97, v106
	v_mul_f32_e32 v101, v100, v99
	v_fma_f32 v102, -v98, v101, v100
	v_fmac_f32_e32 v101, v102, v99
	v_fma_f32 v98, -v98, v101, v100
	v_div_fmas_f32 v98, v98, v99, v101
	v_div_fixup_f32 v97, v98, v97, v106
	v_mul_f32_e32 v96, v97, v96
	v_mul_f32_e32 v97, 0xbfb8aa3b, v107
	v_exp_f32_e32 v97, v97
	v_cvt_pk_bf16_f32 v96, v96, s0
	ds_write_b16 v128, v96 offset:4960
	ds_read_u16 v96, v128 offset:5232
	v_add_f32_e32 v97, 1.0, v97
	v_div_scale_f32 v98, s[0:1], v97, v97, v107
	v_rcp_f32_e32 v99, v98
	s_waitcnt lgkmcnt(0)
	v_lshlrev_b32_e32 v96, 16, v96
	v_fma_f32 v100, -v98, v99, 1.0
	v_fmac_f32_e32 v99, v100, v99
	v_div_scale_f32 v100, vcc, v107, v97, v107
	v_mul_f32_e32 v101, v100, v99
	v_fma_f32 v102, -v98, v101, v100
	v_fmac_f32_e32 v101, v102, v99
	v_fma_f32 v98, -v98, v101, v100
	v_div_fmas_f32 v98, v98, v99, v101
	v_div_fixup_f32 v97, v98, v97, v107
	v_mul_f32_e32 v96, v97, v96
	v_mul_f32_e32 v97, 0xbfb8aa3b, v108
	v_exp_f32_e32 v97, v97
	v_cvt_pk_bf16_f32 v96, v96, s0
	ds_write_b16 v128, v96 offset:5232
	ds_read_u16 v96, v128 offset:6592
	v_add_f32_e32 v97, 1.0, v97
	v_div_scale_f32 v98, s[0:1], v97, v97, v108
	v_rcp_f32_e32 v99, v98
	s_waitcnt lgkmcnt(0)
; DEV u16 f2bf(float f) { return (u16)(pk2bf(f, 0.f) & 0xffffu); }
; DEV float bf2f(u16 h) { return __uint_as_float(((unsigned)h) << 16); }
; DEV float siluf_(float x) { return x / (1.0f + __expf(-x)); }
; template <int MI>
; DEV void p4_tile(const Params& p, int l, int m0, int nt, unsigned char* smem) {
;     ...
;     acc_foreach_t<MI>([&](int mi, int ni, int r, int row, int col) __attribute__((always_inline)) {
;       sC[row * LDC + col] = f2bf(bf2f(sC[row * LDC + col]) * siluf_(acc[mi][ni][r]));
;     });
	v_lshlrev_b32_e32 v96, 16, v96
	v_fma_f32 v100, -v98, v99, 1.0
	v_fmac_f32_e32 v99, v100, v99
	v_div_scale_f32 v100, vcc, v108, v97, v108
	v_mul_f32_e32 v101, v100, v99
	v_fma_f32 v102, -v98, v101, v100
	v_fmac_f32_e32 v101, v102, v99
	v_fma_f32 v98, -v98, v101, v100
	v_div_fmas_f32 v98, v98, v99, v101
	v_div_fixup_f32 v97, v98, v97, v108
	v_mul_f32_e32 v96, v97, v96
	v_mul_f32_e32 v97, 0xbfb8aa3b, v109
	v_exp_f32_e32 v97, v97
	v_cvt_pk_bf16_f32 v96, v96, s0
	ds_write_b16 v128, v96 offset:6592
	ds_read_u16 v96, v128 offset:6864
	v_add_f32_e32 v97, 1.0, v97
	v_div_scale_f32 v98, s[0:1], v97, v97, v109
	v_rcp_f32_e32 v99, v98
	s_waitcnt lgkmcnt(0)
	v_lshlrev_b32_e32 v96, 16, v96
	v_fma_f32 v100, -v98, v99, 1.0
	v_fmac_f32_e32 v99, v100, v99
	v_div_scale_f32 v100, vcc, v109, v97, v109
	v_mul_f32_e32 v101, v100, v99
	v_fma_f32 v102, -v98, v101, v100
	v_fmac_f32_e32 v101, v102, v99
	v_fma_f32 v98, -v98, v101, v100
	v_div_fmas_f32 v98, v98, v99, v101
	v_div_fixup_f32 v97, v98, v97, v109
	v_mul_f32_e32 v96, v97, v96
	v_mul_f32_e32 v97, 0xbfb8aa3b, v110
	v_exp_f32_e32 v97, v97
	v_cvt_pk_bf16_f32 v96, v96, s0
	ds_write_b16 v128, v96 offset:6864
	ds_read_u16 v96, v128 offset:7136
	v_add_f32_e32 v97, 1.0, v97
	v_div_scale_f32 v98, s[0:1], v97, v97, v110
	v_rcp_f32_e32 v99, v98
	s_waitcnt lgkmcnt(0)
	v_lshlrev_b32_e32 v96, 16, v96
	v_fma_f32 v100, -v98, v99, 1.0
	v_fmac_f32_e32 v99, v100, v99
	v_div_scale_f32 v100, vcc, v110, v97, v110
	v_mul_f32_e32 v101, v100, v99
	v_fma_f32 v102, -v98, v101, v100
	v_fmac_f32_e32 v101, v102, v99
	v_fma_f32 v98, -v98, v101, v100
	v_div_fmas_f32 v98, v98, v99, v101
	v_div_fixup_f32 v97, v98, v97, v110
	v_mul_f32_e32 v96, v97, v96
	v_mul_f32_e32 v97, 0xbfb8aa3b, v111
	v_exp_f32_e32 v97, v97
	v_cvt_pk_bf16_f32 v96, v96, s0
	ds_write_b16 v128, v96 offset:7136
	ds_read_u16 v96, v128 offset:7408
	v_add_f32_e32 v97, 1.0, v97
	v_div_scale_f32 v98, s[0:1], v97, v97, v111
	v_rcp_f32_e32 v99, v98
	s_waitcnt lgkmcnt(0)
	v_lshlrev_b32_e32 v96, 16, v96
	v_fma_f32 v100, -v98, v99, 1.0
	v_fmac_f32_e32 v99, v100, v99
	v_div_scale_f32 v100, vcc, v111, v97, v111
	v_mul_f32_e32 v101, v100, v99
	v_fma_f32 v102, -v98, v101, v100
	v_fmac_f32_e32 v101, v102, v99
	v_fma_f32 v98, -v98, v101, v100
	v_div_fmas_f32 v98, v98, v99, v101
	v_div_fixup_f32 v97, v98, v97, v111
	v_mul_f32_e32 v96, v97, v96
	v_mul_f32_e32 v97, 0xbfb8aa3b, v80
	v_exp_f32_e32 v97, v97
	v_cvt_pk_bf16_f32 v96, v96, s0
	ds_write_b16 v128, v96 offset:7408
	ds_read_u16 v96, v128 offset:8704
	v_add_f32_e32 v97, 1.0, v97
	v_div_scale_f32 v98, s[0:1], v97, v97, v80
	v_rcp_f32_e32 v99, v98
	s_waitcnt lgkmcnt(0)
	v_lshlrev_b32_e32 v96, 16, v96
	v_fma_f32 v100, -v98, v99, 1.0
	v_fmac_f32_e32 v99, v100, v99
	v_div_scale_f32 v100, vcc, v80, v97, v80
	v_mul_f32_e32 v101, v100, v99
	v_fma_f32 v102, -v98, v101, v100
	v_fmac_f32_e32 v101, v102, v99
	v_fma_f32 v98, -v98, v101, v100
	v_div_fmas_f32 v98, v98, v99, v101
	v_div_fixup_f32 v80, v98, v97, v80
	v_mul_f32_e32 v80, v80, v96
	v_mul_f32_e32 v96, 0xbfb8aa3b, v81
	v_exp_f32_e32 v96, v96
	v_cvt_pk_bf16_f32 v80, v80, s0
	ds_write_b16 v128, v80 offset:8704
	ds_read_u16 v80, v128 offset:8976
	v_add_f32_e32 v96, 1.0, v96
	v_div_scale_f32 v97, s[0:1], v96, v96, v81
	v_rcp_f32_e32 v98, v97
	s_waitcnt lgkmcnt(0)
	v_lshlrev_b32_e32 v80, 16, v80
	v_fma_f32 v99, -v97, v98, 1.0
	v_fmac_f32_e32 v98, v99, v98
	v_div_scale_f32 v99, vcc, v81, v96, v81
	v_mul_f32_e32 v100, v99, v98
	v_fma_f32 v101, -v97, v100, v99
	v_fmac_f32_e32 v100, v101, v98
	v_fma_f32 v97, -v97, v100, v99
	v_div_fmas_f32 v97, v97, v98, v100
	v_div_fixup_f32 v81, v97, v96, v81
	v_mul_f32_e32 v80, v81, v80
	v_mul_f32_e32 v81, 0xbfb8aa3b, v82
	v_exp_f32_e32 v81, v81
	v_cvt_pk_bf16_f32 v80, v80, s0
	ds_write_b16 v128, v80 offset:8976
	ds_read_u16 v80, v128 offset:9248
	v_add_f32_e32 v81, 1.0, v81
	v_div_scale_f32 v96, s[0:1], v81, v81, v82
	v_rcp_f32_e32 v97, v96
	s_waitcnt lgkmcnt(0)
	v_lshlrev_b32_e32 v80, 16, v80
	v_fma_f32 v98, -v96, v97, 1.0
	v_fmac_f32_e32 v97, v98, v97
	v_div_scale_f32 v98, vcc, v82, v81, v82
	v_mul_f32_e32 v99, v98, v97
	v_fma_f32 v100, -v96, v99, v98
	v_fmac_f32_e32 v99, v100, v97
	v_fma_f32 v96, -v96, v99, v98
	v_div_fmas_f32 v96, v96, v97, v99
	v_div_fixup_f32 v81, v96, v81, v82
	v_mul_f32_e32 v80, v81, v80
	v_mul_f32_e32 v81, 0xbfb8aa3b, v83
	v_exp_f32_e32 v81, v81
	v_cvt_pk_bf16_f32 v80, v80, s0
	ds_write_b16 v128, v80 offset:9248
	ds_read_u16 v80, v128 offset:9520
	v_add_f32_e32 v81, 1.0, v81
	v_div_scale_f32 v82, s[0:1], v81, v81, v83
	v_rcp_f32_e32 v96, v82
	s_waitcnt lgkmcnt(0)
	v_lshlrev_b32_e32 v80, 16, v80
	v_fma_f32 v97, -v82, v96, 1.0
	v_fmac_f32_e32 v96, v97, v96
	v_div_scale_f32 v97, vcc, v83, v81, v83
	v_mul_f32_e32 v98, v97, v96
	v_fma_f32 v99, -v82, v98, v97
	v_fmac_f32_e32 v98, v99, v96
	v_fma_f32 v82, -v82, v98, v97
	v_div_fmas_f32 v82, v82, v96, v98
	v_div_fixup_f32 v81, v82, v81, v83
	v_mul_f32_e32 v80, v81, v80
	v_mul_f32_e32 v81, 0xbfb8aa3b, v84
	v_exp_f32_e32 v81, v81
	v_cvt_pk_bf16_f32 v80, v80, s0
	ds_write_b16 v128, v80 offset:9520
	ds_read_u16 v80, v128 offset:10880
	v_add_f32_e32 v81, 1.0, v81
	v_div_scale_f32 v82, s[0:1], v81, v81, v84
	v_rcp_f32_e32 v83, v82
	s_waitcnt lgkmcnt(0)
	v_lshlrev_b32_e32 v80, 16, v80
	v_fma_f32 v96, -v82, v83, 1.0
	v_fmac_f32_e32 v83, v96, v83
	v_div_scale_f32 v96, vcc, v84, v81, v84
	v_mul_f32_e32 v97, v96, v83
	v_fma_f32 v98, -v82, v97, v96
	v_fmac_f32_e32 v97, v98, v83
	v_fma_f32 v82, -v82, v97, v96
	v_div_fmas_f32 v82, v82, v83, v97
	v_div_fixup_f32 v81, v82, v81, v84
	v_mul_f32_e32 v80, v81, v80
	v_mul_f32_e32 v81, 0xbfb8aa3b, v85
	v_exp_f32_e32 v81, v81
	v_cvt_pk_bf16_f32 v80, v80, s0
	ds_write_b16 v128, v80 offset:10880
	ds_read_u16 v80, v128 offset:11152
	v_add_f32_e32 v81, 1.0, v81
	v_div_scale_f32 v82, s[0:1], v81, v81, v85
	v_rcp_f32_e32 v83, v82
	s_waitcnt lgkmcnt(0)
; DEV u16 f2bf(float f) { return (u16)(pk2bf(f, 0.f) & 0xffffu); }
; DEV float bf2f(u16 h) { return __uint_as_float(((unsigned)h) << 16); }
; DEV float siluf_(float x) { return x / (1.0f + __expf(-x)); }
; template <int MI>
; DEV void p4_tile(const Params& p, int l, int m0, int nt, unsigned char* smem) {
;     ...
;     acc_foreach_t<MI>([&](int mi, int ni, int r, int row, int col) __attribute__((always_inline)) {
;       sC[row * LDC + col] = f2bf(bf2f(sC[row * LDC + col]) * siluf_(acc[mi][ni][r]));
;     });
	v_lshlrev_b32_e32 v80, 16, v80
	v_fma_f32 v84, -v82, v83, 1.0
	v_fmac_f32_e32 v83, v84, v83
	v_div_scale_f32 v84, vcc, v85, v81, v85
	v_mul_f32_e32 v96, v84, v83
	v_fma_f32 v97, -v82, v96, v84
	v_fmac_f32_e32 v96, v97, v83
	v_fma_f32 v82, -v82, v96, v84
	v_div_fmas_f32 v82, v82, v83, v96
	v_div_fixup_f32 v81, v82, v81, v85
	v_mul_f32_e32 v80, v81, v80
	v_mul_f32_e32 v81, 0xbfb8aa3b, v86
	v_exp_f32_e32 v81, v81
	v_cvt_pk_bf16_f32 v80, v80, s0
	ds_write_b16 v128, v80 offset:11152
	ds_read_u16 v80, v128 offset:11424
	v_add_f32_e32 v81, 1.0, v81
	v_div_scale_f32 v82, s[0:1], v81, v81, v86
	v_rcp_f32_e32 v83, v82
	s_waitcnt lgkmcnt(0)
	v_lshlrev_b32_e32 v80, 16, v80
	v_fma_f32 v84, -v82, v83, 1.0
	v_fmac_f32_e32 v83, v84, v83
	v_div_scale_f32 v84, vcc, v86, v81, v86
	v_mul_f32_e32 v85, v84, v83
	v_fma_f32 v96, -v82, v85, v84
	v_fmac_f32_e32 v85, v96, v83
	v_fma_f32 v82, -v82, v85, v84
	v_div_fmas_f32 v82, v82, v83, v85
	v_div_fixup_f32 v81, v82, v81, v86
	v_mul_f32_e32 v80, v81, v80
	v_mul_f32_e32 v81, 0xbfb8aa3b, v87
	v_exp_f32_e32 v81, v81
	v_cvt_pk_bf16_f32 v80, v80, s0
	ds_write_b16 v128, v80 offset:11424
	ds_read_u16 v80, v128 offset:11696
	v_add_f32_e32 v81, 1.0, v81
	v_div_scale_f32 v82, s[0:1], v81, v81, v87
	v_rcp_f32_e32 v83, v82
	s_waitcnt lgkmcnt(0)
	v_lshlrev_b32_e32 v80, 16, v80
	v_fma_f32 v84, -v82, v83, 1.0
	v_fmac_f32_e32 v83, v84, v83
	v_div_scale_f32 v84, vcc, v87, v81, v87
	v_mul_f32_e32 v85, v84, v83
	v_fma_f32 v86, -v82, v85, v84
	v_fmac_f32_e32 v85, v86, v83
	v_fma_f32 v82, -v82, v85, v84
	v_div_fmas_f32 v82, v82, v83, v85
	v_div_fixup_f32 v81, v82, v81, v87
	v_mul_f32_e32 v80, v81, v80
	v_mul_f32_e32 v81, 0xbfb8aa3b, v88
	v_exp_f32_e32 v81, v81
	v_cvt_pk_bf16_f32 v80, v80, s0
	ds_write_b16 v128, v80 offset:11696
	ds_read_u16 v80, v128 offset:13056
	v_add_f32_e32 v81, 1.0, v81
	v_div_scale_f32 v82, s[0:1], v81, v81, v88
	v_rcp_f32_e32 v83, v82
	s_waitcnt lgkmcnt(0)
	v_lshlrev_b32_e32 v80, 16, v80
	v_fma_f32 v84, -v82, v83, 1.0
	v_fmac_f32_e32 v83, v84, v83
	v_div_scale_f32 v84, vcc, v88, v81, v88
	v_mul_f32_e32 v85, v84, v83
	v_fma_f32 v86, -v82, v85, v84
	v_fmac_f32_e32 v85, v86, v83
	v_fma_f32 v82, -v82, v85, v84
	v_div_fmas_f32 v82, v82, v83, v85
	v_div_fixup_f32 v81, v82, v81, v88
	v_mul_f32_e32 v80, v81, v80
	v_mul_f32_e32 v81, 0xbfb8aa3b, v89
	v_exp_f32_e32 v81, v81
	v_cvt_pk_bf16_f32 v80, v80, s0
	ds_write_b16 v128, v80 offset:13056
	ds_read_u16 v80, v128 offset:13328
	v_add_f32_e32 v81, 1.0, v81
	v_div_scale_f32 v82, s[0:1], v81, v81, v89
	v_rcp_f32_e32 v83, v82
	s_waitcnt lgkmcnt(0)
	v_lshlrev_b32_e32 v80, 16, v80
	v_fma_f32 v84, -v82, v83, 1.0
	v_fmac_f32_e32 v83, v84, v83
	v_div_scale_f32 v84, vcc, v89, v81, v89
	v_mul_f32_e32 v85, v84, v83
	v_fma_f32 v86, -v82, v85, v84
	v_fmac_f32_e32 v85, v86, v83
	v_fma_f32 v82, -v82, v85, v84
	v_div_fmas_f32 v82, v82, v83, v85
	v_div_fixup_f32 v81, v82, v81, v89
	v_mul_f32_e32 v80, v81, v80
	v_mul_f32_e32 v81, 0xbfb8aa3b, v90
	v_exp_f32_e32 v81, v81
	v_cvt_pk_bf16_f32 v80, v80, s0
	ds_write_b16 v128, v80 offset:13328
	ds_read_u16 v80, v128 offset:13600
	v_add_f32_e32 v81, 1.0, v81
	v_div_scale_f32 v82, s[0:1], v81, v81, v90
	v_rcp_f32_e32 v83, v82
	s_waitcnt lgkmcnt(0)
	v_lshlrev_b32_e32 v80, 16, v80
	v_fma_f32 v84, -v82, v83, 1.0
	v_fmac_f32_e32 v83, v84, v83
	v_div_scale_f32 v84, vcc, v90, v81, v90
	v_mul_f32_e32 v85, v84, v83
	v_fma_f32 v86, -v82, v85, v84
	v_fmac_f32_e32 v85, v86, v83
	v_fma_f32 v82, -v82, v85, v84
	v_div_fmas_f32 v82, v82, v83, v85
	v_div_fixup_f32 v81, v82, v81, v90
	v_mul_f32_e32 v80, v81, v80
	v_mul_f32_e32 v81, 0xbfb8aa3b, v91
	v_exp_f32_e32 v81, v81
	v_cvt_pk_bf16_f32 v80, v80, s0
	ds_write_b16 v128, v80 offset:13600
	ds_read_u16 v80, v128 offset:13872
	v_add_f32_e32 v81, 1.0, v81
	v_div_scale_f32 v82, s[0:1], v81, v81, v91
	v_rcp_f32_e32 v83, v82
	s_waitcnt lgkmcnt(0)
	v_lshlrev_b32_e32 v80, 16, v80
	v_fma_f32 v84, -v82, v83, 1.0
	v_fmac_f32_e32 v83, v84, v83
	v_div_scale_f32 v84, vcc, v91, v81, v91
	v_mul_f32_e32 v85, v84, v83
	v_fma_f32 v86, -v82, v85, v84
	v_fmac_f32_e32 v85, v86, v83
	v_fma_f32 v82, -v82, v85, v84
	v_div_fmas_f32 v82, v82, v83, v85
	v_div_fixup_f32 v81, v82, v81, v91
	v_mul_f32_e32 v80, v81, v80
	v_mul_f32_e32 v81, 0xbfb8aa3b, v92
	v_exp_f32_e32 v81, v81
	v_cvt_pk_bf16_f32 v80, v80, s0
	ds_write_b16 v128, v80 offset:13872
	ds_read_u16 v80, v128 offset:15232
	v_add_f32_e32 v81, 1.0, v81
	v_div_scale_f32 v82, s[0:1], v81, v81, v92
	v_rcp_f32_e32 v83, v82
	s_waitcnt lgkmcnt(0)
	v_lshlrev_b32_e32 v80, 16, v80
	v_fma_f32 v84, -v82, v83, 1.0
	v_fmac_f32_e32 v83, v84, v83
	v_div_scale_f32 v84, vcc, v92, v81, v92
	v_mul_f32_e32 v85, v84, v83
	v_fma_f32 v86, -v82, v85, v84
	v_fmac_f32_e32 v85, v86, v83
	v_fma_f32 v82, -v82, v85, v84
	v_div_fmas_f32 v82, v82, v83, v85
	v_div_fixup_f32 v81, v82, v81, v92
	v_mul_f32_e32 v80, v81, v80
	v_mul_f32_e32 v81, 0xbfb8aa3b, v93
	v_exp_f32_e32 v81, v81
	v_cvt_pk_bf16_f32 v80, v80, s0
	ds_write_b16 v128, v80 offset:15232
	ds_read_u16 v80, v128 offset:15504
	v_add_f32_e32 v81, 1.0, v81
	v_div_scale_f32 v82, s[0:1], v81, v81, v93
	v_rcp_f32_e32 v83, v82
	s_waitcnt lgkmcnt(0)
	v_lshlrev_b32_e32 v80, 16, v80
	v_fma_f32 v84, -v82, v83, 1.0
	v_fmac_f32_e32 v83, v84, v83
	v_div_scale_f32 v84, vcc, v93, v81, v93
	v_mul_f32_e32 v85, v84, v83
	v_fma_f32 v86, -v82, v85, v84
	v_fmac_f32_e32 v85, v86, v83
	v_fma_f32 v82, -v82, v85, v84
	v_div_fmas_f32 v82, v82, v83, v85
	v_div_fixup_f32 v81, v82, v81, v93
	v_mul_f32_e32 v80, v81, v80
	v_mul_f32_e32 v81, 0xbfb8aa3b, v94
	v_exp_f32_e32 v81, v81
	v_cvt_pk_bf16_f32 v80, v80, s0
	ds_write_b16 v128, v80 offset:15504
	ds_read_u16 v80, v128 offset:15776
	v_add_f32_e32 v81, 1.0, v81
	v_div_scale_f32 v82, s[0:1], v81, v81, v94
	v_rcp_f32_e32 v83, v82
	s_waitcnt lgkmcnt(0)
; DEV u16 f2bf(float f) { return (u16)(pk2bf(f, 0.f) & 0xffffu); }
; DEV float bf2f(u16 h) { return __uint_as_float(((unsigned)h) << 16); }
; DEV float siluf_(float x) { return x / (1.0f + __expf(-x)); }
; template <int MI>
; DEV void p4_tile(const Params& p, int l, int m0, int nt, unsigned char* smem) {
;     ...
;     acc_foreach_t<MI>([&](int mi, int ni, int r, int row, int col) __attribute__((always_inline)) {
;       sC[row * LDC + col] = f2bf(bf2f(sC[row * LDC + col]) * siluf_(acc[mi][ni][r]));
;     });
	v_lshlrev_b32_e32 v80, 16, v80
	v_fma_f32 v84, -v82, v83, 1.0
	v_fmac_f32_e32 v83, v84, v83
	v_div_scale_f32 v84, vcc, v94, v81, v94
	v_mul_f32_e32 v85, v84, v83
	v_fma_f32 v86, -v82, v85, v84
	v_fmac_f32_e32 v85, v86, v83
	v_fma_f32 v82, -v82, v85, v84
	v_div_fmas_f32 v82, v82, v83, v85
	v_div_fixup_f32 v81, v82, v81, v94
	v_mul_f32_e32 v80, v81, v80
	v_mul_f32_e32 v81, 0xbfb8aa3b, v95
	v_exp_f32_e32 v81, v81
	v_cvt_pk_bf16_f32 v80, v80, s0
	ds_write_b16 v128, v80 offset:15776
	ds_read_u16 v80, v128 offset:16048
	v_add_f32_e32 v81, 1.0, v81
	v_div_scale_f32 v82, s[0:1], v81, v81, v95
	v_rcp_f32_e32 v83, v82
	s_waitcnt lgkmcnt(0)
	v_lshlrev_b32_e32 v80, 16, v80
	v_fma_f32 v84, -v82, v83, 1.0
	v_fmac_f32_e32 v83, v84, v83
	v_div_scale_f32 v84, vcc, v95, v81, v95
	v_mul_f32_e32 v85, v84, v83
	v_fma_f32 v86, -v82, v85, v84
	v_fmac_f32_e32 v85, v86, v83
	v_fma_f32 v82, -v82, v85, v84
	v_div_fmas_f32 v82, v82, v83, v85
	v_div_fixup_f32 v81, v82, v81, v95
	v_mul_f32_e32 v80, v81, v80
	v_mul_f32_e32 v81, 0xbfb8aa3b, v64
	v_exp_f32_e32 v81, v81
	v_cvt_pk_bf16_f32 v80, v80, s0
	ds_write_b16 v128, v80 offset:16048
	ds_read_u16 v80, v128 offset:8768
	v_add_f32_e32 v81, 1.0, v81
	v_div_scale_f32 v82, s[0:1], v81, v81, v64
	v_rcp_f32_e32 v83, v82
	s_waitcnt lgkmcnt(0)
	v_lshlrev_b32_e32 v80, 16, v80
	v_fma_f32 v84, -v82, v83, 1.0
	v_fmac_f32_e32 v83, v84, v83
	v_div_scale_f32 v84, vcc, v64, v81, v64
	v_mul_f32_e32 v85, v84, v83
	v_fma_f32 v86, -v82, v85, v84
	v_fmac_f32_e32 v85, v86, v83
	v_fma_f32 v82, -v82, v85, v84
	v_div_fmas_f32 v82, v82, v83, v85
	v_div_fixup_f32 v64, v82, v81, v64
	v_mul_f32_e32 v64, v64, v80
	v_mul_f32_e32 v80, 0xbfb8aa3b, v65
	v_exp_f32_e32 v80, v80
	v_cvt_pk_bf16_f32 v64, v64, s0
	ds_write_b16 v128, v64 offset:8768
	ds_read_u16 v64, v128 offset:9040
	v_add_f32_e32 v80, 1.0, v80
	v_div_scale_f32 v81, s[0:1], v80, v80, v65
	v_rcp_f32_e32 v82, v81
	s_waitcnt lgkmcnt(0)
	v_lshlrev_b32_e32 v64, 16, v64
	v_fma_f32 v83, -v81, v82, 1.0
	v_fmac_f32_e32 v82, v83, v82
	v_div_scale_f32 v83, vcc, v65, v80, v65
	v_mul_f32_e32 v84, v83, v82
	v_fma_f32 v85, -v81, v84, v83
	v_fmac_f32_e32 v84, v85, v82
	v_fma_f32 v81, -v81, v84, v83
	v_div_fmas_f32 v81, v81, v82, v84
	v_div_fixup_f32 v65, v81, v80, v65
	v_mul_f32_e32 v64, v65, v64
	v_mul_f32_e32 v65, 0xbfb8aa3b, v66
	v_exp_f32_e32 v65, v65
	v_cvt_pk_bf16_f32 v64, v64, s0
	ds_write_b16 v128, v64 offset:9040
	ds_read_u16 v64, v128 offset:9312
	v_add_f32_e32 v65, 1.0, v65
	v_div_scale_f32 v80, s[0:1], v65, v65, v66
	v_rcp_f32_e32 v81, v80
	s_waitcnt lgkmcnt(0)
	v_lshlrev_b32_e32 v64, 16, v64
	v_fma_f32 v82, -v80, v81, 1.0
	v_fmac_f32_e32 v81, v82, v81
	v_div_scale_f32 v82, vcc, v66, v65, v66
	v_mul_f32_e32 v83, v82, v81
	v_fma_f32 v84, -v80, v83, v82
	v_fmac_f32_e32 v83, v84, v81
	v_fma_f32 v80, -v80, v83, v82
	v_div_fmas_f32 v80, v80, v81, v83
	v_div_fixup_f32 v65, v80, v65, v66
	v_mul_f32_e32 v64, v65, v64
	v_mul_f32_e32 v65, 0xbfb8aa3b, v67
	v_exp_f32_e32 v65, v65
	v_cvt_pk_bf16_f32 v64, v64, s0
	ds_write_b16 v128, v64 offset:9312
	ds_read_u16 v64, v128 offset:9584
	v_add_f32_e32 v65, 1.0, v65
	v_div_scale_f32 v66, s[0:1], v65, v65, v67
	v_rcp_f32_e32 v80, v66
	s_waitcnt lgkmcnt(0)
	v_lshlrev_b32_e32 v64, 16, v64
	v_fma_f32 v81, -v66, v80, 1.0
	v_fmac_f32_e32 v80, v81, v80
	v_div_scale_f32 v81, vcc, v67, v65, v67
	v_mul_f32_e32 v82, v81, v80
	v_fma_f32 v83, -v66, v82, v81
	v_fmac_f32_e32 v82, v83, v80
	v_fma_f32 v66, -v66, v82, v81
	v_div_fmas_f32 v66, v66, v80, v82
	v_div_fixup_f32 v65, v66, v65, v67
	v_mul_f32_e32 v64, v65, v64
	v_mul_f32_e32 v65, 0xbfb8aa3b, v68
	v_exp_f32_e32 v65, v65
	v_cvt_pk_bf16_f32 v64, v64, s0
	ds_write_b16 v128, v64 offset:9584
	ds_read_u16 v64, v128 offset:10944
	v_add_f32_e32 v65, 1.0, v65
	v_div_scale_f32 v66, s[0:1], v65, v65, v68
	v_rcp_f32_e32 v67, v66
	s_waitcnt lgkmcnt(0)
	v_lshlrev_b32_e32 v64, 16, v64
	v_fma_f32 v80, -v66, v67, 1.0
	v_fmac_f32_e32 v67, v80, v67
	v_div_scale_f32 v80, vcc, v68, v65, v68
	v_mul_f32_e32 v81, v80, v67
	v_fma_f32 v82, -v66, v81, v80
	v_fmac_f32_e32 v81, v82, v67
	v_fma_f32 v66, -v66, v81, v80
	v_div_fmas_f32 v66, v66, v67, v81
	v_div_fixup_f32 v65, v66, v65, v68
	v_mul_f32_e32 v64, v65, v64
	v_mul_f32_e32 v65, 0xbfb8aa3b, v69
	v_exp_f32_e32 v65, v65
	v_cvt_pk_bf16_f32 v64, v64, s0
	ds_write_b16 v128, v64 offset:10944
	ds_read_u16 v64, v128 offset:11216
	v_add_f32_e32 v65, 1.0, v65
	v_div_scale_f32 v66, s[0:1], v65, v65, v69
	v_rcp_f32_e32 v67, v66
	s_waitcnt lgkmcnt(0)
	v_lshlrev_b32_e32 v64, 16, v64
	v_fma_f32 v68, -v66, v67, 1.0
	v_fmac_f32_e32 v67, v68, v67
	v_div_scale_f32 v68, vcc, v69, v65, v69
	v_mul_f32_e32 v80, v68, v67
	v_fma_f32 v81, -v66, v80, v68
	v_fmac_f32_e32 v80, v81, v67
	v_fma_f32 v66, -v66, v80, v68
	v_div_fmas_f32 v66, v66, v67, v80
	v_div_fixup_f32 v65, v66, v65, v69
	v_mul_f32_e32 v64, v65, v64
	v_mul_f32_e32 v65, 0xbfb8aa3b, v70
	v_exp_f32_e32 v65, v65
	v_cvt_pk_bf16_f32 v64, v64, s0
	ds_write_b16 v128, v64 offset:11216
	ds_read_u16 v64, v128 offset:11488
	v_add_f32_e32 v65, 1.0, v65
	v_div_scale_f32 v66, s[0:1], v65, v65, v70
	v_rcp_f32_e32 v67, v66
	s_waitcnt lgkmcnt(0)
	v_lshlrev_b32_e32 v64, 16, v64
	v_fma_f32 v68, -v66, v67, 1.0
	v_fmac_f32_e32 v67, v68, v67
	v_div_scale_f32 v68, vcc, v70, v65, v70
	v_mul_f32_e32 v69, v68, v67
	v_fma_f32 v80, -v66, v69, v68
	v_fmac_f32_e32 v69, v80, v67
	v_fma_f32 v66, -v66, v69, v68
	v_div_fmas_f32 v66, v66, v67, v69
	v_div_fixup_f32 v65, v66, v65, v70
	v_mul_f32_e32 v64, v65, v64
	v_mul_f32_e32 v65, 0xbfb8aa3b, v71
	v_exp_f32_e32 v65, v65
	v_cvt_pk_bf16_f32 v64, v64, s0
	ds_write_b16 v128, v64 offset:11488
	ds_read_u16 v64, v128 offset:11760
	v_add_f32_e32 v65, 1.0, v65
	v_div_scale_f32 v66, s[0:1], v65, v65, v71
	v_rcp_f32_e32 v67, v66
	s_waitcnt lgkmcnt(0)
; DEV u16 f2bf(float f) { return (u16)(pk2bf(f, 0.f) & 0xffffu); }
; DEV float bf2f(u16 h) { return __uint_as_float(((unsigned)h) << 16); }
; DEV float siluf_(float x) { return x / (1.0f + __expf(-x)); }
; template <int MI>
; DEV void p4_tile(const Params& p, int l, int m0, int nt, unsigned char* smem) {
;     ...
;     acc_foreach_t<MI>([&](int mi, int ni, int r, int row, int col) __attribute__((always_inline)) {
;       sC[row * LDC + col] = f2bf(bf2f(sC[row * LDC + col]) * siluf_(acc[mi][ni][r]));
;     });
	v_lshlrev_b32_e32 v64, 16, v64
	v_fma_f32 v68, -v66, v67, 1.0
	v_fmac_f32_e32 v67, v68, v67
	v_div_scale_f32 v68, vcc, v71, v65, v71
	v_mul_f32_e32 v69, v68, v67
	v_fma_f32 v70, -v66, v69, v68
	v_fmac_f32_e32 v69, v70, v67
	v_fma_f32 v66, -v66, v69, v68
	v_div_fmas_f32 v66, v66, v67, v69
	v_div_fixup_f32 v65, v66, v65, v71
	v_mul_f32_e32 v64, v65, v64
	v_mul_f32_e32 v65, 0xbfb8aa3b, v72
	v_exp_f32_e32 v65, v65
	v_cvt_pk_bf16_f32 v64, v64, s0
	ds_write_b16 v128, v64 offset:11760
	ds_read_u16 v64, v128 offset:13120
	v_add_f32_e32 v65, 1.0, v65
	v_div_scale_f32 v66, s[0:1], v65, v65, v72
	v_rcp_f32_e32 v67, v66
	s_waitcnt lgkmcnt(0)
	v_lshlrev_b32_e32 v64, 16, v64
	v_fma_f32 v68, -v66, v67, 1.0
	v_fmac_f32_e32 v67, v68, v67
	v_div_scale_f32 v68, vcc, v72, v65, v72
	v_mul_f32_e32 v69, v68, v67
	v_fma_f32 v70, -v66, v69, v68
	v_fmac_f32_e32 v69, v70, v67
	v_fma_f32 v66, -v66, v69, v68
	v_div_fmas_f32 v66, v66, v67, v69
	v_div_fixup_f32 v65, v66, v65, v72
	v_mul_f32_e32 v64, v65, v64
	v_mul_f32_e32 v65, 0xbfb8aa3b, v73
	v_exp_f32_e32 v65, v65
	v_cvt_pk_bf16_f32 v64, v64, s0
	ds_write_b16 v128, v64 offset:13120
	ds_read_u16 v64, v128 offset:13392
	v_add_f32_e32 v65, 1.0, v65
	v_div_scale_f32 v66, s[0:1], v65, v65, v73
	v_rcp_f32_e32 v67, v66
	s_waitcnt lgkmcnt(0)
	v_lshlrev_b32_e32 v64, 16, v64
	v_fma_f32 v68, -v66, v67, 1.0
	v_fmac_f32_e32 v67, v68, v67
	v_div_scale_f32 v68, vcc, v73, v65, v73
	v_mul_f32_e32 v69, v68, v67
	v_fma_f32 v70, -v66, v69, v68
	v_fmac_f32_e32 v69, v70, v67
	v_fma_f32 v66, -v66, v69, v68
	v_div_fmas_f32 v66, v66, v67, v69
	v_div_fixup_f32 v65, v66, v65, v73
	v_mul_f32_e32 v64, v65, v64
	v_mul_f32_e32 v65, 0xbfb8aa3b, v74
	v_exp_f32_e32 v65, v65
	v_cvt_pk_bf16_f32 v64, v64, s0
	ds_write_b16 v128, v64 offset:13392
	ds_read_u16 v64, v128 offset:13664
	v_add_f32_e32 v65, 1.0, v65
	v_div_scale_f32 v66, s[0:1], v65, v65, v74
	v_rcp_f32_e32 v67, v66
	s_waitcnt lgkmcnt(0)
	v_lshlrev_b32_e32 v64, 16, v64
	v_fma_f32 v68, -v66, v67, 1.0
	v_fmac_f32_e32 v67, v68, v67
	v_div_scale_f32 v68, vcc, v74, v65, v74
	v_mul_f32_e32 v69, v68, v67
	v_fma_f32 v70, -v66, v69, v68
	v_fmac_f32_e32 v69, v70, v67
	v_fma_f32 v66, -v66, v69, v68
	v_div_fmas_f32 v66, v66, v67, v69
	v_div_fixup_f32 v65, v66, v65, v74
	v_mul_f32_e32 v64, v65, v64
	v_mul_f32_e32 v65, 0xbfb8aa3b, v75
	v_exp_f32_e32 v65, v65
	v_cvt_pk_bf16_f32 v64, v64, s0
	ds_write_b16 v128, v64 offset:13664
	ds_read_u16 v64, v128 offset:13936
	v_add_f32_e32 v65, 1.0, v65
	v_div_scale_f32 v66, s[0:1], v65, v65, v75
	v_rcp_f32_e32 v67, v66
	s_waitcnt lgkmcnt(0)
	v_lshlrev_b32_e32 v64, 16, v64
	v_fma_f32 v68, -v66, v67, 1.0
	v_fmac_f32_e32 v67, v68, v67
	v_div_scale_f32 v68, vcc, v75, v65, v75
	v_mul_f32_e32 v69, v68, v67
	v_fma_f32 v70, -v66, v69, v68
	v_fmac_f32_e32 v69, v70, v67
	v_fma_f32 v66, -v66, v69, v68
	v_div_fmas_f32 v66, v66, v67, v69
	v_div_fixup_f32 v65, v66, v65, v75
	v_mul_f32_e32 v64, v65, v64
	v_mul_f32_e32 v65, 0xbfb8aa3b, v76
	v_exp_f32_e32 v65, v65
	v_cvt_pk_bf16_f32 v64, v64, s0
	ds_write_b16 v128, v64 offset:13936
	ds_read_u16 v64, v128 offset:15296
	v_add_f32_e32 v65, 1.0, v65
	v_div_scale_f32 v66, s[0:1], v65, v65, v76
	v_rcp_f32_e32 v67, v66
	s_waitcnt lgkmcnt(0)
	v_lshlrev_b32_e32 v64, 16, v64
	v_fma_f32 v68, -v66, v67, 1.0
	v_fmac_f32_e32 v67, v68, v67
	v_div_scale_f32 v68, vcc, v76, v65, v76
	v_mul_f32_e32 v69, v68, v67
	v_fma_f32 v70, -v66, v69, v68
	v_fmac_f32_e32 v69, v70, v67
	v_fma_f32 v66, -v66, v69, v68
	v_div_fmas_f32 v66, v66, v67, v69
	v_div_fixup_f32 v65, v66, v65, v76
	v_mul_f32_e32 v64, v65, v64
	v_mul_f32_e32 v65, 0xbfb8aa3b, v77
	v_exp_f32_e32 v65, v65
	v_cvt_pk_bf16_f32 v64, v64, s0
	ds_write_b16 v128, v64 offset:15296
	ds_read_u16 v64, v128 offset:15568
	v_add_f32_e32 v65, 1.0, v65
	v_div_scale_f32 v66, s[0:1], v65, v65, v77
	v_rcp_f32_e32 v67, v66
	s_waitcnt lgkmcnt(0)
	v_lshlrev_b32_e32 v64, 16, v64
	v_fma_f32 v68, -v66, v67, 1.0
	v_fmac_f32_e32 v67, v68, v67
	v_div_scale_f32 v68, vcc, v77, v65, v77
	v_mul_f32_e32 v69, v68, v67
	v_fma_f32 v70, -v66, v69, v68
	v_fmac_f32_e32 v69, v70, v67
	v_fma_f32 v66, -v66, v69, v68
	v_div_fmas_f32 v66, v66, v67, v69
	v_div_fixup_f32 v65, v66, v65, v77
	v_mul_f32_e32 v64, v65, v64
	v_mul_f32_e32 v65, 0xbfb8aa3b, v78
	v_exp_f32_e32 v65, v65
	v_cvt_pk_bf16_f32 v64, v64, s0
	ds_write_b16 v128, v64 offset:15568
	ds_read_u16 v64, v128 offset:15840
	v_add_f32_e32 v65, 1.0, v65
	v_div_scale_f32 v66, s[0:1], v65, v65, v78
	v_rcp_f32_e32 v67, v66
	s_waitcnt lgkmcnt(0)
	v_lshlrev_b32_e32 v64, 16, v64
	v_fma_f32 v68, -v66, v67, 1.0
	v_fmac_f32_e32 v67, v68, v67
	v_div_scale_f32 v68, vcc, v78, v65, v78
	v_mul_f32_e32 v69, v68, v67
	v_fma_f32 v70, -v66, v69, v68
	v_fmac_f32_e32 v69, v70, v67
	v_fma_f32 v66, -v66, v69, v68
	v_div_fmas_f32 v66, v66, v67, v69
	v_div_fixup_f32 v65, v66, v65, v78
	v_mul_f32_e32 v64, v65, v64
	v_mul_f32_e32 v65, 0xbfb8aa3b, v79
	v_exp_f32_e32 v65, v65
	v_cvt_pk_bf16_f32 v64, v64, s0
	ds_write_b16 v128, v64 offset:15840
	ds_read_u16 v64, v128 offset:16112
	v_add_f32_e32 v65, 1.0, v65
	v_div_scale_f32 v66, s[0:1], v65, v65, v79
	v_rcp_f32_e32 v67, v66
	s_waitcnt lgkmcnt(0)
	v_lshlrev_b32_e32 v64, 16, v64
	v_fma_f32 v68, -v66, v67, 1.0
	v_fmac_f32_e32 v67, v68, v67
	v_div_scale_f32 v68, vcc, v79, v65, v79
	v_mul_f32_e32 v69, v68, v67
	v_fma_f32 v70, -v66, v69, v68
	v_fmac_f32_e32 v69, v70, v67
	v_fma_f32 v66, -v66, v69, v68
	v_div_fmas_f32 v66, v66, v67, v69
	v_div_fixup_f32 v65, v66, v65, v79
	v_mul_f32_e32 v64, v65, v64
	v_mul_f32_e32 v65, 0xbfb8aa3b, v48
	v_exp_f32_e32 v65, v65
	v_cvt_pk_bf16_f32 v64, v64, s0
	ds_write_b16 v128, v64 offset:16112
	ds_read_u16 v64, v128 offset:17408
	v_add_f32_e32 v65, 1.0, v65
	v_div_scale_f32 v66, s[0:1], v65, v65, v48
	v_rcp_f32_e32 v67, v66
	s_waitcnt lgkmcnt(0)
; DEV u16 f2bf(float f) { return (u16)(pk2bf(f, 0.f) & 0xffffu); }
; DEV float bf2f(u16 h) { return __uint_as_float(((unsigned)h) << 16); }
; DEV float siluf_(float x) { return x / (1.0f + __expf(-x)); }
; template <int MI>
; DEV void p4_tile(const Params& p, int l, int m0, int nt, unsigned char* smem) {
;     ...
;     acc_foreach_t<MI>([&](int mi, int ni, int r, int row, int col) __attribute__((always_inline)) {
;       sC[row * LDC + col] = f2bf(bf2f(sC[row * LDC + col]) * siluf_(acc[mi][ni][r]));
;     });
	v_lshlrev_b32_e32 v64, 16, v64
	v_fma_f32 v68, -v66, v67, 1.0
	v_fmac_f32_e32 v67, v68, v67
	v_div_scale_f32 v68, vcc, v48, v65, v48
	v_mul_f32_e32 v69, v68, v67
	v_fma_f32 v70, -v66, v69, v68
	v_fmac_f32_e32 v69, v70, v67
	v_fma_f32 v66, -v66, v69, v68
	v_div_fmas_f32 v66, v66, v67, v69
	v_div_fixup_f32 v48, v66, v65, v48
	v_mul_f32_e32 v48, v48, v64
	v_mul_f32_e32 v64, 0xbfb8aa3b, v49
	v_exp_f32_e32 v64, v64
	v_cvt_pk_bf16_f32 v48, v48, s0
	ds_write_b16 v128, v48 offset:17408
	ds_read_u16 v48, v128 offset:17680
	v_add_f32_e32 v64, 1.0, v64
	v_div_scale_f32 v65, s[0:1], v64, v64, v49
	v_rcp_f32_e32 v66, v65
	s_waitcnt lgkmcnt(0)
	v_lshlrev_b32_e32 v48, 16, v48
	v_fma_f32 v67, -v65, v66, 1.0
	v_fmac_f32_e32 v66, v67, v66
	v_div_scale_f32 v67, vcc, v49, v64, v49
	v_mul_f32_e32 v68, v67, v66
	v_fma_f32 v69, -v65, v68, v67
	v_fmac_f32_e32 v68, v69, v66
	v_fma_f32 v65, -v65, v68, v67
	v_div_fmas_f32 v65, v65, v66, v68
	v_div_fixup_f32 v49, v65, v64, v49
	v_mul_f32_e32 v48, v49, v48
	v_mul_f32_e32 v49, 0xbfb8aa3b, v50
	v_exp_f32_e32 v49, v49
	v_cvt_pk_bf16_f32 v48, v48, s0
	ds_write_b16 v128, v48 offset:17680
	ds_read_u16 v48, v128 offset:17952
	v_add_f32_e32 v49, 1.0, v49
	v_div_scale_f32 v64, s[0:1], v49, v49, v50
	v_rcp_f32_e32 v65, v64
	s_waitcnt lgkmcnt(0)
	v_lshlrev_b32_e32 v48, 16, v48
	v_fma_f32 v66, -v64, v65, 1.0
	v_fmac_f32_e32 v65, v66, v65
	v_div_scale_f32 v66, vcc, v50, v49, v50
	v_mul_f32_e32 v67, v66, v65
	v_fma_f32 v68, -v64, v67, v66
	v_fmac_f32_e32 v67, v68, v65
	v_fma_f32 v64, -v64, v67, v66
	v_div_fmas_f32 v64, v64, v65, v67
	v_div_fixup_f32 v49, v64, v49, v50
	v_mul_f32_e32 v48, v49, v48
	v_mul_f32_e32 v49, 0xbfb8aa3b, v51
	v_exp_f32_e32 v49, v49
	v_cvt_pk_bf16_f32 v48, v48, s0
	ds_write_b16 v128, v48 offset:17952
	ds_read_u16 v48, v128 offset:18224
	v_add_f32_e32 v49, 1.0, v49
	v_div_scale_f32 v50, s[0:1], v49, v49, v51
	v_rcp_f32_e32 v64, v50
	s_waitcnt lgkmcnt(0)
	v_lshlrev_b32_e32 v48, 16, v48
	v_fma_f32 v65, -v50, v64, 1.0
	v_fmac_f32_e32 v64, v65, v64
	v_div_scale_f32 v65, vcc, v51, v49, v51
	v_mul_f32_e32 v66, v65, v64
	v_fma_f32 v67, -v50, v66, v65
	v_fmac_f32_e32 v66, v67, v64
	v_fma_f32 v50, -v50, v66, v65
	v_div_fmas_f32 v50, v50, v64, v66
	v_div_fixup_f32 v49, v50, v49, v51
	v_mul_f32_e32 v48, v49, v48
	v_mul_f32_e32 v49, 0xbfb8aa3b, v52
	v_exp_f32_e32 v49, v49
	v_cvt_pk_bf16_f32 v48, v48, s0
	ds_write_b16 v128, v48 offset:18224
	ds_read_u16 v48, v128 offset:19584
	v_add_f32_e32 v49, 1.0, v49
	v_div_scale_f32 v50, s[0:1], v49, v49, v52
	v_rcp_f32_e32 v51, v50
	s_waitcnt lgkmcnt(0)
	v_lshlrev_b32_e32 v48, 16, v48
	v_fma_f32 v64, -v50, v51, 1.0
	v_fmac_f32_e32 v51, v64, v51
	v_div_scale_f32 v64, vcc, v52, v49, v52
	v_mul_f32_e32 v65, v64, v51
	v_fma_f32 v66, -v50, v65, v64
	v_fmac_f32_e32 v65, v66, v51
	v_fma_f32 v50, -v50, v65, v64
	v_div_fmas_f32 v50, v50, v51, v65
	v_div_fixup_f32 v49, v50, v49, v52
	v_mul_f32_e32 v48, v49, v48
	v_mul_f32_e32 v49, 0xbfb8aa3b, v53
	v_exp_f32_e32 v49, v49
	v_cvt_pk_bf16_f32 v48, v48, s0
	ds_write_b16 v128, v48 offset:19584
	ds_read_u16 v48, v128 offset:19856
	v_add_f32_e32 v49, 1.0, v49
	v_div_scale_f32 v50, s[0:1], v49, v49, v53
	v_rcp_f32_e32 v51, v50
	s_waitcnt lgkmcnt(0)
	v_lshlrev_b32_e32 v48, 16, v48
	v_fma_f32 v52, -v50, v51, 1.0
	v_fmac_f32_e32 v51, v52, v51
	v_div_scale_f32 v52, vcc, v53, v49, v53
	v_mul_f32_e32 v64, v52, v51
	v_fma_f32 v65, -v50, v64, v52
	v_fmac_f32_e32 v64, v65, v51
	v_fma_f32 v50, -v50, v64, v52
	v_div_fmas_f32 v50, v50, v51, v64
	v_div_fixup_f32 v49, v50, v49, v53
	v_mul_f32_e32 v48, v49, v48
	v_mul_f32_e32 v49, 0xbfb8aa3b, v54
	v_exp_f32_e32 v49, v49
	v_cvt_pk_bf16_f32 v48, v48, s0
	ds_write_b16 v128, v48 offset:19856
	ds_read_u16 v48, v128 offset:20128
	v_add_f32_e32 v49, 1.0, v49
	v_div_scale_f32 v50, s[0:1], v49, v49, v54
	v_rcp_f32_e32 v51, v50
	s_waitcnt lgkmcnt(0)
	v_lshlrev_b32_e32 v48, 16, v48
	v_fma_f32 v52, -v50, v51, 1.0
	v_fmac_f32_e32 v51, v52, v51
	v_div_scale_f32 v52, vcc, v54, v49, v54
	v_mul_f32_e32 v53, v52, v51
	v_fma_f32 v64, -v50, v53, v52
	v_fmac_f32_e32 v53, v64, v51
	v_fma_f32 v50, -v50, v53, v52
	v_div_fmas_f32 v50, v50, v51, v53
	v_div_fixup_f32 v49, v50, v49, v54
	v_mul_f32_e32 v48, v49, v48
	v_mul_f32_e32 v49, 0xbfb8aa3b, v55
	v_exp_f32_e32 v49, v49
	v_cvt_pk_bf16_f32 v48, v48, s0
	ds_write_b16 v128, v48 offset:20128
	ds_read_u16 v48, v128 offset:20400
	v_add_f32_e32 v49, 1.0, v49
	v_div_scale_f32 v50, s[0:1], v49, v49, v55
	v_rcp_f32_e32 v51, v50
	s_waitcnt lgkmcnt(0)
	v_lshlrev_b32_e32 v48, 16, v48
	v_fma_f32 v52, -v50, v51, 1.0
	v_fmac_f32_e32 v51, v52, v51
	v_div_scale_f32 v52, vcc, v55, v49, v55
	v_mul_f32_e32 v53, v52, v51
	v_fma_f32 v54, -v50, v53, v52
	v_fmac_f32_e32 v53, v54, v51
	v_fma_f32 v50, -v50, v53, v52
	v_div_fmas_f32 v50, v50, v51, v53
	v_div_fixup_f32 v49, v50, v49, v55
	v_mul_f32_e32 v48, v49, v48
	v_mul_f32_e32 v49, 0xbfb8aa3b, v56
	v_exp_f32_e32 v49, v49
	v_cvt_pk_bf16_f32 v48, v48, s0
	ds_write_b16 v128, v48 offset:20400
	ds_read_u16 v48, v128 offset:21760
	v_add_f32_e32 v49, 1.0, v49
	v_div_scale_f32 v50, s[0:1], v49, v49, v56
	v_rcp_f32_e32 v51, v50
	s_waitcnt lgkmcnt(0)
	v_lshlrev_b32_e32 v48, 16, v48
	v_fma_f32 v52, -v50, v51, 1.0
	v_fmac_f32_e32 v51, v52, v51
	v_div_scale_f32 v52, vcc, v56, v49, v56
	v_mul_f32_e32 v53, v52, v51
	v_fma_f32 v54, -v50, v53, v52
	v_fmac_f32_e32 v53, v54, v51
	v_fma_f32 v50, -v50, v53, v52
	v_div_fmas_f32 v50, v50, v51, v53
	v_div_fixup_f32 v49, v50, v49, v56
	v_mul_f32_e32 v48, v49, v48
	v_mul_f32_e32 v49, 0xbfb8aa3b, v57
	v_exp_f32_e32 v49, v49
	v_cvt_pk_bf16_f32 v48, v48, s0
	ds_write_b16 v128, v48 offset:21760
	ds_read_u16 v48, v128 offset:22032
	v_add_f32_e32 v49, 1.0, v49
	v_div_scale_f32 v50, s[0:1], v49, v49, v57
	v_rcp_f32_e32 v51, v50
	s_waitcnt lgkmcnt(0)
; DEV u16 f2bf(float f) { return (u16)(pk2bf(f, 0.f) & 0xffffu); }
; DEV float bf2f(u16 h) { return __uint_as_float(((unsigned)h) << 16); }
; DEV float siluf_(float x) { return x / (1.0f + __expf(-x)); }
; template <int MI>
; DEV void p4_tile(const Params& p, int l, int m0, int nt, unsigned char* smem) {
;     ...
;     acc_foreach_t<MI>([&](int mi, int ni, int r, int row, int col) __attribute__((always_inline)) {
;       sC[row * LDC + col] = f2bf(bf2f(sC[row * LDC + col]) * siluf_(acc[mi][ni][r]));
;     });
	v_lshlrev_b32_e32 v48, 16, v48
	v_fma_f32 v52, -v50, v51, 1.0
	v_fmac_f32_e32 v51, v52, v51
	v_div_scale_f32 v52, vcc, v57, v49, v57
	v_mul_f32_e32 v53, v52, v51
	v_fma_f32 v54, -v50, v53, v52
	v_fmac_f32_e32 v53, v54, v51
	v_fma_f32 v50, -v50, v53, v52
	v_div_fmas_f32 v50, v50, v51, v53
	v_div_fixup_f32 v49, v50, v49, v57
	v_mul_f32_e32 v48, v49, v48
	v_mul_f32_e32 v49, 0xbfb8aa3b, v58
	v_exp_f32_e32 v49, v49
	v_cvt_pk_bf16_f32 v48, v48, s0
	ds_write_b16 v128, v48 offset:22032
	ds_read_u16 v48, v128 offset:22304
	v_add_f32_e32 v49, 1.0, v49
	v_div_scale_f32 v50, s[0:1], v49, v49, v58
	v_rcp_f32_e32 v51, v50
	s_waitcnt lgkmcnt(0)
	v_lshlrev_b32_e32 v48, 16, v48
	v_fma_f32 v52, -v50, v51, 1.0
	v_fmac_f32_e32 v51, v52, v51
	v_div_scale_f32 v52, vcc, v58, v49, v58
	v_mul_f32_e32 v53, v52, v51
	v_fma_f32 v54, -v50, v53, v52
	v_fmac_f32_e32 v53, v54, v51
	v_fma_f32 v50, -v50, v53, v52
	v_div_fmas_f32 v50, v50, v51, v53
	v_div_fixup_f32 v49, v50, v49, v58
	v_mul_f32_e32 v48, v49, v48
	v_mul_f32_e32 v49, 0xbfb8aa3b, v59
	v_exp_f32_e32 v49, v49
	v_cvt_pk_bf16_f32 v48, v48, s0
	ds_write_b16 v128, v48 offset:22304
	ds_read_u16 v48, v128 offset:22576
	v_add_f32_e32 v49, 1.0, v49
	v_div_scale_f32 v50, s[0:1], v49, v49, v59
	v_rcp_f32_e32 v51, v50
	s_waitcnt lgkmcnt(0)
	v_lshlrev_b32_e32 v48, 16, v48
	v_fma_f32 v52, -v50, v51, 1.0
	v_fmac_f32_e32 v51, v52, v51
	v_div_scale_f32 v52, vcc, v59, v49, v59
	v_mul_f32_e32 v53, v52, v51
	v_fma_f32 v54, -v50, v53, v52
	v_fmac_f32_e32 v53, v54, v51
	v_fma_f32 v50, -v50, v53, v52
	v_div_fmas_f32 v50, v50, v51, v53
	v_div_fixup_f32 v49, v50, v49, v59
	v_mul_f32_e32 v48, v49, v48
	v_mul_f32_e32 v49, 0xbfb8aa3b, v60
	v_exp_f32_e32 v49, v49
	v_cvt_pk_bf16_f32 v48, v48, s0
	ds_write_b16 v128, v48 offset:22576
	ds_read_u16 v48, v128 offset:23936
	v_add_f32_e32 v49, 1.0, v49
	v_div_scale_f32 v50, s[0:1], v49, v49, v60
	v_rcp_f32_e32 v51, v50
	s_waitcnt lgkmcnt(0)
	v_lshlrev_b32_e32 v48, 16, v48
	v_fma_f32 v52, -v50, v51, 1.0
	v_fmac_f32_e32 v51, v52, v51
	v_div_scale_f32 v52, vcc, v60, v49, v60
	v_mul_f32_e32 v53, v52, v51
	v_fma_f32 v54, -v50, v53, v52
	v_fmac_f32_e32 v53, v54, v51
	v_fma_f32 v50, -v50, v53, v52
	v_div_fmas_f32 v50, v50, v51, v53
	v_div_fixup_f32 v49, v50, v49, v60
	v_mul_f32_e32 v48, v49, v48
	v_mul_f32_e32 v49, 0xbfb8aa3b, v61
	v_exp_f32_e32 v49, v49
	v_cvt_pk_bf16_f32 v48, v48, s0
	ds_write_b16 v128, v48 offset:23936
	ds_read_u16 v48, v128 offset:24208
	v_add_f32_e32 v49, 1.0, v49
	v_div_scale_f32 v50, s[0:1], v49, v49, v61
	v_rcp_f32_e32 v51, v50
	s_waitcnt lgkmcnt(0)
	v_lshlrev_b32_e32 v48, 16, v48
	v_fma_f32 v52, -v50, v51, 1.0
	v_fmac_f32_e32 v51, v52, v51
	v_div_scale_f32 v52, vcc, v61, v49, v61
	v_mul_f32_e32 v53, v52, v51
	v_fma_f32 v54, -v50, v53, v52
	v_fmac_f32_e32 v53, v54, v51
	v_fma_f32 v50, -v50, v53, v52
	v_div_fmas_f32 v50, v50, v51, v53
	v_div_fixup_f32 v49, v50, v49, v61
	v_mul_f32_e32 v48, v49, v48
	v_mul_f32_e32 v49, 0xbfb8aa3b, v62
	v_exp_f32_e32 v49, v49
	v_cvt_pk_bf16_f32 v48, v48, s0
	ds_write_b16 v128, v48 offset:24208
	ds_read_u16 v48, v128 offset:24480
	v_add_f32_e32 v49, 1.0, v49
	v_div_scale_f32 v50, s[0:1], v49, v49, v62
	v_rcp_f32_e32 v51, v50
	s_waitcnt lgkmcnt(0)
	v_lshlrev_b32_e32 v48, 16, v48
	v_fma_f32 v52, -v50, v51, 1.0
	v_fmac_f32_e32 v51, v52, v51
	v_div_scale_f32 v52, vcc, v62, v49, v62
	v_mul_f32_e32 v53, v52, v51
	v_fma_f32 v54, -v50, v53, v52
	v_fmac_f32_e32 v53, v54, v51
	v_fma_f32 v50, -v50, v53, v52
	v_div_fmas_f32 v50, v50, v51, v53
	v_div_fixup_f32 v49, v50, v49, v62
	v_mul_f32_e32 v48, v49, v48
	v_mul_f32_e32 v49, 0xbfb8aa3b, v63
	v_exp_f32_e32 v49, v49
	v_cvt_pk_bf16_f32 v48, v48, s0
	ds_write_b16 v128, v48 offset:24480
	ds_read_u16 v48, v128 offset:24752
	v_add_f32_e32 v49, 1.0, v49
	v_div_scale_f32 v50, s[0:1], v49, v49, v63
	v_rcp_f32_e32 v51, v50
	s_waitcnt lgkmcnt(0)
	v_lshlrev_b32_e32 v48, 16, v48
	v_fma_f32 v52, -v50, v51, 1.0
	v_fmac_f32_e32 v51, v52, v51
	v_div_scale_f32 v52, vcc, v63, v49, v63
	v_mul_f32_e32 v53, v52, v51
	v_fma_f32 v54, -v50, v53, v52
	v_fmac_f32_e32 v53, v54, v51
	v_fma_f32 v50, -v50, v53, v52
	v_div_fmas_f32 v50, v50, v51, v53
	v_div_fixup_f32 v49, v50, v49, v63
	v_mul_f32_e32 v48, v49, v48
	v_mul_f32_e32 v49, 0xbfb8aa3b, v32
	v_exp_f32_e32 v49, v49
	v_cvt_pk_bf16_f32 v48, v48, s0
	ds_write_b16 v128, v48 offset:24752
	ds_read_u16 v48, v128 offset:17472
	v_add_f32_e32 v49, 1.0, v49
	v_div_scale_f32 v50, s[0:1], v49, v49, v32
	v_rcp_f32_e32 v51, v50
	s_waitcnt lgkmcnt(0)
	v_lshlrev_b32_e32 v48, 16, v48
	v_fma_f32 v52, -v50, v51, 1.0
	v_fmac_f32_e32 v51, v52, v51
	v_div_scale_f32 v52, vcc, v32, v49, v32
	v_mul_f32_e32 v53, v52, v51
	v_fma_f32 v54, -v50, v53, v52
	v_fmac_f32_e32 v53, v54, v51
	v_fma_f32 v50, -v50, v53, v52
	v_div_fmas_f32 v50, v50, v51, v53
	v_div_fixup_f32 v32, v50, v49, v32
	v_mul_f32_e32 v32, v32, v48
	v_mul_f32_e32 v48, 0xbfb8aa3b, v33
	v_exp_f32_e32 v48, v48
	v_cvt_pk_bf16_f32 v32, v32, s0
	ds_write_b16 v128, v32 offset:17472
	ds_read_u16 v32, v128 offset:17744
	v_add_f32_e32 v48, 1.0, v48
	v_div_scale_f32 v49, s[0:1], v48, v48, v33
	v_rcp_f32_e32 v50, v49
	s_waitcnt lgkmcnt(0)
	v_lshlrev_b32_e32 v32, 16, v32
	v_fma_f32 v51, -v49, v50, 1.0
	v_fmac_f32_e32 v50, v51, v50
	v_div_scale_f32 v51, vcc, v33, v48, v33
	v_mul_f32_e32 v52, v51, v50
	v_fma_f32 v53, -v49, v52, v51
	v_fmac_f32_e32 v52, v53, v50
	v_fma_f32 v49, -v49, v52, v51
	v_div_fmas_f32 v49, v49, v50, v52
	v_div_fixup_f32 v33, v49, v48, v33
	v_mul_f32_e32 v32, v33, v32
	v_mul_f32_e32 v33, 0xbfb8aa3b, v34
	v_exp_f32_e32 v33, v33
	v_cvt_pk_bf16_f32 v32, v32, s0
	ds_write_b16 v128, v32 offset:17744
	ds_read_u16 v32, v128 offset:18016
	v_add_f32_e32 v33, 1.0, v33
	v_div_scale_f32 v48, s[0:1], v33, v33, v34
	v_rcp_f32_e32 v49, v48
	s_waitcnt lgkmcnt(0)
; DEV u16 f2bf(float f) { return (u16)(pk2bf(f, 0.f) & 0xffffu); }
; DEV float bf2f(u16 h) { return __uint_as_float(((unsigned)h) << 16); }
; DEV float siluf_(float x) { return x / (1.0f + __expf(-x)); }
; template <int MI>
; DEV void p4_tile(const Params& p, int l, int m0, int nt, unsigned char* smem) {
;     ...
;     acc_foreach_t<MI>([&](int mi, int ni, int r, int row, int col) __attribute__((always_inline)) {
;       sC[row * LDC + col] = f2bf(bf2f(sC[row * LDC + col]) * siluf_(acc[mi][ni][r]));
;     });
	v_lshlrev_b32_e32 v32, 16, v32
	v_fma_f32 v50, -v48, v49, 1.0
	v_fmac_f32_e32 v49, v50, v49
	v_div_scale_f32 v50, vcc, v34, v33, v34
	v_mul_f32_e32 v51, v50, v49
	v_fma_f32 v52, -v48, v51, v50
	v_fmac_f32_e32 v51, v52, v49
	v_fma_f32 v48, -v48, v51, v50
	v_div_fmas_f32 v48, v48, v49, v51
	v_div_fixup_f32 v33, v48, v33, v34
	v_mul_f32_e32 v32, v33, v32
	v_mul_f32_e32 v33, 0xbfb8aa3b, v35
	v_exp_f32_e32 v33, v33
	v_cvt_pk_bf16_f32 v32, v32, s0
	ds_write_b16 v128, v32 offset:18016
	ds_read_u16 v32, v128 offset:18288
	v_add_f32_e32 v33, 1.0, v33
	v_div_scale_f32 v34, s[0:1], v33, v33, v35
	v_rcp_f32_e32 v48, v34
	s_waitcnt lgkmcnt(0)
	v_lshlrev_b32_e32 v32, 16, v32
	v_fma_f32 v49, -v34, v48, 1.0
	v_fmac_f32_e32 v48, v49, v48
	v_div_scale_f32 v49, vcc, v35, v33, v35
	v_mul_f32_e32 v50, v49, v48
	v_fma_f32 v51, -v34, v50, v49
	v_fmac_f32_e32 v50, v51, v48
	v_fma_f32 v34, -v34, v50, v49
	v_div_fmas_f32 v34, v34, v48, v50
	v_div_fixup_f32 v33, v34, v33, v35
	v_mul_f32_e32 v32, v33, v32
	v_mul_f32_e32 v33, 0xbfb8aa3b, v36
	v_exp_f32_e32 v33, v33
	v_cvt_pk_bf16_f32 v32, v32, s0
	ds_write_b16 v128, v32 offset:18288
	ds_read_u16 v32, v128 offset:19648
	v_add_f32_e32 v33, 1.0, v33
	v_div_scale_f32 v34, s[0:1], v33, v33, v36
	v_rcp_f32_e32 v35, v34
	s_waitcnt lgkmcnt(0)
	v_lshlrev_b32_e32 v32, 16, v32
	v_fma_f32 v48, -v34, v35, 1.0
	v_fmac_f32_e32 v35, v48, v35
	v_div_scale_f32 v48, vcc, v36, v33, v36
	v_mul_f32_e32 v49, v48, v35
	v_fma_f32 v50, -v34, v49, v48
	v_fmac_f32_e32 v49, v50, v35
	v_fma_f32 v34, -v34, v49, v48
	v_div_fmas_f32 v34, v34, v35, v49
	v_div_fixup_f32 v33, v34, v33, v36
	v_mul_f32_e32 v32, v33, v32
	v_mul_f32_e32 v33, 0xbfb8aa3b, v37
	v_exp_f32_e32 v33, v33
	v_cvt_pk_bf16_f32 v32, v32, s0
	ds_write_b16 v128, v32 offset:19648
	ds_read_u16 v32, v128 offset:19920
	v_add_f32_e32 v33, 1.0, v33
	v_div_scale_f32 v34, s[0:1], v33, v33, v37
	v_rcp_f32_e32 v35, v34
	s_waitcnt lgkmcnt(0)
	v_lshlrev_b32_e32 v32, 16, v32
	v_fma_f32 v36, -v34, v35, 1.0
	v_fmac_f32_e32 v35, v36, v35
	v_div_scale_f32 v36, vcc, v37, v33, v37
	v_mul_f32_e32 v48, v36, v35
	v_fma_f32 v49, -v34, v48, v36
	v_fmac_f32_e32 v48, v49, v35
	v_fma_f32 v34, -v34, v48, v36
	v_div_fmas_f32 v34, v34, v35, v48
	v_div_fixup_f32 v33, v34, v33, v37
	v_mul_f32_e32 v32, v33, v32
	v_mul_f32_e32 v33, 0xbfb8aa3b, v38
	v_exp_f32_e32 v33, v33
	v_cvt_pk_bf16_f32 v32, v32, s0
	ds_write_b16 v128, v32 offset:19920
	ds_read_u16 v32, v128 offset:20192
	v_add_f32_e32 v33, 1.0, v33
	v_div_scale_f32 v34, s[0:1], v33, v33, v38
	v_rcp_f32_e32 v35, v34
	s_waitcnt lgkmcnt(0)
	v_lshlrev_b32_e32 v32, 16, v32
	v_fma_f32 v36, -v34, v35, 1.0
	v_fmac_f32_e32 v35, v36, v35
	v_div_scale_f32 v36, vcc, v38, v33, v38
	v_mul_f32_e32 v37, v36, v35
	v_fma_f32 v48, -v34, v37, v36
	v_fmac_f32_e32 v37, v48, v35
	v_fma_f32 v34, -v34, v37, v36
	v_div_fmas_f32 v34, v34, v35, v37
	v_div_fixup_f32 v33, v34, v33, v38
	v_mul_f32_e32 v32, v33, v32
	v_mul_f32_e32 v33, 0xbfb8aa3b, v39
	v_exp_f32_e32 v33, v33
	v_cvt_pk_bf16_f32 v32, v32, s0
	ds_write_b16 v128, v32 offset:20192
	ds_read_u16 v32, v128 offset:20464
	v_add_f32_e32 v33, 1.0, v33
	v_div_scale_f32 v34, s[0:1], v33, v33, v39
	v_rcp_f32_e32 v35, v34
	s_waitcnt lgkmcnt(0)
	v_lshlrev_b32_e32 v32, 16, v32
	v_fma_f32 v36, -v34, v35, 1.0
	v_fmac_f32_e32 v35, v36, v35
	v_div_scale_f32 v36, vcc, v39, v33, v39
	v_mul_f32_e32 v37, v36, v35
	v_fma_f32 v38, -v34, v37, v36
	v_fmac_f32_e32 v37, v38, v35
	v_fma_f32 v34, -v34, v37, v36
	v_div_fmas_f32 v34, v34, v35, v37
	v_div_fixup_f32 v33, v34, v33, v39
	v_mul_f32_e32 v32, v33, v32
	v_mul_f32_e32 v33, 0xbfb8aa3b, v40
	v_exp_f32_e32 v33, v33
	v_cvt_pk_bf16_f32 v32, v32, s0
	ds_write_b16 v128, v32 offset:20464
	ds_read_u16 v32, v128 offset:21824
	v_add_f32_e32 v33, 1.0, v33
	v_div_scale_f32 v34, s[0:1], v33, v33, v40
	v_rcp_f32_e32 v35, v34
	s_waitcnt lgkmcnt(0)
	v_lshlrev_b32_e32 v32, 16, v32
	v_fma_f32 v36, -v34, v35, 1.0
	v_fmac_f32_e32 v35, v36, v35
	v_div_scale_f32 v36, vcc, v40, v33, v40
	v_mul_f32_e32 v37, v36, v35
	v_fma_f32 v38, -v34, v37, v36
	v_fmac_f32_e32 v37, v38, v35
	v_fma_f32 v34, -v34, v37, v36
	v_div_fmas_f32 v34, v34, v35, v37
	v_div_fixup_f32 v33, v34, v33, v40
	v_mul_f32_e32 v32, v33, v32
	v_mul_f32_e32 v33, 0xbfb8aa3b, v41
	v_exp_f32_e32 v33, v33
	v_cvt_pk_bf16_f32 v32, v32, s0
	ds_write_b16 v128, v32 offset:21824
	ds_read_u16 v32, v128 offset:22096
	v_add_f32_e32 v33, 1.0, v33
	v_div_scale_f32 v34, s[0:1], v33, v33, v41
	v_rcp_f32_e32 v35, v34
	s_waitcnt lgkmcnt(0)
	v_lshlrev_b32_e32 v32, 16, v32
	v_fma_f32 v36, -v34, v35, 1.0
	v_fmac_f32_e32 v35, v36, v35
	v_div_scale_f32 v36, vcc, v41, v33, v41
	v_mul_f32_e32 v37, v36, v35
	v_fma_f32 v38, -v34, v37, v36
	v_fmac_f32_e32 v37, v38, v35
	v_fma_f32 v34, -v34, v37, v36
	v_div_fmas_f32 v34, v34, v35, v37
	v_div_fixup_f32 v33, v34, v33, v41
	v_mul_f32_e32 v32, v33, v32
	v_mul_f32_e32 v33, 0xbfb8aa3b, v42
	v_exp_f32_e32 v33, v33
	v_cvt_pk_bf16_f32 v32, v32, s0
	ds_write_b16 v128, v32 offset:22096
	ds_read_u16 v32, v128 offset:22368
	v_add_f32_e32 v33, 1.0, v33
	v_div_scale_f32 v34, s[0:1], v33, v33, v42
	v_rcp_f32_e32 v35, v34
	s_waitcnt lgkmcnt(0)
	v_lshlrev_b32_e32 v32, 16, v32
	v_fma_f32 v36, -v34, v35, 1.0
	v_fmac_f32_e32 v35, v36, v35
	v_div_scale_f32 v36, vcc, v42, v33, v42
	v_mul_f32_e32 v37, v36, v35
	v_fma_f32 v38, -v34, v37, v36
	v_fmac_f32_e32 v37, v38, v35
	v_fma_f32 v34, -v34, v37, v36
	v_div_fmas_f32 v34, v34, v35, v37
	v_div_fixup_f32 v33, v34, v33, v42
	v_mul_f32_e32 v32, v33, v32
	v_mul_f32_e32 v33, 0xbfb8aa3b, v43
	v_exp_f32_e32 v33, v33
	v_cvt_pk_bf16_f32 v32, v32, s0
	ds_write_b16 v128, v32 offset:22368
	ds_read_u16 v32, v128 offset:22640
	v_add_f32_e32 v33, 1.0, v33
	v_div_scale_f32 v34, s[0:1], v33, v33, v43
	v_rcp_f32_e32 v35, v34
	s_waitcnt lgkmcnt(0)
; DEV u16 f2bf(float f) { return (u16)(pk2bf(f, 0.f) & 0xffffu); }
; DEV float bf2f(u16 h) { return __uint_as_float(((unsigned)h) << 16); }
; DEV float siluf_(float x) { return x / (1.0f + __expf(-x)); }
; template <int MI>
; DEV void p4_tile(const Params& p, int l, int m0, int nt, unsigned char* smem) {
;     ...
;     acc_foreach_t<MI>([&](int mi, int ni, int r, int row, int col) __attribute__((always_inline)) {
;       sC[row * LDC + col] = f2bf(bf2f(sC[row * LDC + col]) * siluf_(acc[mi][ni][r]));
;     });
	v_lshlrev_b32_e32 v32, 16, v32
	v_fma_f32 v36, -v34, v35, 1.0
	v_fmac_f32_e32 v35, v36, v35
	v_div_scale_f32 v36, vcc, v43, v33, v43
	v_mul_f32_e32 v37, v36, v35
	v_fma_f32 v38, -v34, v37, v36
	v_fmac_f32_e32 v37, v38, v35
	v_fma_f32 v34, -v34, v37, v36
	v_div_fmas_f32 v34, v34, v35, v37
	v_div_fixup_f32 v33, v34, v33, v43
	v_mul_f32_e32 v32, v33, v32
	v_mul_f32_e32 v33, 0xbfb8aa3b, v44
	v_exp_f32_e32 v33, v33
	v_cvt_pk_bf16_f32 v32, v32, s0
	ds_write_b16 v128, v32 offset:22640
	ds_read_u16 v32, v128 offset:24000
	v_add_f32_e32 v33, 1.0, v33
	v_div_scale_f32 v34, s[0:1], v33, v33, v44
	v_rcp_f32_e32 v35, v34
	s_waitcnt lgkmcnt(0)
	v_lshlrev_b32_e32 v32, 16, v32
	v_fma_f32 v36, -v34, v35, 1.0
	v_fmac_f32_e32 v35, v36, v35
	v_div_scale_f32 v36, vcc, v44, v33, v44
	v_mul_f32_e32 v37, v36, v35
	v_fma_f32 v38, -v34, v37, v36
	v_fmac_f32_e32 v37, v38, v35
	v_fma_f32 v34, -v34, v37, v36
	v_div_fmas_f32 v34, v34, v35, v37
	v_div_fixup_f32 v33, v34, v33, v44
	v_mul_f32_e32 v32, v33, v32
	v_mul_f32_e32 v33, 0xbfb8aa3b, v45
	v_exp_f32_e32 v33, v33
	v_cvt_pk_bf16_f32 v32, v32, s0
	ds_write_b16 v128, v32 offset:24000
	ds_read_u16 v32, v128 offset:24272
	v_add_f32_e32 v33, 1.0, v33
	v_div_scale_f32 v34, s[0:1], v33, v33, v45
	v_rcp_f32_e32 v35, v34
	s_waitcnt lgkmcnt(0)
	v_lshlrev_b32_e32 v32, 16, v32
	v_fma_f32 v36, -v34, v35, 1.0
	v_fmac_f32_e32 v35, v36, v35
	v_div_scale_f32 v36, vcc, v45, v33, v45
	v_mul_f32_e32 v37, v36, v35
	v_fma_f32 v38, -v34, v37, v36
	v_fmac_f32_e32 v37, v38, v35
	v_fma_f32 v34, -v34, v37, v36
	v_div_fmas_f32 v34, v34, v35, v37
	v_div_fixup_f32 v33, v34, v33, v45
	v_mul_f32_e32 v32, v33, v32
	v_mul_f32_e32 v33, 0xbfb8aa3b, v46
	v_exp_f32_e32 v33, v33
	v_cvt_pk_bf16_f32 v32, v32, s0
	ds_write_b16 v128, v32 offset:24272
	ds_read_u16 v32, v128 offset:24544
	v_add_f32_e32 v33, 1.0, v33
	v_div_scale_f32 v34, s[0:1], v33, v33, v46
	v_rcp_f32_e32 v35, v34
	s_waitcnt lgkmcnt(0)
	v_lshlrev_b32_e32 v32, 16, v32
	v_fma_f32 v36, -v34, v35, 1.0
	v_fmac_f32_e32 v35, v36, v35
	v_div_scale_f32 v36, vcc, v46, v33, v46
	v_mul_f32_e32 v37, v36, v35
	v_fma_f32 v38, -v34, v37, v36
	v_fmac_f32_e32 v37, v38, v35
	v_fma_f32 v34, -v34, v37, v36
	v_div_fmas_f32 v34, v34, v35, v37
	v_div_fixup_f32 v33, v34, v33, v46
	v_mul_f32_e32 v32, v33, v32
	v_mul_f32_e32 v33, 0xbfb8aa3b, v47
	v_exp_f32_e32 v33, v33
	v_cvt_pk_bf16_f32 v32, v32, s0
	ds_write_b16 v128, v32 offset:24544
	ds_read_u16 v32, v128 offset:24816
	v_add_f32_e32 v33, 1.0, v33
	v_div_scale_f32 v34, s[0:1], v33, v33, v47
	v_rcp_f32_e32 v35, v34
	s_waitcnt lgkmcnt(0)
	v_lshlrev_b32_e32 v32, 16, v32
	v_fma_f32 v36, -v34, v35, 1.0
	v_fmac_f32_e32 v35, v36, v35
	v_div_scale_f32 v36, vcc, v47, v33, v47
	v_mul_f32_e32 v37, v36, v35
	v_fma_f32 v38, -v34, v37, v36
	v_fmac_f32_e32 v37, v38, v35
	v_fma_f32 v34, -v34, v37, v36
	v_div_fmas_f32 v34, v34, v35, v37
	v_div_fixup_f32 v33, v34, v33, v47
	v_mul_f32_e32 v32, v33, v32
	v_mul_f32_e32 v33, 0xbfb8aa3b, v16
	v_exp_f32_e32 v33, v33
	v_cvt_pk_bf16_f32 v32, v32, s0
	ds_write_b16 v128, v32 offset:24816
	ds_read_u16 v32, v128 offset:26112
	v_add_f32_e32 v33, 1.0, v33
	v_div_scale_f32 v34, s[0:1], v33, v33, v16
	v_rcp_f32_e32 v35, v34
	s_waitcnt lgkmcnt(0)
	v_lshlrev_b32_e32 v32, 16, v32
	v_fma_f32 v36, -v34, v35, 1.0
	v_fmac_f32_e32 v35, v36, v35
	v_div_scale_f32 v36, vcc, v16, v33, v16
	v_mul_f32_e32 v37, v36, v35
	v_fma_f32 v38, -v34, v37, v36
	v_fmac_f32_e32 v37, v38, v35
	v_fma_f32 v34, -v34, v37, v36
	v_div_fmas_f32 v34, v34, v35, v37
	v_div_fixup_f32 v16, v34, v33, v16
	v_mul_f32_e32 v16, v16, v32
	v_mul_f32_e32 v32, 0xbfb8aa3b, v17
	v_exp_f32_e32 v32, v32
	v_cvt_pk_bf16_f32 v16, v16, s0
	ds_write_b16 v128, v16 offset:26112
	ds_read_u16 v16, v128 offset:26384
	v_add_f32_e32 v32, 1.0, v32
	v_div_scale_f32 v33, s[0:1], v32, v32, v17
	v_rcp_f32_e32 v34, v33
	s_waitcnt lgkmcnt(0)
	v_lshlrev_b32_e32 v16, 16, v16
	v_fma_f32 v35, -v33, v34, 1.0
	v_fmac_f32_e32 v34, v35, v34
	v_div_scale_f32 v35, vcc, v17, v32, v17
	v_mul_f32_e32 v36, v35, v34
	v_fma_f32 v37, -v33, v36, v35
	v_fmac_f32_e32 v36, v37, v34
	v_fma_f32 v33, -v33, v36, v35
	v_div_fmas_f32 v33, v33, v34, v36
	v_div_fixup_f32 v17, v33, v32, v17
	v_mul_f32_e32 v16, v17, v16
	v_mul_f32_e32 v17, 0xbfb8aa3b, v18
	v_exp_f32_e32 v17, v17
	v_cvt_pk_bf16_f32 v16, v16, s0
	ds_write_b16 v128, v16 offset:26384
	ds_read_u16 v16, v128 offset:26656
	v_add_f32_e32 v17, 1.0, v17
	v_div_scale_f32 v32, s[0:1], v17, v17, v18
	v_rcp_f32_e32 v33, v32
	s_waitcnt lgkmcnt(0)
	v_lshlrev_b32_e32 v16, 16, v16
	v_fma_f32 v34, -v32, v33, 1.0
	v_fmac_f32_e32 v33, v34, v33
	v_div_scale_f32 v34, vcc, v18, v17, v18
	v_mul_f32_e32 v35, v34, v33
	v_fma_f32 v36, -v32, v35, v34
	v_fmac_f32_e32 v35, v36, v33
	v_fma_f32 v32, -v32, v35, v34
	v_div_fmas_f32 v32, v32, v33, v35
	v_div_fixup_f32 v17, v32, v17, v18
	v_mul_f32_e32 v16, v17, v16
	v_mul_f32_e32 v17, 0xbfb8aa3b, v19
	v_exp_f32_e32 v17, v17
	v_cvt_pk_bf16_f32 v16, v16, s0
	ds_write_b16 v128, v16 offset:26656
	ds_read_u16 v16, v128 offset:26928
	v_add_f32_e32 v17, 1.0, v17
	v_div_scale_f32 v18, s[0:1], v17, v17, v19
	v_rcp_f32_e32 v32, v18
	s_waitcnt lgkmcnt(0)
	v_lshlrev_b32_e32 v16, 16, v16
	v_fma_f32 v33, -v18, v32, 1.0
	v_fmac_f32_e32 v32, v33, v32
	v_div_scale_f32 v33, vcc, v19, v17, v19
	v_mul_f32_e32 v34, v33, v32
	v_fma_f32 v35, -v18, v34, v33
	v_fmac_f32_e32 v34, v35, v32
	v_fma_f32 v18, -v18, v34, v33
	v_div_fmas_f32 v18, v18, v32, v34
	v_div_fixup_f32 v17, v18, v17, v19
	v_mul_f32_e32 v16, v17, v16
	v_mul_f32_e32 v17, 0xbfb8aa3b, v20
	v_exp_f32_e32 v17, v17
	v_cvt_pk_bf16_f32 v16, v16, s0
	ds_write_b16 v128, v16 offset:26928
	ds_read_u16 v16, v128 offset:28288
	v_add_f32_e32 v17, 1.0, v17
	v_div_scale_f32 v18, s[0:1], v17, v17, v20
	v_rcp_f32_e32 v19, v18
	s_waitcnt lgkmcnt(0)
; DEV u16 f2bf(float f) { return (u16)(pk2bf(f, 0.f) & 0xffffu); }
; DEV float bf2f(u16 h) { return __uint_as_float(((unsigned)h) << 16); }
; DEV float siluf_(float x) { return x / (1.0f + __expf(-x)); }
; template <int MI>
; DEV void p4_tile(const Params& p, int l, int m0, int nt, unsigned char* smem) {
;     ...
;     acc_foreach_t<MI>([&](int mi, int ni, int r, int row, int col) __attribute__((always_inline)) {
;       sC[row * LDC + col] = f2bf(bf2f(sC[row * LDC + col]) * siluf_(acc[mi][ni][r]));
;     });
	v_lshlrev_b32_e32 v16, 16, v16
	v_fma_f32 v32, -v18, v19, 1.0
	v_fmac_f32_e32 v19, v32, v19
	v_div_scale_f32 v32, vcc, v20, v17, v20
	v_mul_f32_e32 v33, v32, v19
	v_fma_f32 v34, -v18, v33, v32
	v_fmac_f32_e32 v33, v34, v19
	v_fma_f32 v18, -v18, v33, v32
	v_div_fmas_f32 v18, v18, v19, v33
	v_div_fixup_f32 v17, v18, v17, v20
	v_mul_f32_e32 v16, v17, v16
	v_mul_f32_e32 v17, 0xbfb8aa3b, v21
	v_exp_f32_e32 v17, v17
	v_cvt_pk_bf16_f32 v16, v16, s0
	ds_write_b16 v128, v16 offset:28288
	ds_read_u16 v16, v128 offset:28560
	v_add_f32_e32 v17, 1.0, v17
	v_div_scale_f32 v18, s[0:1], v17, v17, v21
	v_rcp_f32_e32 v19, v18
	s_waitcnt lgkmcnt(0)
	v_lshlrev_b32_e32 v16, 16, v16
	v_fma_f32 v20, -v18, v19, 1.0
	v_fmac_f32_e32 v19, v20, v19
	v_div_scale_f32 v20, vcc, v21, v17, v21
	v_mul_f32_e32 v32, v20, v19
	v_fma_f32 v33, -v18, v32, v20
	v_fmac_f32_e32 v32, v33, v19
	v_fma_f32 v18, -v18, v32, v20
	v_div_fmas_f32 v18, v18, v19, v32
	v_div_fixup_f32 v17, v18, v17, v21
	v_mul_f32_e32 v16, v17, v16
	v_mul_f32_e32 v17, 0xbfb8aa3b, v22
	v_exp_f32_e32 v17, v17
	v_cvt_pk_bf16_f32 v16, v16, s0
	ds_write_b16 v128, v16 offset:28560
	ds_read_u16 v16, v128 offset:28832
	v_add_f32_e32 v17, 1.0, v17
	v_div_scale_f32 v18, s[0:1], v17, v17, v22
	v_rcp_f32_e32 v19, v18
	s_waitcnt lgkmcnt(0)
	v_lshlrev_b32_e32 v16, 16, v16
	v_fma_f32 v20, -v18, v19, 1.0
	v_fmac_f32_e32 v19, v20, v19
	v_div_scale_f32 v20, vcc, v22, v17, v22
	v_mul_f32_e32 v21, v20, v19
	v_fma_f32 v32, -v18, v21, v20
	v_fmac_f32_e32 v21, v32, v19
	v_fma_f32 v18, -v18, v21, v20
	v_div_fmas_f32 v18, v18, v19, v21
	v_div_fixup_f32 v17, v18, v17, v22
	v_mul_f32_e32 v16, v17, v16
	v_mul_f32_e32 v17, 0xbfb8aa3b, v23
	v_exp_f32_e32 v17, v17
	v_cvt_pk_bf16_f32 v16, v16, s0
	ds_write_b16 v128, v16 offset:28832
	ds_read_u16 v16, v128 offset:29104
	v_add_f32_e32 v17, 1.0, v17
	v_div_scale_f32 v18, s[0:1], v17, v17, v23
	v_rcp_f32_e32 v19, v18
	s_waitcnt lgkmcnt(0)
	v_lshlrev_b32_e32 v16, 16, v16
	v_fma_f32 v20, -v18, v19, 1.0
	v_fmac_f32_e32 v19, v20, v19
	v_div_scale_f32 v20, vcc, v23, v17, v23
	v_mul_f32_e32 v21, v20, v19
	v_fma_f32 v22, -v18, v21, v20
	v_fmac_f32_e32 v21, v22, v19
	v_fma_f32 v18, -v18, v21, v20
	v_div_fmas_f32 v18, v18, v19, v21
	v_div_fixup_f32 v17, v18, v17, v23
	v_mul_f32_e32 v16, v17, v16
	v_mul_f32_e32 v17, 0xbfb8aa3b, v24
	v_exp_f32_e32 v17, v17
	v_cvt_pk_bf16_f32 v16, v16, s0
	ds_write_b16 v128, v16 offset:29104
	ds_read_u16 v16, v128 offset:30464
	v_add_f32_e32 v17, 1.0, v17
	v_div_scale_f32 v18, s[0:1], v17, v17, v24
	v_rcp_f32_e32 v19, v18
	s_waitcnt lgkmcnt(0)
	v_lshlrev_b32_e32 v16, 16, v16
	v_fma_f32 v20, -v18, v19, 1.0
	v_fmac_f32_e32 v19, v20, v19
	v_div_scale_f32 v20, vcc, v24, v17, v24
	v_mul_f32_e32 v21, v20, v19
	v_fma_f32 v22, -v18, v21, v20
	v_fmac_f32_e32 v21, v22, v19
	v_fma_f32 v18, -v18, v21, v20
	v_div_fmas_f32 v18, v18, v19, v21
	v_div_fixup_f32 v17, v18, v17, v24
	v_mul_f32_e32 v16, v17, v16
	v_mul_f32_e32 v17, 0xbfb8aa3b, v25
	v_exp_f32_e32 v17, v17
	v_cvt_pk_bf16_f32 v16, v16, s0
	ds_write_b16 v128, v16 offset:30464
	ds_read_u16 v16, v128 offset:30736
	v_add_f32_e32 v17, 1.0, v17
	v_div_scale_f32 v18, s[0:1], v17, v17, v25
	v_rcp_f32_e32 v19, v18
	s_waitcnt lgkmcnt(0)
	v_lshlrev_b32_e32 v16, 16, v16
	v_fma_f32 v20, -v18, v19, 1.0
	v_fmac_f32_e32 v19, v20, v19
	v_div_scale_f32 v20, vcc, v25, v17, v25
	v_mul_f32_e32 v21, v20, v19
	v_fma_f32 v22, -v18, v21, v20
	v_fmac_f32_e32 v21, v22, v19
	v_fma_f32 v18, -v18, v21, v20
	v_div_fmas_f32 v18, v18, v19, v21
	v_div_fixup_f32 v17, v18, v17, v25
	v_mul_f32_e32 v16, v17, v16
	v_mul_f32_e32 v17, 0xbfb8aa3b, v26
	v_exp_f32_e32 v17, v17
	v_cvt_pk_bf16_f32 v16, v16, s0
	ds_write_b16 v128, v16 offset:30736
	ds_read_u16 v16, v128 offset:31008
	v_add_f32_e32 v17, 1.0, v17
	v_div_scale_f32 v18, s[0:1], v17, v17, v26
	v_rcp_f32_e32 v19, v18
	s_waitcnt lgkmcnt(0)
	v_lshlrev_b32_e32 v16, 16, v16
	v_fma_f32 v20, -v18, v19, 1.0
	v_fmac_f32_e32 v19, v20, v19
	v_div_scale_f32 v20, vcc, v26, v17, v26
	v_mul_f32_e32 v21, v20, v19
	v_fma_f32 v22, -v18, v21, v20
	v_fmac_f32_e32 v21, v22, v19
	v_fma_f32 v18, -v18, v21, v20
	v_div_fmas_f32 v18, v18, v19, v21
	v_div_fixup_f32 v17, v18, v17, v26
	v_mul_f32_e32 v16, v17, v16
	v_mul_f32_e32 v17, 0xbfb8aa3b, v27
	v_exp_f32_e32 v17, v17
	v_cvt_pk_bf16_f32 v16, v16, s0
	ds_write_b16 v128, v16 offset:31008
	ds_read_u16 v16, v128 offset:31280
	v_add_f32_e32 v17, 1.0, v17
	v_div_scale_f32 v18, s[0:1], v17, v17, v27
	v_rcp_f32_e32 v19, v18
	s_waitcnt lgkmcnt(0)
	v_lshlrev_b32_e32 v16, 16, v16
	v_fma_f32 v20, -v18, v19, 1.0
	v_fmac_f32_e32 v19, v20, v19
	v_div_scale_f32 v20, vcc, v27, v17, v27
	v_mul_f32_e32 v21, v20, v19
	v_fma_f32 v22, -v18, v21, v20
	v_fmac_f32_e32 v21, v22, v19
	v_fma_f32 v18, -v18, v21, v20
	v_div_fmas_f32 v18, v18, v19, v21
	v_div_fixup_f32 v17, v18, v17, v27
	v_mul_f32_e32 v16, v17, v16
	v_mul_f32_e32 v17, 0xbfb8aa3b, v28
	v_exp_f32_e32 v17, v17
	v_cvt_pk_bf16_f32 v16, v16, s0
	ds_write_b16 v128, v16 offset:31280
	ds_read_u16 v16, v128 offset:32640
	v_add_f32_e32 v17, 1.0, v17
	v_div_scale_f32 v18, s[0:1], v17, v17, v28
	v_rcp_f32_e32 v19, v18
	s_waitcnt lgkmcnt(0)
	v_lshlrev_b32_e32 v16, 16, v16
	v_fma_f32 v20, -v18, v19, 1.0
	v_fmac_f32_e32 v19, v20, v19
	v_div_scale_f32 v20, vcc, v28, v17, v28
	v_mul_f32_e32 v21, v20, v19
	v_fma_f32 v22, -v18, v21, v20
	v_fmac_f32_e32 v21, v22, v19
	v_fma_f32 v18, -v18, v21, v20
	v_div_fmas_f32 v18, v18, v19, v21
	v_div_fixup_f32 v17, v18, v17, v28
	v_mul_f32_e32 v16, v17, v16
	v_mul_f32_e32 v17, 0xbfb8aa3b, v29
	v_exp_f32_e32 v17, v17
	v_cvt_pk_bf16_f32 v16, v16, s0
	ds_write_b16 v128, v16 offset:32640
	ds_read_u16 v16, v128 offset:32912
	v_add_f32_e32 v17, 1.0, v17
	v_div_scale_f32 v18, s[0:1], v17, v17, v29
	v_rcp_f32_e32 v19, v18
	s_waitcnt lgkmcnt(0)
; DEV u16 f2bf(float f) { return (u16)(pk2bf(f, 0.f) & 0xffffu); }
; DEV float bf2f(u16 h) { return __uint_as_float(((unsigned)h) << 16); }
; DEV float siluf_(float x) { return x / (1.0f + __expf(-x)); }
; template <int MI>
; DEV void p4_tile(const Params& p, int l, int m0, int nt, unsigned char* smem) {
;     ...
;     acc_foreach_t<MI>([&](int mi, int ni, int r, int row, int col) __attribute__((always_inline)) {
;       sC[row * LDC + col] = f2bf(bf2f(sC[row * LDC + col]) * siluf_(acc[mi][ni][r]));
;     });
	v_lshlrev_b32_e32 v16, 16, v16
	v_fma_f32 v20, -v18, v19, 1.0
	v_fmac_f32_e32 v19, v20, v19
	v_div_scale_f32 v20, vcc, v29, v17, v29
	v_mul_f32_e32 v21, v20, v19
	v_fma_f32 v22, -v18, v21, v20
	v_fmac_f32_e32 v21, v22, v19
	v_fma_f32 v18, -v18, v21, v20
	v_div_fmas_f32 v18, v18, v19, v21
	v_div_fixup_f32 v17, v18, v17, v29
	v_mul_f32_e32 v16, v17, v16
	v_mul_f32_e32 v17, 0xbfb8aa3b, v30
	v_exp_f32_e32 v17, v17
	v_cvt_pk_bf16_f32 v16, v16, s0
	ds_write_b16 v128, v16 offset:32912
	ds_read_u16 v16, v128 offset:33184
	v_add_f32_e32 v17, 1.0, v17
	v_div_scale_f32 v18, s[0:1], v17, v17, v30
	v_rcp_f32_e32 v19, v18
	s_waitcnt lgkmcnt(0)
	v_lshlrev_b32_e32 v16, 16, v16
	v_fma_f32 v20, -v18, v19, 1.0
	v_fmac_f32_e32 v19, v20, v19
	v_div_scale_f32 v20, vcc, v30, v17, v30
	v_mul_f32_e32 v21, v20, v19
	v_fma_f32 v22, -v18, v21, v20
	v_fmac_f32_e32 v21, v22, v19
	v_fma_f32 v18, -v18, v21, v20
	v_div_fmas_f32 v18, v18, v19, v21
	v_div_fixup_f32 v17, v18, v17, v30
	v_mul_f32_e32 v16, v17, v16
	v_mul_f32_e32 v17, 0xbfb8aa3b, v31
	v_exp_f32_e32 v17, v17
	v_cvt_pk_bf16_f32 v16, v16, s0
	ds_write_b16 v128, v16 offset:33184
	ds_read_u16 v16, v128 offset:33456
	v_add_f32_e32 v17, 1.0, v17
	v_div_scale_f32 v18, s[0:1], v17, v17, v31
	v_rcp_f32_e32 v19, v18
	s_waitcnt lgkmcnt(0)
	v_lshlrev_b32_e32 v16, 16, v16
	v_fma_f32 v20, -v18, v19, 1.0
	v_fmac_f32_e32 v19, v20, v19
	v_div_scale_f32 v20, vcc, v31, v17, v31
	v_mul_f32_e32 v21, v20, v19
	v_fma_f32 v22, -v18, v21, v20
	v_fmac_f32_e32 v21, v22, v19
	v_fma_f32 v18, -v18, v21, v20
	v_div_fmas_f32 v18, v18, v19, v21
	v_div_fixup_f32 v17, v18, v17, v31
	v_mul_f32_e32 v16, v17, v16
	v_mul_f32_e32 v17, 0xbfb8aa3b, v0
	v_exp_f32_e32 v17, v17
	v_cvt_pk_bf16_f32 v16, v16, s0
	ds_write_b16 v128, v16 offset:33456
	ds_read_u16 v16, v128 offset:26176
	v_add_f32_e32 v17, 1.0, v17
	v_div_scale_f32 v18, s[0:1], v17, v17, v0
	v_rcp_f32_e32 v19, v18
	s_waitcnt lgkmcnt(0)
	v_lshlrev_b32_e32 v16, 16, v16
	v_fma_f32 v20, -v18, v19, 1.0
	v_fmac_f32_e32 v19, v20, v19
	v_div_scale_f32 v20, vcc, v0, v17, v0
	v_mul_f32_e32 v21, v20, v19
	v_fma_f32 v22, -v18, v21, v20
	v_fmac_f32_e32 v21, v22, v19
	v_fma_f32 v18, -v18, v21, v20
	v_div_fmas_f32 v18, v18, v19, v21
	v_div_fixup_f32 v0, v18, v17, v0
	v_mul_f32_e32 v0, v0, v16
	v_mul_f32_e32 v16, 0xbfb8aa3b, v1
	v_exp_f32_e32 v16, v16
	v_cvt_pk_bf16_f32 v0, v0, s0
	ds_write_b16 v128, v0 offset:26176
	ds_read_u16 v0, v128 offset:26448
	v_add_f32_e32 v16, 1.0, v16
	v_div_scale_f32 v17, s[0:1], v16, v16, v1
	v_rcp_f32_e32 v18, v17
	s_waitcnt lgkmcnt(0)
	v_lshlrev_b32_e32 v0, 16, v0
	v_fma_f32 v19, -v17, v18, 1.0
	v_fmac_f32_e32 v18, v19, v18
	v_div_scale_f32 v19, vcc, v1, v16, v1
	v_mul_f32_e32 v20, v19, v18
	v_fma_f32 v21, -v17, v20, v19
	v_fmac_f32_e32 v20, v21, v18
	v_fma_f32 v17, -v17, v20, v19
	v_div_fmas_f32 v17, v17, v18, v20
	v_div_fixup_f32 v1, v17, v16, v1
	v_mul_f32_e32 v0, v1, v0
	v_mul_f32_e32 v1, 0xbfb8aa3b, v2
	v_exp_f32_e32 v1, v1
	v_cvt_pk_bf16_f32 v0, v0, s0
	ds_write_b16 v128, v0 offset:26448
	ds_read_u16 v0, v128 offset:26720
	v_add_f32_e32 v1, 1.0, v1
	v_div_scale_f32 v16, s[0:1], v1, v1, v2
	v_rcp_f32_e32 v17, v16
	s_waitcnt lgkmcnt(0)
	v_lshlrev_b32_e32 v0, 16, v0
	v_fma_f32 v18, -v16, v17, 1.0
	v_fmac_f32_e32 v17, v18, v17
	v_div_scale_f32 v18, vcc, v2, v1, v2
	v_mul_f32_e32 v19, v18, v17
	v_fma_f32 v20, -v16, v19, v18
	v_fmac_f32_e32 v19, v20, v17
	v_fma_f32 v16, -v16, v19, v18
	v_div_fmas_f32 v16, v16, v17, v19
	v_div_fixup_f32 v1, v16, v1, v2
	v_mul_f32_e32 v0, v1, v0
	v_mul_f32_e32 v1, 0xbfb8aa3b, v3
	v_exp_f32_e32 v1, v1
	v_cvt_pk_bf16_f32 v0, v0, s0
	ds_write_b16 v128, v0 offset:26720
	ds_read_u16 v0, v128 offset:26992
	v_add_f32_e32 v1, 1.0, v1
	v_div_scale_f32 v2, s[0:1], v1, v1, v3
	v_rcp_f32_e32 v16, v2
	s_waitcnt lgkmcnt(0)
	v_lshlrev_b32_e32 v0, 16, v0
	v_fma_f32 v17, -v2, v16, 1.0
	v_fmac_f32_e32 v16, v17, v16
	v_div_scale_f32 v17, vcc, v3, v1, v3
	v_mul_f32_e32 v18, v17, v16
	v_fma_f32 v19, -v2, v18, v17
	v_fmac_f32_e32 v18, v19, v16
	v_fma_f32 v2, -v2, v18, v17
	v_div_fmas_f32 v2, v2, v16, v18
	v_div_fixup_f32 v1, v2, v1, v3
	v_mul_f32_e32 v0, v1, v0
	v_mul_f32_e32 v1, 0xbfb8aa3b, v4
	v_exp_f32_e32 v1, v1
	v_cvt_pk_bf16_f32 v0, v0, s0
	ds_write_b16 v128, v0 offset:26992
	ds_read_u16 v0, v128 offset:28352
	v_add_f32_e32 v1, 1.0, v1
	v_div_scale_f32 v2, s[0:1], v1, v1, v4
	v_rcp_f32_e32 v3, v2
	s_waitcnt lgkmcnt(0)
	v_lshlrev_b32_e32 v0, 16, v0
	v_fma_f32 v16, -v2, v3, 1.0
	v_fmac_f32_e32 v3, v16, v3
	v_div_scale_f32 v16, vcc, v4, v1, v4
	v_mul_f32_e32 v17, v16, v3
	v_fma_f32 v18, -v2, v17, v16
	v_fmac_f32_e32 v17, v18, v3
	v_fma_f32 v2, -v2, v17, v16
	v_div_fmas_f32 v2, v2, v3, v17
	v_div_fixup_f32 v1, v2, v1, v4
	v_mul_f32_e32 v0, v1, v0
	v_mul_f32_e32 v1, 0xbfb8aa3b, v5
	v_exp_f32_e32 v1, v1
	v_cvt_pk_bf16_f32 v0, v0, s0
	ds_write_b16 v128, v0 offset:28352
	ds_read_u16 v0, v128 offset:28624
	v_add_f32_e32 v1, 1.0, v1
	v_div_scale_f32 v2, s[0:1], v1, v1, v5
	v_rcp_f32_e32 v3, v2
	s_waitcnt lgkmcnt(0)
	v_lshlrev_b32_e32 v0, 16, v0
	v_fma_f32 v4, -v2, v3, 1.0
	v_fmac_f32_e32 v3, v4, v3
	v_div_scale_f32 v4, vcc, v5, v1, v5
	v_mul_f32_e32 v16, v4, v3
	v_fma_f32 v17, -v2, v16, v4
	v_fmac_f32_e32 v16, v17, v3
	v_fma_f32 v2, -v2, v16, v4
	v_div_fmas_f32 v2, v2, v3, v16
	v_div_fixup_f32 v1, v2, v1, v5
	v_mul_f32_e32 v0, v1, v0
	v_mul_f32_e32 v1, 0xbfb8aa3b, v6
	v_exp_f32_e32 v1, v1
	v_cvt_pk_bf16_f32 v0, v0, s0
	ds_write_b16 v128, v0 offset:28624
	ds_read_u16 v0, v128 offset:28896
	v_add_f32_e32 v1, 1.0, v1
	v_div_scale_f32 v2, s[0:1], v1, v1, v6
	v_rcp_f32_e32 v3, v2
	s_waitcnt lgkmcnt(0)
; DEV u16 f2bf(float f) { return (u16)(pk2bf(f, 0.f) & 0xffffu); }
; DEV float bf2f(u16 h) { return __uint_as_float(((unsigned)h) << 16); }
; DEV float siluf_(float x) { return x / (1.0f + __expf(-x)); }
; template <int MI>
; DEV void tile_store_t(unsigned char* smem, u16* dst, size_t ldd) {
;   const u16* sC = (const u16*)smem;
;   __syncthreads();
; template <int MI>
; DEV void p4_tile(const Params& p, int l, int m0, int nt, unsigned char* smem) {
;     ...
;     acc_foreach_t<MI>([&](int mi, int ni, int r, int row, int col) __attribute__((always_inline)) {
;       sC[row * LDC + col] = f2bf(bf2f(sC[row * LDC + col]) * siluf_(acc[mi][ni][r]));
;     });
;     tile_store_t<MI>(smem, YB + (size_t)m0 * 1024 + nt * 128, 1024);
	v_lshlrev_b32_e32 v0, 16, v0
	v_fma_f32 v4, -v2, v3, 1.0
	v_fmac_f32_e32 v3, v4, v3
	v_div_scale_f32 v4, vcc, v6, v1, v6
	v_mul_f32_e32 v5, v4, v3
	v_fma_f32 v16, -v2, v5, v4
	v_fmac_f32_e32 v5, v16, v3
	v_fma_f32 v2, -v2, v5, v4
	v_div_fmas_f32 v2, v2, v3, v5
	v_div_fixup_f32 v1, v2, v1, v6
	v_mul_f32_e32 v0, v1, v0
	v_mul_f32_e32 v1, 0xbfb8aa3b, v7
	v_exp_f32_e32 v1, v1
	v_cvt_pk_bf16_f32 v0, v0, s0
	ds_write_b16 v128, v0 offset:28896
	ds_read_u16 v0, v128 offset:29168
	v_add_f32_e32 v1, 1.0, v1
	v_div_scale_f32 v2, s[0:1], v1, v1, v7
	v_rcp_f32_e32 v3, v2
	s_waitcnt lgkmcnt(0)
	v_lshlrev_b32_e32 v0, 16, v0
	v_fma_f32 v4, -v2, v3, 1.0
	v_fmac_f32_e32 v3, v4, v3
	v_div_scale_f32 v4, vcc, v7, v1, v7
	v_mul_f32_e32 v5, v4, v3
	v_fma_f32 v6, -v2, v5, v4
	v_fmac_f32_e32 v5, v6, v3
	v_fma_f32 v2, -v2, v5, v4
	v_div_fmas_f32 v2, v2, v3, v5
	v_div_fixup_f32 v1, v2, v1, v7
	v_mul_f32_e32 v0, v1, v0
	v_mul_f32_e32 v1, 0xbfb8aa3b, v8
	v_exp_f32_e32 v1, v1
	v_cvt_pk_bf16_f32 v0, v0, s0
	ds_write_b16 v128, v0 offset:29168
	ds_read_u16 v0, v128 offset:30528
	v_add_f32_e32 v1, 1.0, v1
	v_div_scale_f32 v2, s[0:1], v1, v1, v8
	v_rcp_f32_e32 v3, v2
	s_waitcnt lgkmcnt(0)
	v_lshlrev_b32_e32 v0, 16, v0
	v_fma_f32 v4, -v2, v3, 1.0
	v_fmac_f32_e32 v3, v4, v3
	v_div_scale_f32 v4, vcc, v8, v1, v8
	v_mul_f32_e32 v5, v4, v3
	v_fma_f32 v6, -v2, v5, v4
	v_fmac_f32_e32 v5, v6, v3
	v_fma_f32 v2, -v2, v5, v4
	v_div_fmas_f32 v2, v2, v3, v5
	v_div_fixup_f32 v1, v2, v1, v8
	v_mul_f32_e32 v0, v1, v0
	v_mul_f32_e32 v1, 0xbfb8aa3b, v9
	v_exp_f32_e32 v1, v1
	v_cvt_pk_bf16_f32 v0, v0, s0
	ds_write_b16 v128, v0 offset:30528
	ds_read_u16 v0, v128 offset:30800
	v_add_f32_e32 v1, 1.0, v1
	v_div_scale_f32 v2, s[0:1], v1, v1, v9
	v_rcp_f32_e32 v3, v2
	s_waitcnt lgkmcnt(0)
	v_lshlrev_b32_e32 v0, 16, v0
	v_fma_f32 v4, -v2, v3, 1.0
	v_fmac_f32_e32 v3, v4, v3
	v_div_scale_f32 v4, vcc, v9, v1, v9
	v_mul_f32_e32 v5, v4, v3
	v_fma_f32 v6, -v2, v5, v4
	v_fmac_f32_e32 v5, v6, v3
	v_fma_f32 v2, -v2, v5, v4
	v_div_fmas_f32 v2, v2, v3, v5
	v_div_fixup_f32 v1, v2, v1, v9
	v_mul_f32_e32 v0, v1, v0
	v_mul_f32_e32 v1, 0xbfb8aa3b, v10
	v_exp_f32_e32 v1, v1
	v_cvt_pk_bf16_f32 v0, v0, s0
	ds_write_b16 v128, v0 offset:30800
	ds_read_u16 v0, v128 offset:31072
	v_add_f32_e32 v1, 1.0, v1
	v_div_scale_f32 v2, s[0:1], v1, v1, v10
	v_rcp_f32_e32 v3, v2
	s_waitcnt lgkmcnt(0)
	v_lshlrev_b32_e32 v0, 16, v0
	v_fma_f32 v4, -v2, v3, 1.0
	v_fmac_f32_e32 v3, v4, v3
	v_div_scale_f32 v4, vcc, v10, v1, v10
	v_mul_f32_e32 v5, v4, v3
	v_fma_f32 v6, -v2, v5, v4
	v_fmac_f32_e32 v5, v6, v3
	v_fma_f32 v2, -v2, v5, v4
	v_div_fmas_f32 v2, v2, v3, v5
	v_div_fixup_f32 v1, v2, v1, v10
	v_mul_f32_e32 v0, v1, v0
	v_mul_f32_e32 v1, 0xbfb8aa3b, v11
	v_exp_f32_e32 v1, v1
	v_cvt_pk_bf16_f32 v0, v0, s0
	ds_write_b16 v128, v0 offset:31072
	ds_read_u16 v0, v128 offset:31344
	v_add_f32_e32 v1, 1.0, v1
	v_div_scale_f32 v2, s[0:1], v1, v1, v11
	v_rcp_f32_e32 v3, v2
	s_waitcnt lgkmcnt(0)
	v_lshlrev_b32_e32 v0, 16, v0
	v_fma_f32 v4, -v2, v3, 1.0
	v_fmac_f32_e32 v3, v4, v3
	v_div_scale_f32 v4, vcc, v11, v1, v11
	v_mul_f32_e32 v5, v4, v3
	v_fma_f32 v6, -v2, v5, v4
	v_fmac_f32_e32 v5, v6, v3
	v_fma_f32 v2, -v2, v5, v4
	v_div_fmas_f32 v2, v2, v3, v5
	v_div_fixup_f32 v1, v2, v1, v11
	v_mul_f32_e32 v0, v1, v0
	v_mul_f32_e32 v1, 0xbfb8aa3b, v12
	v_exp_f32_e32 v1, v1
	v_cvt_pk_bf16_f32 v0, v0, s0
	ds_write_b16 v128, v0 offset:31344
	ds_read_u16 v0, v128 offset:32704
	v_add_f32_e32 v1, 1.0, v1
	v_div_scale_f32 v2, s[0:1], v1, v1, v12
	v_rcp_f32_e32 v3, v2
	s_waitcnt lgkmcnt(0)
	v_lshlrev_b32_e32 v0, 16, v0
	v_fma_f32 v4, -v2, v3, 1.0
	v_fmac_f32_e32 v3, v4, v3
	v_div_scale_f32 v4, vcc, v12, v1, v12
	v_mul_f32_e32 v5, v4, v3
	v_fma_f32 v6, -v2, v5, v4
	v_fmac_f32_e32 v5, v6, v3
	v_fma_f32 v2, -v2, v5, v4
	v_div_fmas_f32 v2, v2, v3, v5
	v_div_fixup_f32 v1, v2, v1, v12
	v_mul_f32_e32 v0, v1, v0
	v_mul_f32_e32 v1, 0xbfb8aa3b, v13
	v_exp_f32_e32 v1, v1
	v_cvt_pk_bf16_f32 v0, v0, s0
	ds_write_b16 v128, v0 offset:32704
	ds_read_u16 v0, v128 offset:32976
	v_add_f32_e32 v1, 1.0, v1
	v_div_scale_f32 v2, s[0:1], v1, v1, v13
	v_rcp_f32_e32 v3, v2
	s_waitcnt lgkmcnt(0)
	v_lshlrev_b32_e32 v0, 16, v0
	v_fma_f32 v4, -v2, v3, 1.0
	v_fmac_f32_e32 v3, v4, v3
	v_div_scale_f32 v4, vcc, v13, v1, v13
	v_mul_f32_e32 v5, v4, v3
	v_fma_f32 v6, -v2, v5, v4
	v_fmac_f32_e32 v5, v6, v3
	v_fma_f32 v2, -v2, v5, v4
	v_div_fmas_f32 v2, v2, v3, v5
	v_div_fixup_f32 v1, v2, v1, v13
	v_mul_f32_e32 v0, v1, v0
	v_mul_f32_e32 v1, 0xbfb8aa3b, v14
	v_exp_f32_e32 v1, v1
	v_cvt_pk_bf16_f32 v0, v0, s0
	ds_write_b16 v128, v0 offset:32976
	ds_read_u16 v0, v128 offset:33248
	v_add_f32_e32 v1, 1.0, v1
	v_div_scale_f32 v2, s[0:1], v1, v1, v14
	v_rcp_f32_e32 v3, v2
	s_waitcnt lgkmcnt(0)
	v_lshlrev_b32_e32 v0, 16, v0
	v_fma_f32 v4, -v2, v3, 1.0
	v_fmac_f32_e32 v3, v4, v3
	v_div_scale_f32 v4, vcc, v14, v1, v14
	v_mul_f32_e32 v5, v4, v3
	v_fma_f32 v6, -v2, v5, v4
	v_fmac_f32_e32 v5, v6, v3
	v_fma_f32 v2, -v2, v5, v4
	v_div_fmas_f32 v2, v2, v3, v5
	v_div_fixup_f32 v1, v2, v1, v14
	v_mul_f32_e32 v0, v1, v0
	v_mul_f32_e32 v1, 0xbfb8aa3b, v15
	v_exp_f32_e32 v1, v1
	v_cvt_pk_bf16_f32 v0, v0, s0
	ds_write_b16 v128, v0 offset:33248
	ds_read_u16 v0, v128 offset:33520
	v_add_f32_e32 v1, 1.0, v1
	v_div_scale_f32 v2, s[0:1], v1, v1, v15
	v_rcp_f32_e32 v3, v2
	s_waitcnt lgkmcnt(0)
	v_lshlrev_b32_e32 v0, 16, v0
	v_fma_f32 v4, -v2, v3, 1.0
	v_fmac_f32_e32 v3, v4, v3
	v_div_scale_f32 v4, vcc, v15, v1, v15
	v_mul_f32_e32 v5, v4, v3
	v_fma_f32 v6, -v2, v5, v4
	v_fmac_f32_e32 v5, v6, v3
	v_fma_f32 v2, -v2, v5, v4
	v_div_fmas_f32 v2, v2, v3, v5
	v_div_fixup_f32 v1, v2, v1, v15
	v_mul_f32_e32 v0, v1, v0
	v_cvt_pk_bf16_f32 v0, v0, s0
	s_lshl_b64 s[0:1], s[4:5], 1
	s_add_u32 s0, s17, s0
	s_addc_u32 s1, s18, s1
	s_lshl_b32 s4, s37, 8
	s_add_u32 s4, s0, s4
	ds_write_b16 v128, v0 offset:33520
	s_addc_u32 s5, s1, 0
	v_mov_b32_e32 v0, v232
	s_waitcnt lgkmcnt(0)
	s_barrier

; DEV u16 f2bf(float f) { return (u16)(pk2bf(f, 0.f) & 0xffffu); }
; DEV float bf2f(u16 h) { return __uint_as_float(((unsigned)h) << 16); }
; DEV float siluf_(float x) { return x / (1.0f + __expf(-x)); }
; template <int MI>
; DEV void tile_load_t(unsigned char* smem, const u16* src, size_t lds_) {
;   u16* sC = (u16*)smem;
;   const int tid_ = TIDX();
; #pragma unroll
;   for (int i = 0; i < MI * 4; ++i) {
;     const int c = tid_ + 256 * i, row = c >> 4, cc = (c & 15) * 8;
;     *(bf16x8*)(sC + row * LDC + cc) = __builtin_nontemporal_load((const bf16x8*)(src + (size_t)row * lds_ + cc));
;   }
;   __syncthreads();
; }
; template <int MI>
; DEV void p4_tile(const Params& p, int l, int m0, int nt, unsigned char* smem) {
;     ...
;     tile_load_t<MI>(smem, YA + (size_t)m0 * 1024 + n0, 1024);
;     acc_foreach_t<MI>([&](int mi, int ni, int r, int row, int col) __attribute__((always_inline)) {
;       sC[row * LDC + col] = f2bf(bf2f(sC[row * LDC + col]) * siluf_(acc[mi][ni][r]));
;     });
.LBB0_1218:
	s_lshl_b64 s[4:5], s[4:5], 1
	s_add_u32 s1, s15, s4
	s_addc_u32 s6, s16, s5
	s_lshl_b64 s[4:5], s[96:97], 1
	s_waitcnt vmcnt(11)
	v_mov_b32_e32 v136, v232
	s_barrier
	s_add_u32 s4, s1, s4
	s_addc_u32 s5, s6, s5
	s_waitcnt vmcnt(10)
	v_lshlrev_b32_e32 v128, 4, v136
	s_waitcnt vmcnt(9)
	v_ashrrev_i32_e32 v134, 4, v136
	v_and_b32_e32 v224, 0xf0, v128
	v_ashrrev_i32_e32 v135, 31, v134
	v_lshl_add_u64 v[128:129], s[4:5], 0, v[224:225]
	v_lshlrev_b64 v[204:205], 11, v[134:135]
	v_lshl_add_u64 v[204:205], v[128:129], 0, v[204:205]
	v_mad_u64_u32 v[206:207], s[6:7], v134, s42, v[224:225]
	s_mov_b32 s6, 0x8000
	s_mov_b32 s7, 0
	global_load_dwordx4 v[140:143], v[204:205], off nt
	v_lshl_add_u64 v[204:205], v[204:205], 0, s[6:7]
	global_load_dwordx4 v[144:147], v[204:205], off nt
	v_lshl_add_u64 v[204:205], v[204:205], 0, s[6:7]
	global_load_dwordx4 v[148:151], v[204:205], off nt
	v_lshl_add_u64 v[204:205], v[204:205], 0, s[6:7]
	global_load_dwordx4 v[152:155], v[204:205], off nt
	v_lshl_add_u64 v[204:205], v[204:205], 0, s[6:7]
	global_load_dwordx4 v[156:159], v[204:205], off nt
	v_lshl_add_u64 v[204:205], v[204:205], 0, s[6:7]
	global_load_dwordx4 v[160:163], v[204:205], off nt
	v_lshl_add_u64 v[204:205], v[204:205], 0, s[6:7]
	global_load_dwordx4 v[164:167], v[204:205], off nt
	v_lshl_add_u64 v[204:205], v[204:205], 0, s[6:7]
	global_load_dwordx4 v[168:171], v[204:205], off nt
	v_lshl_add_u64 v[204:205], v[204:205], 0, s[6:7]
	global_load_dwordx4 v[172:175], v[204:205], off nt
	v_lshl_add_u64 v[204:205], v[204:205], 0, s[6:7]
	global_load_dwordx4 v[176:179], v[204:205], off nt
	v_lshl_add_u64 v[204:205], v[204:205], 0, s[6:7]
	global_load_dwordx4 v[180:183], v[204:205], off nt
	v_lshl_add_u64 v[204:205], v[204:205], 0, s[6:7]
	global_load_dwordx4 v[184:187], v[204:205], off nt
	v_lshl_add_u64 v[204:205], v[204:205], 0, s[6:7]
	global_load_dwordx4 v[188:191], v[204:205], off nt
	v_lshl_add_u64 v[204:205], v[204:205], 0, s[6:7]
	global_load_dwordx4 v[192:195], v[204:205], off nt
	v_lshl_add_u64 v[204:205], v[204:205], 0, s[6:7]
	global_load_dwordx4 v[196:199], v[204:205], off nt
	v_lshl_add_u64 v[204:205], v[204:205], 0, s[6:7]
	global_load_dwordx4 v[200:203], v[204:205], off nt
	s_waitcnt vmcnt(15)
	ds_write_b128 v206, v[140:143]
	s_waitcnt vmcnt(14)
	ds_write_b128 v206, v[144:147] offset:4352
	s_waitcnt vmcnt(13)
	ds_write_b128 v206, v[148:151] offset:8704
	s_waitcnt vmcnt(12)
	ds_write_b128 v206, v[152:155] offset:13056
	s_waitcnt vmcnt(11)
	ds_write_b128 v206, v[156:159] offset:17408
	s_waitcnt vmcnt(10)
	ds_write_b128 v206, v[160:163] offset:21760
	s_waitcnt vmcnt(9)
	ds_write_b128 v206, v[164:167] offset:26112
	s_waitcnt vmcnt(8)
	ds_write_b128 v206, v[168:171] offset:30464
	s_waitcnt vmcnt(7)
	ds_write_b128 v206, v[172:175] offset:34816
	s_waitcnt vmcnt(6)
	ds_write_b128 v206, v[176:179] offset:39168
	s_waitcnt vmcnt(5)
	ds_write_b128 v206, v[180:183] offset:43520
	s_waitcnt vmcnt(4)
	ds_write_b128 v206, v[184:187] offset:47872
	s_waitcnt vmcnt(3)
	ds_write_b128 v206, v[188:191] offset:52224
	s_waitcnt vmcnt(2)
	ds_write_b128 v206, v[192:195] offset:56576
	s_waitcnt vmcnt(1)
	ds_write_b128 v206, v[196:199] offset:60928
	s_waitcnt vmcnt(0)
	ds_write_b128 v206, v[200:203] offset:65280
	v_mov_b32_e32 v128, v232
	s_waitcnt lgkmcnt(0)
	s_barrier
	s_nop 0
	v_and_b32_e32 v129, 0xfffff80, v128
	v_lshrrev_b32_e32 v130, 3, v128
	v_and_or_b32 v129, v130, 4, v129
	v_mul_f32_e32 v130, 0xbfb8aa3b, v112
	v_exp_f32_e32 v130, v130
	v_and_b32_e32 v128, 0x5f, v128
	v_mul_lo_u32 v129, v129, s42
	v_lshl_add_u32 v128, v128, 1, v129
	v_add_f32_e32 v130, 1.0, v130
	v_div_scale_f32 v131, s[6:7], v130, v130, v112
	v_rcp_f32_e32 v132, v131
	ds_read_u16 v129, v128
	v_fma_f32 v133, -v131, v132, 1.0
	v_fmac_f32_e32 v132, v133, v132
	v_div_scale_f32 v133, vcc, v112, v130, v112
	v_mul_f32_e32 v134, v133, v132
	v_fma_f32 v135, -v131, v134, v133
	v_fmac_f32_e32 v134, v135, v132
	v_fma_f32 v131, -v131, v134, v133
	v_div_fmas_f32 v131, v131, v132, v134
	s_waitcnt lgkmcnt(0)
	v_lshlrev_b32_e32 v129, 16, v129
	v_div_fixup_f32 v112, v131, v130, v112
	v_mul_f32_e32 v112, v112, v129
	v_mul_f32_e32 v129, 0xbfb8aa3b, v113
	v_exp_f32_e32 v129, v129
	v_cvt_pk_bf16_f32 v112, v112, s0
	ds_write_b16 v128, v112
	ds_read_u16 v112, v128 offset:272
	v_add_f32_e32 v129, 1.0, v129
	v_div_scale_f32 v130, s[6:7], v129, v129, v113
	v_rcp_f32_e32 v131, v130
	s_waitcnt lgkmcnt(0)
	v_lshlrev_b32_e32 v112, 16, v112
	v_fma_f32 v132, -v130, v131, 1.0
	v_fmac_f32_e32 v131, v132, v131
	v_div_scale_f32 v132, vcc, v113, v129, v113
	v_mul_f32_e32 v133, v132, v131
	v_fma_f32 v134, -v130, v133, v132
	v_fmac_f32_e32 v133, v134, v131
	v_fma_f32 v130, -v130, v133, v132
	v_div_fmas_f32 v130, v130, v131, v133
	v_div_fixup_f32 v113, v130, v129, v113
	v_mul_f32_e32 v112, v113, v112
	v_mul_f32_e32 v113, 0xbfb8aa3b, v114
	v_exp_f32_e32 v113, v113
	v_cvt_pk_bf16_f32 v112, v112, s0
	ds_write_b16 v128, v112 offset:272
	ds_read_u16 v112, v128 offset:544
	v_add_f32_e32 v113, 1.0, v113
	v_div_scale_f32 v129, s[6:7], v113, v113, v114
	v_rcp_f32_e32 v130, v129
	s_waitcnt lgkmcnt(0)
	v_lshlrev_b32_e32 v112, 16, v112
	v_fma_f32 v131, -v129, v130, 1.0
	v_fmac_f32_e32 v130, v131, v130
	v_div_scale_f32 v131, vcc, v114, v113, v114
	v_mul_f32_e32 v132, v131, v130
	v_fma_f32 v133, -v129, v132, v131
	v_fmac_f32_e32 v132, v133, v130
	v_fma_f32 v129, -v129, v132, v131
	v_div_fmas_f32 v129, v129, v130, v132
	v_div_fixup_f32 v113, v129, v113, v114
	v_mul_f32_e32 v112, v113, v112
	v_mul_f32_e32 v113, 0xbfb8aa3b, v115
	v_exp_f32_e32 v113, v113
	v_cvt_pk_bf16_f32 v112, v112, s0
	ds_write_b16 v128, v112 offset:544
	ds_read_u16 v112, v128 offset:816
	v_add_f32_e32 v113, 1.0, v113
	v_div_scale_f32 v114, s[6:7], v113, v113, v115
	v_rcp_f32_e32 v129, v114
	s_waitcnt lgkmcnt(0)
; DEV u16 f2bf(float f) { return (u16)(pk2bf(f, 0.f) & 0xffffu); }
; DEV float bf2f(u16 h) { return __uint_as_float(((unsigned)h) << 16); }
; DEV float siluf_(float x) { return x / (1.0f + __expf(-x)); }
; template <int MI>
; DEV void p4_tile(const Params& p, int l, int m0, int nt, unsigned char* smem) {
;     ...
;     acc_foreach_t<MI>([&](int mi, int ni, int r, int row, int col) __attribute__((always_inline)) {
;       sC[row * LDC + col] = f2bf(bf2f(sC[row * LDC + col]) * siluf_(acc[mi][ni][r]));
;     });
	v_lshlrev_b32_e32 v112, 16, v112
	v_fma_f32 v130, -v114, v129, 1.0
	v_fmac_f32_e32 v129, v130, v129
	v_div_scale_f32 v130, vcc, v115, v113, v115
	v_mul_f32_e32 v131, v130, v129
	v_fma_f32 v132, -v114, v131, v130
	v_fmac_f32_e32 v131, v132, v129
	v_fma_f32 v114, -v114, v131, v130
	v_div_fmas_f32 v114, v114, v129, v131
	v_div_fixup_f32 v113, v114, v113, v115
	v_mul_f32_e32 v112, v113, v112
	v_mul_f32_e32 v113, 0xbfb8aa3b, v116
	v_exp_f32_e32 v113, v113
	v_cvt_pk_bf16_f32 v112, v112, s0
	ds_write_b16 v128, v112 offset:816
	ds_read_u16 v112, v128 offset:2176
	v_add_f32_e32 v113, 1.0, v113
	v_div_scale_f32 v114, s[6:7], v113, v113, v116
	v_rcp_f32_e32 v115, v114
	s_waitcnt lgkmcnt(0)
	v_lshlrev_b32_e32 v112, 16, v112
	v_fma_f32 v129, -v114, v115, 1.0
	v_fmac_f32_e32 v115, v129, v115
	v_div_scale_f32 v129, vcc, v116, v113, v116
	v_mul_f32_e32 v130, v129, v115
	v_fma_f32 v131, -v114, v130, v129
	v_fmac_f32_e32 v130, v131, v115
	v_fma_f32 v114, -v114, v130, v129
	v_div_fmas_f32 v114, v114, v115, v130
	v_div_fixup_f32 v113, v114, v113, v116
	v_mul_f32_e32 v112, v113, v112
	v_mul_f32_e32 v113, 0xbfb8aa3b, v117
	v_exp_f32_e32 v113, v113
	v_cvt_pk_bf16_f32 v112, v112, s0
	ds_write_b16 v128, v112 offset:2176
	ds_read_u16 v112, v128 offset:2448
	v_add_f32_e32 v113, 1.0, v113
	v_div_scale_f32 v114, s[6:7], v113, v113, v117
	v_rcp_f32_e32 v115, v114
	s_waitcnt lgkmcnt(0)
	v_lshlrev_b32_e32 v112, 16, v112
	v_fma_f32 v116, -v114, v115, 1.0
	v_fmac_f32_e32 v115, v116, v115
	v_div_scale_f32 v116, vcc, v117, v113, v117
	v_mul_f32_e32 v129, v116, v115
	v_fma_f32 v130, -v114, v129, v116
	v_fmac_f32_e32 v129, v130, v115
	v_fma_f32 v114, -v114, v129, v116
	v_div_fmas_f32 v114, v114, v115, v129
	v_div_fixup_f32 v113, v114, v113, v117
	v_mul_f32_e32 v112, v113, v112
	v_mul_f32_e32 v113, 0xbfb8aa3b, v118
	v_exp_f32_e32 v113, v113
	v_cvt_pk_bf16_f32 v112, v112, s0
	ds_write_b16 v128, v112 offset:2448
	ds_read_u16 v112, v128 offset:2720
	v_add_f32_e32 v113, 1.0, v113
	v_div_scale_f32 v114, s[6:7], v113, v113, v118
	v_rcp_f32_e32 v115, v114
	s_waitcnt lgkmcnt(0)
	v_lshlrev_b32_e32 v112, 16, v112
	v_fma_f32 v116, -v114, v115, 1.0
	v_fmac_f32_e32 v115, v116, v115
	v_div_scale_f32 v116, vcc, v118, v113, v118
	v_mul_f32_e32 v117, v116, v115
	v_fma_f32 v129, -v114, v117, v116
	v_fmac_f32_e32 v117, v129, v115
	v_fma_f32 v114, -v114, v117, v116
	v_div_fmas_f32 v114, v114, v115, v117
	v_div_fixup_f32 v113, v114, v113, v118
	v_mul_f32_e32 v112, v113, v112
	v_mul_f32_e32 v113, 0xbfb8aa3b, v119
	v_exp_f32_e32 v113, v113
	v_cvt_pk_bf16_f32 v112, v112, s0
	ds_write_b16 v128, v112 offset:2720
	ds_read_u16 v112, v128 offset:2992
	v_add_f32_e32 v113, 1.0, v113
	v_div_scale_f32 v114, s[6:7], v113, v113, v119
	v_rcp_f32_e32 v115, v114
	s_waitcnt lgkmcnt(0)
	v_lshlrev_b32_e32 v112, 16, v112
	v_fma_f32 v116, -v114, v115, 1.0
	v_fmac_f32_e32 v115, v116, v115
	v_div_scale_f32 v116, vcc, v119, v113, v119
	v_mul_f32_e32 v117, v116, v115
	v_fma_f32 v118, -v114, v117, v116
	v_fmac_f32_e32 v117, v118, v115
	v_fma_f32 v114, -v114, v117, v116
	v_div_fmas_f32 v114, v114, v115, v117
	v_div_fixup_f32 v113, v114, v113, v119
	v_mul_f32_e32 v112, v113, v112
	v_mul_f32_e32 v113, 0xbfb8aa3b, v120
	v_exp_f32_e32 v113, v113
	v_cvt_pk_bf16_f32 v112, v112, s0
	ds_write_b16 v128, v112 offset:2992
	ds_read_u16 v112, v128 offset:4352
	v_add_f32_e32 v113, 1.0, v113
	v_div_scale_f32 v114, s[6:7], v113, v113, v120
	v_rcp_f32_e32 v115, v114
	s_waitcnt lgkmcnt(0)
	v_lshlrev_b32_e32 v112, 16, v112
	v_fma_f32 v116, -v114, v115, 1.0
	v_fmac_f32_e32 v115, v116, v115
	v_div_scale_f32 v116, vcc, v120, v113, v120
	v_mul_f32_e32 v117, v116, v115
	v_fma_f32 v118, -v114, v117, v116
	v_fmac_f32_e32 v117, v118, v115
	v_fma_f32 v114, -v114, v117, v116
	v_div_fmas_f32 v114, v114, v115, v117
	v_div_fixup_f32 v113, v114, v113, v120
	v_mul_f32_e32 v112, v113, v112
	v_mul_f32_e32 v113, 0xbfb8aa3b, v121
	v_exp_f32_e32 v113, v113
	v_cvt_pk_bf16_f32 v112, v112, s0
	ds_write_b16 v128, v112 offset:4352
	ds_read_u16 v112, v128 offset:4624
	v_add_f32_e32 v113, 1.0, v113
	v_div_scale_f32 v114, s[6:7], v113, v113, v121
	v_rcp_f32_e32 v115, v114
	s_waitcnt lgkmcnt(0)
	v_lshlrev_b32_e32 v112, 16, v112
	v_fma_f32 v116, -v114, v115, 1.0
	v_fmac_f32_e32 v115, v116, v115
	v_div_scale_f32 v116, vcc, v121, v113, v121
	v_mul_f32_e32 v117, v116, v115
	v_fma_f32 v118, -v114, v117, v116
	v_fmac_f32_e32 v117, v118, v115
	v_fma_f32 v114, -v114, v117, v116
	v_div_fmas_f32 v114, v114, v115, v117
	v_div_fixup_f32 v113, v114, v113, v121
	v_mul_f32_e32 v112, v113, v112
	v_mul_f32_e32 v113, 0xbfb8aa3b, v122
	v_exp_f32_e32 v113, v113
	v_cvt_pk_bf16_f32 v112, v112, s0
	ds_write_b16 v128, v112 offset:4624
	ds_read_u16 v112, v128 offset:4896
	v_add_f32_e32 v113, 1.0, v113
	v_div_scale_f32 v114, s[6:7], v113, v113, v122
	v_rcp_f32_e32 v115, v114
	s_waitcnt lgkmcnt(0)
	v_lshlrev_b32_e32 v112, 16, v112
	v_fma_f32 v116, -v114, v115, 1.0
	v_fmac_f32_e32 v115, v116, v115
	v_div_scale_f32 v116, vcc, v122, v113, v122
	v_mul_f32_e32 v117, v116, v115
	v_fma_f32 v118, -v114, v117, v116
	v_fmac_f32_e32 v117, v118, v115
	v_fma_f32 v114, -v114, v117, v116
	v_div_fmas_f32 v114, v114, v115, v117
	v_div_fixup_f32 v113, v114, v113, v122
	v_mul_f32_e32 v112, v113, v112
	v_mul_f32_e32 v113, 0xbfb8aa3b, v123
	v_exp_f32_e32 v113, v113
	v_cvt_pk_bf16_f32 v112, v112, s0
	ds_write_b16 v128, v112 offset:4896
	ds_read_u16 v112, v128 offset:5168
	v_add_f32_e32 v113, 1.0, v113
	v_div_scale_f32 v114, s[6:7], v113, v113, v123
	v_rcp_f32_e32 v115, v114
	s_waitcnt lgkmcnt(0)
; DEV u16 f2bf(float f) { return (u16)(pk2bf(f, 0.f) & 0xffffu); }
; DEV float bf2f(u16 h) { return __uint_as_float(((unsigned)h) << 16); }
; DEV float siluf_(float x) { return x / (1.0f + __expf(-x)); }
; template <int MI>
; DEV void p4_tile(const Params& p, int l, int m0, int nt, unsigned char* smem) {
;     ...
;     acc_foreach_t<MI>([&](int mi, int ni, int r, int row, int col) __attribute__((always_inline)) {
;       sC[row * LDC + col] = f2bf(bf2f(sC[row * LDC + col]) * siluf_(acc[mi][ni][r]));
;     });
	v_lshlrev_b32_e32 v112, 16, v112
	v_fma_f32 v116, -v114, v115, 1.0
	v_fmac_f32_e32 v115, v116, v115
	v_div_scale_f32 v116, vcc, v123, v113, v123
	v_mul_f32_e32 v117, v116, v115
	v_fma_f32 v118, -v114, v117, v116
	v_fmac_f32_e32 v117, v118, v115
	v_fma_f32 v114, -v114, v117, v116
	v_div_fmas_f32 v114, v114, v115, v117
	v_div_fixup_f32 v113, v114, v113, v123
	v_mul_f32_e32 v112, v113, v112
	v_mul_f32_e32 v113, 0xbfb8aa3b, v124
	v_exp_f32_e32 v113, v113
	v_cvt_pk_bf16_f32 v112, v112, s0
	ds_write_b16 v128, v112 offset:5168
	ds_read_u16 v112, v128 offset:6528
	v_add_f32_e32 v113, 1.0, v113
	v_div_scale_f32 v114, s[6:7], v113, v113, v124
	v_rcp_f32_e32 v115, v114
	s_waitcnt lgkmcnt(0)
	v_lshlrev_b32_e32 v112, 16, v112
	v_fma_f32 v116, -v114, v115, 1.0
	v_fmac_f32_e32 v115, v116, v115
	v_div_scale_f32 v116, vcc, v124, v113, v124
	v_mul_f32_e32 v117, v116, v115
	v_fma_f32 v118, -v114, v117, v116
	v_fmac_f32_e32 v117, v118, v115
	v_fma_f32 v114, -v114, v117, v116
	v_div_fmas_f32 v114, v114, v115, v117
	v_div_fixup_f32 v113, v114, v113, v124
	v_mul_f32_e32 v112, v113, v112
	v_mul_f32_e32 v113, 0xbfb8aa3b, v125
	v_exp_f32_e32 v113, v113
	v_cvt_pk_bf16_f32 v112, v112, s0
	ds_write_b16 v128, v112 offset:6528
	ds_read_u16 v112, v128 offset:6800
	v_add_f32_e32 v113, 1.0, v113
	v_div_scale_f32 v114, s[6:7], v113, v113, v125
	v_rcp_f32_e32 v115, v114
	s_waitcnt lgkmcnt(0)
	v_lshlrev_b32_e32 v112, 16, v112
	v_fma_f32 v116, -v114, v115, 1.0
	v_fmac_f32_e32 v115, v116, v115
	v_div_scale_f32 v116, vcc, v125, v113, v125
	v_mul_f32_e32 v117, v116, v115
	v_fma_f32 v118, -v114, v117, v116
	v_fmac_f32_e32 v117, v118, v115
	v_fma_f32 v114, -v114, v117, v116
	v_div_fmas_f32 v114, v114, v115, v117
	v_div_fixup_f32 v113, v114, v113, v125
	v_mul_f32_e32 v112, v113, v112
	v_mul_f32_e32 v113, 0xbfb8aa3b, v126
	v_exp_f32_e32 v113, v113
	v_cvt_pk_bf16_f32 v112, v112, s0
	ds_write_b16 v128, v112 offset:6800
	ds_read_u16 v112, v128 offset:7072
	v_add_f32_e32 v113, 1.0, v113
	v_div_scale_f32 v114, s[6:7], v113, v113, v126
	v_rcp_f32_e32 v115, v114
	s_waitcnt lgkmcnt(0)
	v_lshlrev_b32_e32 v112, 16, v112
	v_fma_f32 v116, -v114, v115, 1.0
	v_fmac_f32_e32 v115, v116, v115
	v_div_scale_f32 v116, vcc, v126, v113, v126
	v_mul_f32_e32 v117, v116, v115
	v_fma_f32 v118, -v114, v117, v116
	v_fmac_f32_e32 v117, v118, v115
	v_fma_f32 v114, -v114, v117, v116
	v_div_fmas_f32 v114, v114, v115, v117
	v_div_fixup_f32 v113, v114, v113, v126
	v_mul_f32_e32 v112, v113, v112
	v_mul_f32_e32 v113, 0xbfb8aa3b, v127
	v_exp_f32_e32 v113, v113
	v_cvt_pk_bf16_f32 v112, v112, s0
	ds_write_b16 v128, v112 offset:7072
	ds_read_u16 v112, v128 offset:7344
	v_add_f32_e32 v113, 1.0, v113
	v_div_scale_f32 v114, s[6:7], v113, v113, v127
	v_rcp_f32_e32 v115, v114
	s_waitcnt lgkmcnt(0)
	v_lshlrev_b32_e32 v112, 16, v112
	v_fma_f32 v116, -v114, v115, 1.0
	v_fmac_f32_e32 v115, v116, v115
	v_div_scale_f32 v116, vcc, v127, v113, v127
	v_mul_f32_e32 v117, v116, v115
	v_fma_f32 v118, -v114, v117, v116
	v_fmac_f32_e32 v117, v118, v115
	v_fma_f32 v114, -v114, v117, v116
	v_div_fmas_f32 v114, v114, v115, v117
	v_div_fixup_f32 v113, v114, v113, v127
	v_mul_f32_e32 v112, v113, v112
	v_mul_f32_e32 v113, 0xbfb8aa3b, v96
	v_exp_f32_e32 v113, v113
	v_cvt_pk_bf16_f32 v112, v112, s0
	ds_write_b16 v128, v112 offset:7344
	ds_read_u16 v112, v128 offset:64
	v_add_f32_e32 v113, 1.0, v113
	v_div_scale_f32 v114, s[6:7], v113, v113, v96
	v_rcp_f32_e32 v115, v114
	s_waitcnt lgkmcnt(0)
	v_lshlrev_b32_e32 v112, 16, v112
	v_fma_f32 v116, -v114, v115, 1.0
	v_fmac_f32_e32 v115, v116, v115
	v_div_scale_f32 v116, vcc, v96, v113, v96
	v_mul_f32_e32 v117, v116, v115
	v_fma_f32 v118, -v114, v117, v116
	v_fmac_f32_e32 v117, v118, v115
	v_fma_f32 v114, -v114, v117, v116
	v_div_fmas_f32 v114, v114, v115, v117
	v_div_fixup_f32 v96, v114, v113, v96
	v_mul_f32_e32 v96, v96, v112
	v_mul_f32_e32 v112, 0xbfb8aa3b, v97
	v_exp_f32_e32 v112, v112
	v_cvt_pk_bf16_f32 v96, v96, s0
	ds_write_b16 v128, v96 offset:64
	ds_read_u16 v96, v128 offset:336
	v_add_f32_e32 v112, 1.0, v112
	v_div_scale_f32 v113, s[6:7], v112, v112, v97
	v_rcp_f32_e32 v114, v113
	s_waitcnt lgkmcnt(0)
	v_lshlrev_b32_e32 v96, 16, v96
	v_fma_f32 v115, -v113, v114, 1.0
	v_fmac_f32_e32 v114, v115, v114
	v_div_scale_f32 v115, vcc, v97, v112, v97
	v_mul_f32_e32 v116, v115, v114
	v_fma_f32 v117, -v113, v116, v115
	v_fmac_f32_e32 v116, v117, v114
	v_fma_f32 v113, -v113, v116, v115
	v_div_fmas_f32 v113, v113, v114, v116
	v_div_fixup_f32 v97, v113, v112, v97
	v_mul_f32_e32 v96, v97, v96
	v_mul_f32_e32 v97, 0xbfb8aa3b, v98
	v_exp_f32_e32 v97, v97
	v_cvt_pk_bf16_f32 v96, v96, s0
	ds_write_b16 v128, v96 offset:336
	ds_read_u16 v96, v128 offset:608
	v_add_f32_e32 v97, 1.0, v97
	v_div_scale_f32 v112, s[6:7], v97, v97, v98
	v_rcp_f32_e32 v113, v112
	s_waitcnt lgkmcnt(0)
	v_lshlrev_b32_e32 v96, 16, v96
	v_fma_f32 v114, -v112, v113, 1.0
	v_fmac_f32_e32 v113, v114, v113
	v_div_scale_f32 v114, vcc, v98, v97, v98
	v_mul_f32_e32 v115, v114, v113
	v_fma_f32 v116, -v112, v115, v114
	v_fmac_f32_e32 v115, v116, v113
	v_fma_f32 v112, -v112, v115, v114
	v_div_fmas_f32 v112, v112, v113, v115
	v_div_fixup_f32 v97, v112, v97, v98
	v_mul_f32_e32 v96, v97, v96
	v_mul_f32_e32 v97, 0xbfb8aa3b, v99
	v_exp_f32_e32 v97, v97
	v_cvt_pk_bf16_f32 v96, v96, s0
	ds_write_b16 v128, v96 offset:608
	ds_read_u16 v96, v128 offset:880
	v_add_f32_e32 v97, 1.0, v97
	v_div_scale_f32 v98, s[6:7], v97, v97, v99
	v_rcp_f32_e32 v112, v98
	s_waitcnt lgkmcnt(0)
; DEV u16 f2bf(float f) { return (u16)(pk2bf(f, 0.f) & 0xffffu); }
; DEV float bf2f(u16 h) { return __uint_as_float(((unsigned)h) << 16); }
; DEV float siluf_(float x) { return x / (1.0f + __expf(-x)); }
; template <int MI>
; DEV void p4_tile(const Params& p, int l, int m0, int nt, unsigned char* smem) {
;     ...
;     acc_foreach_t<MI>([&](int mi, int ni, int r, int row, int col) __attribute__((always_inline)) {
;       sC[row * LDC + col] = f2bf(bf2f(sC[row * LDC + col]) * siluf_(acc[mi][ni][r]));
;     });
	v_lshlrev_b32_e32 v96, 16, v96
	v_fma_f32 v113, -v98, v112, 1.0
	v_fmac_f32_e32 v112, v113, v112
	v_div_scale_f32 v113, vcc, v99, v97, v99
	v_mul_f32_e32 v114, v113, v112
	v_fma_f32 v115, -v98, v114, v113
	v_fmac_f32_e32 v114, v115, v112
	v_fma_f32 v98, -v98, v114, v113
	v_div_fmas_f32 v98, v98, v112, v114
	v_div_fixup_f32 v97, v98, v97, v99
	v_mul_f32_e32 v96, v97, v96
	v_mul_f32_e32 v97, 0xbfb8aa3b, v100
	v_exp_f32_e32 v97, v97
	v_cvt_pk_bf16_f32 v96, v96, s0
	ds_write_b16 v128, v96 offset:880
	ds_read_u16 v96, v128 offset:2240
	v_add_f32_e32 v97, 1.0, v97
	v_div_scale_f32 v98, s[6:7], v97, v97, v100
	v_rcp_f32_e32 v99, v98
	s_waitcnt lgkmcnt(0)
	v_lshlrev_b32_e32 v96, 16, v96
	v_fma_f32 v112, -v98, v99, 1.0
	v_fmac_f32_e32 v99, v112, v99
	v_div_scale_f32 v112, vcc, v100, v97, v100
	v_mul_f32_e32 v113, v112, v99
	v_fma_f32 v114, -v98, v113, v112
	v_fmac_f32_e32 v113, v114, v99
	v_fma_f32 v98, -v98, v113, v112
	v_div_fmas_f32 v98, v98, v99, v113
	v_div_fixup_f32 v97, v98, v97, v100
	v_mul_f32_e32 v96, v97, v96
	v_mul_f32_e32 v97, 0xbfb8aa3b, v101
	v_exp_f32_e32 v97, v97
	v_cvt_pk_bf16_f32 v96, v96, s0
	ds_write_b16 v128, v96 offset:2240
	ds_read_u16 v96, v128 offset:2512
	v_add_f32_e32 v97, 1.0, v97
	v_div_scale_f32 v98, s[6:7], v97, v97, v101
	v_rcp_f32_e32 v99, v98
	s_waitcnt lgkmcnt(0)
	v_lshlrev_b32_e32 v96, 16, v96
	v_fma_f32 v100, -v98, v99, 1.0
	v_fmac_f32_e32 v99, v100, v99
	v_div_scale_f32 v100, vcc, v101, v97, v101
	v_mul_f32_e32 v112, v100, v99
	v_fma_f32 v113, -v98, v112, v100
	v_fmac_f32_e32 v112, v113, v99
	v_fma_f32 v98, -v98, v112, v100
	v_div_fmas_f32 v98, v98, v99, v112
	v_div_fixup_f32 v97, v98, v97, v101
	v_mul_f32_e32 v96, v97, v96
	v_mul_f32_e32 v97, 0xbfb8aa3b, v102
	v_exp_f32_e32 v97, v97
	v_cvt_pk_bf16_f32 v96, v96, s0
	ds_write_b16 v128, v96 offset:2512
	ds_read_u16 v96, v128 offset:2784
	v_add_f32_e32 v97, 1.0, v97
	v_div_scale_f32 v98, s[6:7], v97, v97, v102
	v_rcp_f32_e32 v99, v98
	s_waitcnt lgkmcnt(0)
	v_lshlrev_b32_e32 v96, 16, v96
	v_fma_f32 v100, -v98, v99, 1.0
	v_fmac_f32_e32 v99, v100, v99
	v_div_scale_f32 v100, vcc, v102, v97, v102
	v_mul_f32_e32 v101, v100, v99
	v_fma_f32 v112, -v98, v101, v100
	v_fmac_f32_e32 v101, v112, v99
	v_fma_f32 v98, -v98, v101, v100
	v_div_fmas_f32 v98, v98, v99, v101
	v_div_fixup_f32 v97, v98, v97, v102
	v_mul_f32_e32 v96, v97, v96
	v_mul_f32_e32 v97, 0xbfb8aa3b, v103
	v_exp_f32_e32 v97, v97
	v_cvt_pk_bf16_f32 v96, v96, s0
	ds_write_b16 v128, v96 offset:2784
	ds_read_u16 v96, v128 offset:3056
	v_add_f32_e32 v97, 1.0, v97
	v_div_scale_f32 v98, s[6:7], v97, v97, v103
	v_rcp_f32_e32 v99, v98
	s_waitcnt lgkmcnt(0)
	v_lshlrev_b32_e32 v96, 16, v96
	v_fma_f32 v100, -v98, v99, 1.0
	v_fmac_f32_e32 v99, v100, v99
	v_div_scale_f32 v100, vcc, v103, v97, v103
	v_mul_f32_e32 v101, v100, v99
	v_fma_f32 v102, -v98, v101, v100
	v_fmac_f32_e32 v101, v102, v99
	v_fma_f32 v98, -v98, v101, v100
	v_div_fmas_f32 v98, v98, v99, v101
	v_div_fixup_f32 v97, v98, v97, v103
	v_mul_f32_e32 v96, v97, v96
	v_mul_f32_e32 v97, 0xbfb8aa3b, v104
	v_exp_f32_e32 v97, v97
	v_cvt_pk_bf16_f32 v96, v96, s0
	ds_write_b16 v128, v96 offset:3056
	ds_read_u16 v96, v128 offset:4416
	v_add_f32_e32 v97, 1.0, v97
	v_div_scale_f32 v98, s[6:7], v97, v97, v104
	v_rcp_f32_e32 v99, v98
	s_waitcnt lgkmcnt(0)
	v_lshlrev_b32_e32 v96, 16, v96
	v_fma_f32 v100, -v98, v99, 1.0
	v_fmac_f32_e32 v99, v100, v99
	v_div_scale_f32 v100, vcc, v104, v97, v104
	v_mul_f32_e32 v101, v100, v99
	v_fma_f32 v102, -v98, v101, v100
	v_fmac_f32_e32 v101, v102, v99
	v_fma_f32 v98, -v98, v101, v100
	v_div_fmas_f32 v98, v98, v99, v101
	v_div_fixup_f32 v97, v98, v97, v104
	v_mul_f32_e32 v96, v97, v96
	v_mul_f32_e32 v97, 0xbfb8aa3b, v105
	v_exp_f32_e32 v97, v97
	v_cvt_pk_bf16_f32 v96, v96, s0
	ds_write_b16 v128, v96 offset:4416
	ds_read_u16 v96, v128 offset:4688
	v_add_f32_e32 v97, 1.0, v97
	v_div_scale_f32 v98, s[6:7], v97, v97, v105
	v_rcp_f32_e32 v99, v98
	s_waitcnt lgkmcnt(0)
	v_lshlrev_b32_e32 v96, 16, v96
	v_fma_f32 v100, -v98, v99, 1.0
	v_fmac_f32_e32 v99, v100, v99
	v_div_scale_f32 v100, vcc, v105, v97, v105
	v_mul_f32_e32 v101, v100, v99
	v_fma_f32 v102, -v98, v101, v100
	v_fmac_f32_e32 v101, v102, v99
	v_fma_f32 v98, -v98, v101, v100
	v_div_fmas_f32 v98, v98, v99, v101
	v_div_fixup_f32 v97, v98, v97, v105
	v_mul_f32_e32 v96, v97, v96
	v_mul_f32_e32 v97, 0xbfb8aa3b, v106
	v_exp_f32_e32 v97, v97
	v_cvt_pk_bf16_f32 v96, v96, s0
	ds_write_b16 v128, v96 offset:4688
	ds_read_u16 v96, v128 offset:4960
	v_add_f32_e32 v97, 1.0, v97
	v_div_scale_f32 v98, s[6:7], v97, v97, v106
	v_rcp_f32_e32 v99, v98
	s_waitcnt lgkmcnt(0)
	v_lshlrev_b32_e32 v96, 16, v96
	v_fma_f32 v100, -v98, v99, 1.0
	v_fmac_f32_e32 v99, v100, v99
	v_div_scale_f32 v100, vcc, v106, v97, v106
	v_mul_f32_e32 v101, v100, v99
	v_fma_f32 v102, -v98, v101, v100
	v_fmac_f32_e32 v101, v102, v99
	v_fma_f32 v98, -v98, v101, v100
	v_div_fmas_f32 v98, v98, v99, v101
	v_div_fixup_f32 v97, v98, v97, v106
	v_mul_f32_e32 v96, v97, v96
	v_mul_f32_e32 v97, 0xbfb8aa3b, v107
	v_exp_f32_e32 v97, v97
	v_cvt_pk_bf16_f32 v96, v96, s0
	ds_write_b16 v128, v96 offset:4960
	ds_read_u16 v96, v128 offset:5232
	v_add_f32_e32 v97, 1.0, v97
	v_div_scale_f32 v98, s[6:7], v97, v97, v107
	v_rcp_f32_e32 v99, v98
	s_waitcnt lgkmcnt(0)
	v_lshlrev_b32_e32 v96, 16, v96
	v_fma_f32 v100, -v98, v99, 1.0
	v_fmac_f32_e32 v99, v100, v99
	v_div_scale_f32 v100, vcc, v107, v97, v107
	v_mul_f32_e32 v101, v100, v99
	v_fma_f32 v102, -v98, v101, v100
	v_fmac_f32_e32 v101, v102, v99
	v_fma_f32 v98, -v98, v101, v100
	v_div_fmas_f32 v98, v98, v99, v101
	v_div_fixup_f32 v97, v98, v97, v107
	v_mul_f32_e32 v96, v97, v96
	v_mul_f32_e32 v97, 0xbfb8aa3b, v108
	v_exp_f32_e32 v97, v97
	v_cvt_pk_bf16_f32 v96, v96, s0
	ds_write_b16 v128, v96 offset:5232
	ds_read_u16 v96, v128 offset:6592
	v_add_f32_e32 v97, 1.0, v97
	v_div_scale_f32 v98, s[6:7], v97, v97, v108
	v_rcp_f32_e32 v99, v98
	s_waitcnt lgkmcnt(0)
; DEV u16 f2bf(float f) { return (u16)(pk2bf(f, 0.f) & 0xffffu); }
; DEV float bf2f(u16 h) { return __uint_as_float(((unsigned)h) << 16); }
; DEV float siluf_(float x) { return x / (1.0f + __expf(-x)); }
; template <int MI>
; DEV void p4_tile(const Params& p, int l, int m0, int nt, unsigned char* smem) {
;     ...
;     acc_foreach_t<MI>([&](int mi, int ni, int r, int row, int col) __attribute__((always_inline)) {
;       sC[row * LDC + col] = f2bf(bf2f(sC[row * LDC + col]) * siluf_(acc[mi][ni][r]));
;     });
	v_lshlrev_b32_e32 v96, 16, v96
	v_fma_f32 v100, -v98, v99, 1.0
	v_fmac_f32_e32 v99, v100, v99
	v_div_scale_f32 v100, vcc, v108, v97, v108
	v_mul_f32_e32 v101, v100, v99
	v_fma_f32 v102, -v98, v101, v100
	v_fmac_f32_e32 v101, v102, v99
	v_fma_f32 v98, -v98, v101, v100
	v_div_fmas_f32 v98, v98, v99, v101
	v_div_fixup_f32 v97, v98, v97, v108
	v_mul_f32_e32 v96, v97, v96
	v_mul_f32_e32 v97, 0xbfb8aa3b, v109
	v_exp_f32_e32 v97, v97
	v_cvt_pk_bf16_f32 v96, v96, s0
	ds_write_b16 v128, v96 offset:6592
	ds_read_u16 v96, v128 offset:6864
	v_add_f32_e32 v97, 1.0, v97
	v_div_scale_f32 v98, s[6:7], v97, v97, v109
	v_rcp_f32_e32 v99, v98
	s_waitcnt lgkmcnt(0)
	v_lshlrev_b32_e32 v96, 16, v96
	v_fma_f32 v100, -v98, v99, 1.0
	v_fmac_f32_e32 v99, v100, v99
	v_div_scale_f32 v100, vcc, v109, v97, v109
	v_mul_f32_e32 v101, v100, v99
	v_fma_f32 v102, -v98, v101, v100
	v_fmac_f32_e32 v101, v102, v99
	v_fma_f32 v98, -v98, v101, v100
	v_div_fmas_f32 v98, v98, v99, v101
	v_div_fixup_f32 v97, v98, v97, v109
	v_mul_f32_e32 v96, v97, v96
	v_mul_f32_e32 v97, 0xbfb8aa3b, v110
	v_exp_f32_e32 v97, v97
	v_cvt_pk_bf16_f32 v96, v96, s0
	ds_write_b16 v128, v96 offset:6864
	ds_read_u16 v96, v128 offset:7136
	v_add_f32_e32 v97, 1.0, v97
	v_div_scale_f32 v98, s[6:7], v97, v97, v110
	v_rcp_f32_e32 v99, v98
	s_waitcnt lgkmcnt(0)
	v_lshlrev_b32_e32 v96, 16, v96
	v_fma_f32 v100, -v98, v99, 1.0
	v_fmac_f32_e32 v99, v100, v99
	v_div_scale_f32 v100, vcc, v110, v97, v110
	v_mul_f32_e32 v101, v100, v99
	v_fma_f32 v102, -v98, v101, v100
	v_fmac_f32_e32 v101, v102, v99
	v_fma_f32 v98, -v98, v101, v100
	v_div_fmas_f32 v98, v98, v99, v101
	v_div_fixup_f32 v97, v98, v97, v110
	v_mul_f32_e32 v96, v97, v96
	v_mul_f32_e32 v97, 0xbfb8aa3b, v111
	v_exp_f32_e32 v97, v97
	v_cvt_pk_bf16_f32 v96, v96, s0
	ds_write_b16 v128, v96 offset:7136
	ds_read_u16 v96, v128 offset:7408
	v_add_f32_e32 v97, 1.0, v97
	v_div_scale_f32 v98, s[6:7], v97, v97, v111
	v_rcp_f32_e32 v99, v98
	s_waitcnt lgkmcnt(0)
	v_lshlrev_b32_e32 v96, 16, v96
	v_fma_f32 v100, -v98, v99, 1.0
	v_fmac_f32_e32 v99, v100, v99
	v_div_scale_f32 v100, vcc, v111, v97, v111
	v_mul_f32_e32 v101, v100, v99
	v_fma_f32 v102, -v98, v101, v100
	v_fmac_f32_e32 v101, v102, v99
	v_fma_f32 v98, -v98, v101, v100
	v_div_fmas_f32 v98, v98, v99, v101
	v_div_fixup_f32 v97, v98, v97, v111
	v_mul_f32_e32 v96, v97, v96
	v_mul_f32_e32 v97, 0xbfb8aa3b, v80
	v_exp_f32_e32 v97, v97
	v_cvt_pk_bf16_f32 v96, v96, s0
	ds_write_b16 v128, v96 offset:7408
	ds_read_u16 v96, v128 offset:8704
	v_add_f32_e32 v97, 1.0, v97
	v_div_scale_f32 v98, s[6:7], v97, v97, v80
	v_rcp_f32_e32 v99, v98
	s_waitcnt lgkmcnt(0)
	v_lshlrev_b32_e32 v96, 16, v96
	v_fma_f32 v100, -v98, v99, 1.0
	v_fmac_f32_e32 v99, v100, v99
	v_div_scale_f32 v100, vcc, v80, v97, v80
	v_mul_f32_e32 v101, v100, v99
	v_fma_f32 v102, -v98, v101, v100
	v_fmac_f32_e32 v101, v102, v99
	v_fma_f32 v98, -v98, v101, v100
	v_div_fmas_f32 v98, v98, v99, v101
	v_div_fixup_f32 v80, v98, v97, v80
	v_mul_f32_e32 v80, v80, v96
	v_mul_f32_e32 v96, 0xbfb8aa3b, v81
	v_exp_f32_e32 v96, v96
	v_cvt_pk_bf16_f32 v80, v80, s0
	ds_write_b16 v128, v80 offset:8704
	ds_read_u16 v80, v128 offset:8976
	v_add_f32_e32 v96, 1.0, v96
	v_div_scale_f32 v97, s[6:7], v96, v96, v81
	v_rcp_f32_e32 v98, v97
	s_waitcnt lgkmcnt(0)
	v_lshlrev_b32_e32 v80, 16, v80
	v_fma_f32 v99, -v97, v98, 1.0
	v_fmac_f32_e32 v98, v99, v98
	v_div_scale_f32 v99, vcc, v81, v96, v81
	v_mul_f32_e32 v100, v99, v98
	v_fma_f32 v101, -v97, v100, v99
	v_fmac_f32_e32 v100, v101, v98
	v_fma_f32 v97, -v97, v100, v99
	v_div_fmas_f32 v97, v97, v98, v100
	v_div_fixup_f32 v81, v97, v96, v81
	v_mul_f32_e32 v80, v81, v80
	v_mul_f32_e32 v81, 0xbfb8aa3b, v82
	v_exp_f32_e32 v81, v81
	v_cvt_pk_bf16_f32 v80, v80, s0
	ds_write_b16 v128, v80 offset:8976
	ds_read_u16 v80, v128 offset:9248
	v_add_f32_e32 v81, 1.0, v81
	v_div_scale_f32 v96, s[6:7], v81, v81, v82
	v_rcp_f32_e32 v97, v96
	s_waitcnt lgkmcnt(0)
	v_lshlrev_b32_e32 v80, 16, v80
	v_fma_f32 v98, -v96, v97, 1.0
	v_fmac_f32_e32 v97, v98, v97
	v_div_scale_f32 v98, vcc, v82, v81, v82
	v_mul_f32_e32 v99, v98, v97
	v_fma_f32 v100, -v96, v99, v98
	v_fmac_f32_e32 v99, v100, v97
	v_fma_f32 v96, -v96, v99, v98
	v_div_fmas_f32 v96, v96, v97, v99
	v_div_fixup_f32 v81, v96, v81, v82
	v_mul_f32_e32 v80, v81, v80
	v_mul_f32_e32 v81, 0xbfb8aa3b, v83
	v_exp_f32_e32 v81, v81
	v_cvt_pk_bf16_f32 v80, v80, s0
	ds_write_b16 v128, v80 offset:9248
	ds_read_u16 v80, v128 offset:9520
	v_add_f32_e32 v81, 1.0, v81
	v_div_scale_f32 v82, s[6:7], v81, v81, v83
	v_rcp_f32_e32 v96, v82
	s_waitcnt lgkmcnt(0)
	v_lshlrev_b32_e32 v80, 16, v80
	v_fma_f32 v97, -v82, v96, 1.0
	v_fmac_f32_e32 v96, v97, v96
	v_div_scale_f32 v97, vcc, v83, v81, v83
	v_mul_f32_e32 v98, v97, v96
	v_fma_f32 v99, -v82, v98, v97
	v_fmac_f32_e32 v98, v99, v96
	v_fma_f32 v82, -v82, v98, v97
	v_div_fmas_f32 v82, v82, v96, v98
	v_div_fixup_f32 v81, v82, v81, v83
	v_mul_f32_e32 v80, v81, v80
	v_mul_f32_e32 v81, 0xbfb8aa3b, v84
	v_exp_f32_e32 v81, v81
	v_cvt_pk_bf16_f32 v80, v80, s0
	ds_write_b16 v128, v80 offset:9520
	ds_read_u16 v80, v128 offset:10880
	v_add_f32_e32 v81, 1.0, v81
	v_div_scale_f32 v82, s[6:7], v81, v81, v84
	v_rcp_f32_e32 v83, v82
	s_waitcnt lgkmcnt(0)
	v_lshlrev_b32_e32 v80, 16, v80
	v_fma_f32 v96, -v82, v83, 1.0
	v_fmac_f32_e32 v83, v96, v83
	v_div_scale_f32 v96, vcc, v84, v81, v84
	v_mul_f32_e32 v97, v96, v83
	v_fma_f32 v98, -v82, v97, v96
	v_fmac_f32_e32 v97, v98, v83
	v_fma_f32 v82, -v82, v97, v96
	v_div_fmas_f32 v82, v82, v83, v97
	v_div_fixup_f32 v81, v82, v81, v84
	v_mul_f32_e32 v80, v81, v80
	v_mul_f32_e32 v81, 0xbfb8aa3b, v85
	v_exp_f32_e32 v81, v81
	v_cvt_pk_bf16_f32 v80, v80, s0
	ds_write_b16 v128, v80 offset:10880
	ds_read_u16 v80, v128 offset:11152
	v_add_f32_e32 v81, 1.0, v81
	v_div_scale_f32 v82, s[6:7], v81, v81, v85
	v_rcp_f32_e32 v83, v82
	s_waitcnt lgkmcnt(0)
; DEV u16 f2bf(float f) { return (u16)(pk2bf(f, 0.f) & 0xffffu); }
; DEV float bf2f(u16 h) { return __uint_as_float(((unsigned)h) << 16); }
; DEV float siluf_(float x) { return x / (1.0f + __expf(-x)); }
; template <int MI>
; DEV void p4_tile(const Params& p, int l, int m0, int nt, unsigned char* smem) {
;     ...
;     acc_foreach_t<MI>([&](int mi, int ni, int r, int row, int col) __attribute__((always_inline)) {
;       sC[row * LDC + col] = f2bf(bf2f(sC[row * LDC + col]) * siluf_(acc[mi][ni][r]));
;     });
	v_lshlrev_b32_e32 v80, 16, v80
	v_fma_f32 v84, -v82, v83, 1.0
	v_fmac_f32_e32 v83, v84, v83
	v_div_scale_f32 v84, vcc, v85, v81, v85
	v_mul_f32_e32 v96, v84, v83
	v_fma_f32 v97, -v82, v96, v84
	v_fmac_f32_e32 v96, v97, v83
	v_fma_f32 v82, -v82, v96, v84
	v_div_fmas_f32 v82, v82, v83, v96
	v_div_fixup_f32 v81, v82, v81, v85
	v_mul_f32_e32 v80, v81, v80
	v_mul_f32_e32 v81, 0xbfb8aa3b, v86
	v_exp_f32_e32 v81, v81
	v_cvt_pk_bf16_f32 v80, v80, s0
	ds_write_b16 v128, v80 offset:11152
	ds_read_u16 v80, v128 offset:11424
	v_add_f32_e32 v81, 1.0, v81
	v_div_scale_f32 v82, s[6:7], v81, v81, v86
	v_rcp_f32_e32 v83, v82
	s_waitcnt lgkmcnt(0)
	v_lshlrev_b32_e32 v80, 16, v80
	v_fma_f32 v84, -v82, v83, 1.0
	v_fmac_f32_e32 v83, v84, v83
	v_div_scale_f32 v84, vcc, v86, v81, v86
	v_mul_f32_e32 v85, v84, v83
	v_fma_f32 v96, -v82, v85, v84
	v_fmac_f32_e32 v85, v96, v83
	v_fma_f32 v82, -v82, v85, v84
	v_div_fmas_f32 v82, v82, v83, v85
	v_div_fixup_f32 v81, v82, v81, v86
	v_mul_f32_e32 v80, v81, v80
	v_mul_f32_e32 v81, 0xbfb8aa3b, v87
	v_exp_f32_e32 v81, v81
	v_cvt_pk_bf16_f32 v80, v80, s0
	ds_write_b16 v128, v80 offset:11424
	ds_read_u16 v80, v128 offset:11696
	v_add_f32_e32 v81, 1.0, v81
	v_div_scale_f32 v82, s[6:7], v81, v81, v87
	v_rcp_f32_e32 v83, v82
	s_waitcnt lgkmcnt(0)
	v_lshlrev_b32_e32 v80, 16, v80
	v_fma_f32 v84, -v82, v83, 1.0
	v_fmac_f32_e32 v83, v84, v83
	v_div_scale_f32 v84, vcc, v87, v81, v87
	v_mul_f32_e32 v85, v84, v83
	v_fma_f32 v86, -v82, v85, v84
	v_fmac_f32_e32 v85, v86, v83
	v_fma_f32 v82, -v82, v85, v84
	v_div_fmas_f32 v82, v82, v83, v85
	v_div_fixup_f32 v81, v82, v81, v87
	v_mul_f32_e32 v80, v81, v80
	v_mul_f32_e32 v81, 0xbfb8aa3b, v88
	v_exp_f32_e32 v81, v81
	v_cvt_pk_bf16_f32 v80, v80, s0
	ds_write_b16 v128, v80 offset:11696
	ds_read_u16 v80, v128 offset:13056
	v_add_f32_e32 v81, 1.0, v81
	v_div_scale_f32 v82, s[6:7], v81, v81, v88
	v_rcp_f32_e32 v83, v82
	s_waitcnt lgkmcnt(0)
	v_lshlrev_b32_e32 v80, 16, v80
	v_fma_f32 v84, -v82, v83, 1.0
	v_fmac_f32_e32 v83, v84, v83
	v_div_scale_f32 v84, vcc, v88, v81, v88
	v_mul_f32_e32 v85, v84, v83
	v_fma_f32 v86, -v82, v85, v84
	v_fmac_f32_e32 v85, v86, v83
	v_fma_f32 v82, -v82, v85, v84
	v_div_fmas_f32 v82, v82, v83, v85
	v_div_fixup_f32 v81, v82, v81, v88
	v_mul_f32_e32 v80, v81, v80
	v_mul_f32_e32 v81, 0xbfb8aa3b, v89
	v_exp_f32_e32 v81, v81
	v_cvt_pk_bf16_f32 v80, v80, s0
	ds_write_b16 v128, v80 offset:13056
	ds_read_u16 v80, v128 offset:13328
	v_add_f32_e32 v81, 1.0, v81
	v_div_scale_f32 v82, s[6:7], v81, v81, v89
	v_rcp_f32_e32 v83, v82
	s_waitcnt lgkmcnt(0)
	v_lshlrev_b32_e32 v80, 16, v80
	v_fma_f32 v84, -v82, v83, 1.0
	v_fmac_f32_e32 v83, v84, v83
	v_div_scale_f32 v84, vcc, v89, v81, v89
	v_mul_f32_e32 v85, v84, v83
	v_fma_f32 v86, -v82, v85, v84
	v_fmac_f32_e32 v85, v86, v83
	v_fma_f32 v82, -v82, v85, v84
	v_div_fmas_f32 v82, v82, v83, v85
	v_div_fixup_f32 v81, v82, v81, v89
	v_mul_f32_e32 v80, v81, v80
	v_mul_f32_e32 v81, 0xbfb8aa3b, v90
	v_exp_f32_e32 v81, v81
	v_cvt_pk_bf16_f32 v80, v80, s0
	ds_write_b16 v128, v80 offset:13328
	ds_read_u16 v80, v128 offset:13600
	v_add_f32_e32 v81, 1.0, v81
	v_div_scale_f32 v82, s[6:7], v81, v81, v90
	v_rcp_f32_e32 v83, v82
	s_waitcnt lgkmcnt(0)
	v_lshlrev_b32_e32 v80, 16, v80
	v_fma_f32 v84, -v82, v83, 1.0
	v_fmac_f32_e32 v83, v84, v83
	v_div_scale_f32 v84, vcc, v90, v81, v90
	v_mul_f32_e32 v85, v84, v83
	v_fma_f32 v86, -v82, v85, v84
	v_fmac_f32_e32 v85, v86, v83
	v_fma_f32 v82, -v82, v85, v84
	v_div_fmas_f32 v82, v82, v83, v85
	v_div_fixup_f32 v81, v82, v81, v90
	v_mul_f32_e32 v80, v81, v80
	v_mul_f32_e32 v81, 0xbfb8aa3b, v91
	v_exp_f32_e32 v81, v81
	v_cvt_pk_bf16_f32 v80, v80, s0
	ds_write_b16 v128, v80 offset:13600
	ds_read_u16 v80, v128 offset:13872
	v_add_f32_e32 v81, 1.0, v81
	v_div_scale_f32 v82, s[6:7], v81, v81, v91
	v_rcp_f32_e32 v83, v82
	s_waitcnt lgkmcnt(0)
	v_lshlrev_b32_e32 v80, 16, v80
	v_fma_f32 v84, -v82, v83, 1.0
	v_fmac_f32_e32 v83, v84, v83
	v_div_scale_f32 v84, vcc, v91, v81, v91
	v_mul_f32_e32 v85, v84, v83
	v_fma_f32 v86, -v82, v85, v84
	v_fmac_f32_e32 v85, v86, v83
	v_fma_f32 v82, -v82, v85, v84
	v_div_fmas_f32 v82, v82, v83, v85
	v_div_fixup_f32 v81, v82, v81, v91
	v_mul_f32_e32 v80, v81, v80
	v_mul_f32_e32 v81, 0xbfb8aa3b, v92
	v_exp_f32_e32 v81, v81
	v_cvt_pk_bf16_f32 v80, v80, s0
	ds_write_b16 v128, v80 offset:13872
	ds_read_u16 v80, v128 offset:15232
	v_add_f32_e32 v81, 1.0, v81
	v_div_scale_f32 v82, s[6:7], v81, v81, v92
	v_rcp_f32_e32 v83, v82
	s_waitcnt lgkmcnt(0)
	v_lshlrev_b32_e32 v80, 16, v80
	v_fma_f32 v84, -v82, v83, 1.0
	v_fmac_f32_e32 v83, v84, v83
	v_div_scale_f32 v84, vcc, v92, v81, v92
	v_mul_f32_e32 v85, v84, v83
	v_fma_f32 v86, -v82, v85, v84
	v_fmac_f32_e32 v85, v86, v83
	v_fma_f32 v82, -v82, v85, v84
	v_div_fmas_f32 v82, v82, v83, v85
	v_div_fixup_f32 v81, v82, v81, v92
	v_mul_f32_e32 v80, v81, v80
	v_mul_f32_e32 v81, 0xbfb8aa3b, v93
	v_exp_f32_e32 v81, v81
	v_cvt_pk_bf16_f32 v80, v80, s0
	ds_write_b16 v128, v80 offset:15232
	ds_read_u16 v80, v128 offset:15504
	v_add_f32_e32 v81, 1.0, v81
	v_div_scale_f32 v82, s[6:7], v81, v81, v93
	v_rcp_f32_e32 v83, v82
	s_waitcnt lgkmcnt(0)
	v_lshlrev_b32_e32 v80, 16, v80
	v_fma_f32 v84, -v82, v83, 1.0
	v_fmac_f32_e32 v83, v84, v83
	v_div_scale_f32 v84, vcc, v93, v81, v93
	v_mul_f32_e32 v85, v84, v83
	v_fma_f32 v86, -v82, v85, v84
	v_fmac_f32_e32 v85, v86, v83
	v_fma_f32 v82, -v82, v85, v84
	v_div_fmas_f32 v82, v82, v83, v85
	v_div_fixup_f32 v81, v82, v81, v93
	v_mul_f32_e32 v80, v81, v80
	v_mul_f32_e32 v81, 0xbfb8aa3b, v94
	v_exp_f32_e32 v81, v81
	v_cvt_pk_bf16_f32 v80, v80, s0
	ds_write_b16 v128, v80 offset:15504
	ds_read_u16 v80, v128 offset:15776
	v_add_f32_e32 v81, 1.0, v81
	v_div_scale_f32 v82, s[6:7], v81, v81, v94
	v_rcp_f32_e32 v83, v82
	s_waitcnt lgkmcnt(0)
; DEV u16 f2bf(float f) { return (u16)(pk2bf(f, 0.f) & 0xffffu); }
; DEV float bf2f(u16 h) { return __uint_as_float(((unsigned)h) << 16); }
; DEV float siluf_(float x) { return x / (1.0f + __expf(-x)); }
; template <int MI>
; DEV void p4_tile(const Params& p, int l, int m0, int nt, unsigned char* smem) {
;     ...
;     acc_foreach_t<MI>([&](int mi, int ni, int r, int row, int col) __attribute__((always_inline)) {
;       sC[row * LDC + col] = f2bf(bf2f(sC[row * LDC + col]) * siluf_(acc[mi][ni][r]));
;     });
	v_lshlrev_b32_e32 v80, 16, v80
	v_fma_f32 v84, -v82, v83, 1.0
	v_fmac_f32_e32 v83, v84, v83
	v_div_scale_f32 v84, vcc, v94, v81, v94
	v_mul_f32_e32 v85, v84, v83
	v_fma_f32 v86, -v82, v85, v84
	v_fmac_f32_e32 v85, v86, v83
	v_fma_f32 v82, -v82, v85, v84
	v_div_fmas_f32 v82, v82, v83, v85
	v_div_fixup_f32 v81, v82, v81, v94
	v_mul_f32_e32 v80, v81, v80
	v_mul_f32_e32 v81, 0xbfb8aa3b, v95
	v_exp_f32_e32 v81, v81
	v_cvt_pk_bf16_f32 v80, v80, s0
	ds_write_b16 v128, v80 offset:15776
	ds_read_u16 v80, v128 offset:16048
	v_add_f32_e32 v81, 1.0, v81
	v_div_scale_f32 v82, s[6:7], v81, v81, v95
	v_rcp_f32_e32 v83, v82
	s_waitcnt lgkmcnt(0)
	v_lshlrev_b32_e32 v80, 16, v80
	v_fma_f32 v84, -v82, v83, 1.0
	v_fmac_f32_e32 v83, v84, v83
	v_div_scale_f32 v84, vcc, v95, v81, v95
	v_mul_f32_e32 v85, v84, v83
	v_fma_f32 v86, -v82, v85, v84
	v_fmac_f32_e32 v85, v86, v83
	v_fma_f32 v82, -v82, v85, v84
	v_div_fmas_f32 v82, v82, v83, v85
	v_div_fixup_f32 v81, v82, v81, v95
	v_mul_f32_e32 v80, v81, v80
	v_mul_f32_e32 v81, 0xbfb8aa3b, v64
	v_exp_f32_e32 v81, v81
	v_cvt_pk_bf16_f32 v80, v80, s0
	ds_write_b16 v128, v80 offset:16048
	ds_read_u16 v80, v128 offset:8768
	v_add_f32_e32 v81, 1.0, v81
	v_div_scale_f32 v82, s[6:7], v81, v81, v64
	v_rcp_f32_e32 v83, v82
	s_waitcnt lgkmcnt(0)
	v_lshlrev_b32_e32 v80, 16, v80
	v_fma_f32 v84, -v82, v83, 1.0
	v_fmac_f32_e32 v83, v84, v83
	v_div_scale_f32 v84, vcc, v64, v81, v64
	v_mul_f32_e32 v85, v84, v83
	v_fma_f32 v86, -v82, v85, v84
	v_fmac_f32_e32 v85, v86, v83
	v_fma_f32 v82, -v82, v85, v84
	v_div_fmas_f32 v82, v82, v83, v85
	v_div_fixup_f32 v64, v82, v81, v64
	v_mul_f32_e32 v64, v64, v80
	v_mul_f32_e32 v80, 0xbfb8aa3b, v65
	v_exp_f32_e32 v80, v80
	v_cvt_pk_bf16_f32 v64, v64, s0
	ds_write_b16 v128, v64 offset:8768
	ds_read_u16 v64, v128 offset:9040
	v_add_f32_e32 v80, 1.0, v80
	v_div_scale_f32 v81, s[6:7], v80, v80, v65
	v_rcp_f32_e32 v82, v81
	s_waitcnt lgkmcnt(0)
	v_lshlrev_b32_e32 v64, 16, v64
	v_fma_f32 v83, -v81, v82, 1.0
	v_fmac_f32_e32 v82, v83, v82
	v_div_scale_f32 v83, vcc, v65, v80, v65
	v_mul_f32_e32 v84, v83, v82
	v_fma_f32 v85, -v81, v84, v83
	v_fmac_f32_e32 v84, v85, v82
	v_fma_f32 v81, -v81, v84, v83
	v_div_fmas_f32 v81, v81, v82, v84
	v_div_fixup_f32 v65, v81, v80, v65
	v_mul_f32_e32 v64, v65, v64
	v_mul_f32_e32 v65, 0xbfb8aa3b, v66
	v_exp_f32_e32 v65, v65
	v_cvt_pk_bf16_f32 v64, v64, s0
	ds_write_b16 v128, v64 offset:9040
	ds_read_u16 v64, v128 offset:9312
	v_add_f32_e32 v65, 1.0, v65
	v_div_scale_f32 v80, s[6:7], v65, v65, v66
	v_rcp_f32_e32 v81, v80
	s_waitcnt lgkmcnt(0)
	v_lshlrev_b32_e32 v64, 16, v64
	v_fma_f32 v82, -v80, v81, 1.0
	v_fmac_f32_e32 v81, v82, v81
	v_div_scale_f32 v82, vcc, v66, v65, v66
	v_mul_f32_e32 v83, v82, v81
	v_fma_f32 v84, -v80, v83, v82
	v_fmac_f32_e32 v83, v84, v81
	v_fma_f32 v80, -v80, v83, v82
	v_div_fmas_f32 v80, v80, v81, v83
	v_div_fixup_f32 v65, v80, v65, v66
	v_mul_f32_e32 v64, v65, v64
	v_mul_f32_e32 v65, 0xbfb8aa3b, v67
	v_exp_f32_e32 v65, v65
	v_cvt_pk_bf16_f32 v64, v64, s0
	ds_write_b16 v128, v64 offset:9312
	ds_read_u16 v64, v128 offset:9584
	v_add_f32_e32 v65, 1.0, v65
	v_div_scale_f32 v66, s[6:7], v65, v65, v67
	v_rcp_f32_e32 v80, v66
	s_waitcnt lgkmcnt(0)
	v_lshlrev_b32_e32 v64, 16, v64
	v_fma_f32 v81, -v66, v80, 1.0
	v_fmac_f32_e32 v80, v81, v80
	v_div_scale_f32 v81, vcc, v67, v65, v67
	v_mul_f32_e32 v82, v81, v80
	v_fma_f32 v83, -v66, v82, v81
	v_fmac_f32_e32 v82, v83, v80
	v_fma_f32 v66, -v66, v82, v81
	v_div_fmas_f32 v66, v66, v80, v82
	v_div_fixup_f32 v65, v66, v65, v67
	v_mul_f32_e32 v64, v65, v64
	v_mul_f32_e32 v65, 0xbfb8aa3b, v68
	v_exp_f32_e32 v65, v65
	v_cvt_pk_bf16_f32 v64, v64, s0
	ds_write_b16 v128, v64 offset:9584
	ds_read_u16 v64, v128 offset:10944
	v_add_f32_e32 v65, 1.0, v65
	v_div_scale_f32 v66, s[6:7], v65, v65, v68
	v_rcp_f32_e32 v67, v66
	s_waitcnt lgkmcnt(0)
	v_lshlrev_b32_e32 v64, 16, v64
	v_fma_f32 v80, -v66, v67, 1.0
	v_fmac_f32_e32 v67, v80, v67
	v_div_scale_f32 v80, vcc, v68, v65, v68
	v_mul_f32_e32 v81, v80, v67
	v_fma_f32 v82, -v66, v81, v80
	v_fmac_f32_e32 v81, v82, v67
	v_fma_f32 v66, -v66, v81, v80
	v_div_fmas_f32 v66, v66, v67, v81
	v_div_fixup_f32 v65, v66, v65, v68
	v_mul_f32_e32 v64, v65, v64
	v_mul_f32_e32 v65, 0xbfb8aa3b, v69
	v_exp_f32_e32 v65, v65
	v_cvt_pk_bf16_f32 v64, v64, s0
	ds_write_b16 v128, v64 offset:10944
	ds_read_u16 v64, v128 offset:11216
	v_add_f32_e32 v65, 1.0, v65
	v_div_scale_f32 v66, s[6:7], v65, v65, v69
	v_rcp_f32_e32 v67, v66
	s_waitcnt lgkmcnt(0)
	v_lshlrev_b32_e32 v64, 16, v64
	v_fma_f32 v68, -v66, v67, 1.0
	v_fmac_f32_e32 v67, v68, v67
	v_div_scale_f32 v68, vcc, v69, v65, v69
	v_mul_f32_e32 v80, v68, v67
	v_fma_f32 v81, -v66, v80, v68
	v_fmac_f32_e32 v80, v81, v67
	v_fma_f32 v66, -v66, v80, v68
	v_div_fmas_f32 v66, v66, v67, v80
	v_div_fixup_f32 v65, v66, v65, v69
	v_mul_f32_e32 v64, v65, v64
	v_mul_f32_e32 v65, 0xbfb8aa3b, v70
	v_exp_f32_e32 v65, v65
	v_cvt_pk_bf16_f32 v64, v64, s0
	ds_write_b16 v128, v64 offset:11216
	ds_read_u16 v64, v128 offset:11488
	v_add_f32_e32 v65, 1.0, v65
	v_div_scale_f32 v66, s[6:7], v65, v65, v70
	v_rcp_f32_e32 v67, v66
	s_waitcnt lgkmcnt(0)
	v_lshlrev_b32_e32 v64, 16, v64
	v_fma_f32 v68, -v66, v67, 1.0
	v_fmac_f32_e32 v67, v68, v67
	v_div_scale_f32 v68, vcc, v70, v65, v70
	v_mul_f32_e32 v69, v68, v67
	v_fma_f32 v80, -v66, v69, v68
	v_fmac_f32_e32 v69, v80, v67
	v_fma_f32 v66, -v66, v69, v68
	v_div_fmas_f32 v66, v66, v67, v69
	v_div_fixup_f32 v65, v66, v65, v70
	v_mul_f32_e32 v64, v65, v64
	v_mul_f32_e32 v65, 0xbfb8aa3b, v71
	v_exp_f32_e32 v65, v65
	v_cvt_pk_bf16_f32 v64, v64, s0
	ds_write_b16 v128, v64 offset:11488
	ds_read_u16 v64, v128 offset:11760
	v_add_f32_e32 v65, 1.0, v65
	v_div_scale_f32 v66, s[6:7], v65, v65, v71
	v_rcp_f32_e32 v67, v66
	s_waitcnt lgkmcnt(0)
; DEV u16 f2bf(float f) { return (u16)(pk2bf(f, 0.f) & 0xffffu); }
; DEV float bf2f(u16 h) { return __uint_as_float(((unsigned)h) << 16); }
; DEV float siluf_(float x) { return x / (1.0f + __expf(-x)); }
; template <int MI>
; DEV void p4_tile(const Params& p, int l, int m0, int nt, unsigned char* smem) {
;     ...
;     acc_foreach_t<MI>([&](int mi, int ni, int r, int row, int col) __attribute__((always_inline)) {
;       sC[row * LDC + col] = f2bf(bf2f(sC[row * LDC + col]) * siluf_(acc[mi][ni][r]));
;     });
	v_lshlrev_b32_e32 v64, 16, v64
	v_fma_f32 v68, -v66, v67, 1.0
	v_fmac_f32_e32 v67, v68, v67
	v_div_scale_f32 v68, vcc, v71, v65, v71
	v_mul_f32_e32 v69, v68, v67
	v_fma_f32 v70, -v66, v69, v68
	v_fmac_f32_e32 v69, v70, v67
	v_fma_f32 v66, -v66, v69, v68
	v_div_fmas_f32 v66, v66, v67, v69
	v_div_fixup_f32 v65, v66, v65, v71
	v_mul_f32_e32 v64, v65, v64
	v_mul_f32_e32 v65, 0xbfb8aa3b, v72
	v_exp_f32_e32 v65, v65
	v_cvt_pk_bf16_f32 v64, v64, s0
	ds_write_b16 v128, v64 offset:11760
	ds_read_u16 v64, v128 offset:13120
	v_add_f32_e32 v65, 1.0, v65
	v_div_scale_f32 v66, s[6:7], v65, v65, v72
	v_rcp_f32_e32 v67, v66
	s_waitcnt lgkmcnt(0)
	v_lshlrev_b32_e32 v64, 16, v64
	v_fma_f32 v68, -v66, v67, 1.0
	v_fmac_f32_e32 v67, v68, v67
	v_div_scale_f32 v68, vcc, v72, v65, v72
	v_mul_f32_e32 v69, v68, v67
	v_fma_f32 v70, -v66, v69, v68
	v_fmac_f32_e32 v69, v70, v67
	v_fma_f32 v66, -v66, v69, v68
	v_div_fmas_f32 v66, v66, v67, v69
	v_div_fixup_f32 v65, v66, v65, v72
	v_mul_f32_e32 v64, v65, v64
	v_mul_f32_e32 v65, 0xbfb8aa3b, v73
	v_exp_f32_e32 v65, v65
	v_cvt_pk_bf16_f32 v64, v64, s0
	ds_write_b16 v128, v64 offset:13120
	ds_read_u16 v64, v128 offset:13392
	v_add_f32_e32 v65, 1.0, v65
	v_div_scale_f32 v66, s[6:7], v65, v65, v73
	v_rcp_f32_e32 v67, v66
	s_waitcnt lgkmcnt(0)
	v_lshlrev_b32_e32 v64, 16, v64
	v_fma_f32 v68, -v66, v67, 1.0
	v_fmac_f32_e32 v67, v68, v67
	v_div_scale_f32 v68, vcc, v73, v65, v73
	v_mul_f32_e32 v69, v68, v67
	v_fma_f32 v70, -v66, v69, v68
	v_fmac_f32_e32 v69, v70, v67
	v_fma_f32 v66, -v66, v69, v68
	v_div_fmas_f32 v66, v66, v67, v69
	v_div_fixup_f32 v65, v66, v65, v73
	v_mul_f32_e32 v64, v65, v64
	v_mul_f32_e32 v65, 0xbfb8aa3b, v74
	v_exp_f32_e32 v65, v65
	v_cvt_pk_bf16_f32 v64, v64, s0
	ds_write_b16 v128, v64 offset:13392
	ds_read_u16 v64, v128 offset:13664
	v_add_f32_e32 v65, 1.0, v65
	v_div_scale_f32 v66, s[6:7], v65, v65, v74
	v_rcp_f32_e32 v67, v66
	s_waitcnt lgkmcnt(0)
	v_lshlrev_b32_e32 v64, 16, v64
	v_fma_f32 v68, -v66, v67, 1.0
	v_fmac_f32_e32 v67, v68, v67
	v_div_scale_f32 v68, vcc, v74, v65, v74
	v_mul_f32_e32 v69, v68, v67
	v_fma_f32 v70, -v66, v69, v68
	v_fmac_f32_e32 v69, v70, v67
	v_fma_f32 v66, -v66, v69, v68
	v_div_fmas_f32 v66, v66, v67, v69
	v_div_fixup_f32 v65, v66, v65, v74
	v_mul_f32_e32 v64, v65, v64
	v_mul_f32_e32 v65, 0xbfb8aa3b, v75
	v_exp_f32_e32 v65, v65
	v_cvt_pk_bf16_f32 v64, v64, s0
	ds_write_b16 v128, v64 offset:13664
	ds_read_u16 v64, v128 offset:13936
	v_add_f32_e32 v65, 1.0, v65
	v_div_scale_f32 v66, s[6:7], v65, v65, v75
	v_rcp_f32_e32 v67, v66
	s_waitcnt lgkmcnt(0)
	v_lshlrev_b32_e32 v64, 16, v64
	v_fma_f32 v68, -v66, v67, 1.0
	v_fmac_f32_e32 v67, v68, v67
	v_div_scale_f32 v68, vcc, v75, v65, v75
	v_mul_f32_e32 v69, v68, v67
	v_fma_f32 v70, -v66, v69, v68
	v_fmac_f32_e32 v69, v70, v67
	v_fma_f32 v66, -v66, v69, v68
	v_div_fmas_f32 v66, v66, v67, v69
	v_div_fixup_f32 v65, v66, v65, v75
	v_mul_f32_e32 v64, v65, v64
	v_mul_f32_e32 v65, 0xbfb8aa3b, v76
	v_exp_f32_e32 v65, v65
	v_cvt_pk_bf16_f32 v64, v64, s0
	ds_write_b16 v128, v64 offset:13936
	ds_read_u16 v64, v128 offset:15296
	v_add_f32_e32 v65, 1.0, v65
	v_div_scale_f32 v66, s[6:7], v65, v65, v76
	v_rcp_f32_e32 v67, v66
	s_waitcnt lgkmcnt(0)
	v_lshlrev_b32_e32 v64, 16, v64
	v_fma_f32 v68, -v66, v67, 1.0
	v_fmac_f32_e32 v67, v68, v67
	v_div_scale_f32 v68, vcc, v76, v65, v76
	v_mul_f32_e32 v69, v68, v67
	v_fma_f32 v70, -v66, v69, v68
	v_fmac_f32_e32 v69, v70, v67
	v_fma_f32 v66, -v66, v69, v68
	v_div_fmas_f32 v66, v66, v67, v69
	v_div_fixup_f32 v65, v66, v65, v76
	v_mul_f32_e32 v64, v65, v64
	v_mul_f32_e32 v65, 0xbfb8aa3b, v77
	v_exp_f32_e32 v65, v65
	v_cvt_pk_bf16_f32 v64, v64, s0
	ds_write_b16 v128, v64 offset:15296
	ds_read_u16 v64, v128 offset:15568
	v_add_f32_e32 v65, 1.0, v65
	v_div_scale_f32 v66, s[6:7], v65, v65, v77
	v_rcp_f32_e32 v67, v66
	s_waitcnt lgkmcnt(0)
	v_lshlrev_b32_e32 v64, 16, v64
	v_fma_f32 v68, -v66, v67, 1.0
	v_fmac_f32_e32 v67, v68, v67
	v_div_scale_f32 v68, vcc, v77, v65, v77
	v_mul_f32_e32 v69, v68, v67
	v_fma_f32 v70, -v66, v69, v68
	v_fmac_f32_e32 v69, v70, v67
	v_fma_f32 v66, -v66, v69, v68
	v_div_fmas_f32 v66, v66, v67, v69
	v_div_fixup_f32 v65, v66, v65, v77
	v_mul_f32_e32 v64, v65, v64
	v_mul_f32_e32 v65, 0xbfb8aa3b, v78
	v_exp_f32_e32 v65, v65
	v_cvt_pk_bf16_f32 v64, v64, s0
	ds_write_b16 v128, v64 offset:15568
	ds_read_u16 v64, v128 offset:15840
	v_add_f32_e32 v65, 1.0, v65
	v_div_scale_f32 v66, s[6:7], v65, v65, v78
	v_rcp_f32_e32 v67, v66
	s_waitcnt lgkmcnt(0)
	v_lshlrev_b32_e32 v64, 16, v64
	v_fma_f32 v68, -v66, v67, 1.0
	v_fmac_f32_e32 v67, v68, v67
	v_div_scale_f32 v68, vcc, v78, v65, v78
	v_mul_f32_e32 v69, v68, v67
	v_fma_f32 v70, -v66, v69, v68
	v_fmac_f32_e32 v69, v70, v67
	v_fma_f32 v66, -v66, v69, v68
	v_div_fmas_f32 v66, v66, v67, v69
	v_div_fixup_f32 v65, v66, v65, v78
	v_mul_f32_e32 v64, v65, v64
	v_mul_f32_e32 v65, 0xbfb8aa3b, v79
	v_exp_f32_e32 v65, v65
	v_cvt_pk_bf16_f32 v64, v64, s0
	ds_write_b16 v128, v64 offset:15840
	ds_read_u16 v64, v128 offset:16112
	v_add_f32_e32 v65, 1.0, v65
	v_div_scale_f32 v66, s[6:7], v65, v65, v79
	v_rcp_f32_e32 v67, v66
	s_waitcnt lgkmcnt(0)
	v_lshlrev_b32_e32 v64, 16, v64
	v_fma_f32 v68, -v66, v67, 1.0
	v_fmac_f32_e32 v67, v68, v67
	v_div_scale_f32 v68, vcc, v79, v65, v79
	v_mul_f32_e32 v69, v68, v67
	v_fma_f32 v70, -v66, v69, v68
	v_fmac_f32_e32 v69, v70, v67
	v_fma_f32 v66, -v66, v69, v68
	v_div_fmas_f32 v66, v66, v67, v69
	v_div_fixup_f32 v65, v66, v65, v79
	v_mul_f32_e32 v64, v65, v64
	v_mul_f32_e32 v65, 0xbfb8aa3b, v48
	v_exp_f32_e32 v65, v65
	v_cvt_pk_bf16_f32 v64, v64, s0
	ds_write_b16 v128, v64 offset:16112
	ds_read_u16 v64, v128 offset:17408
	v_add_f32_e32 v65, 1.0, v65
	v_div_scale_f32 v66, s[6:7], v65, v65, v48
	v_rcp_f32_e32 v67, v66
	s_waitcnt lgkmcnt(0)
; DEV u16 f2bf(float f) { return (u16)(pk2bf(f, 0.f) & 0xffffu); }
; DEV float bf2f(u16 h) { return __uint_as_float(((unsigned)h) << 16); }
; DEV float siluf_(float x) { return x / (1.0f + __expf(-x)); }
; template <int MI>
; DEV void p4_tile(const Params& p, int l, int m0, int nt, unsigned char* smem) {
;     ...
;     acc_foreach_t<MI>([&](int mi, int ni, int r, int row, int col) __attribute__((always_inline)) {
;       sC[row * LDC + col] = f2bf(bf2f(sC[row * LDC + col]) * siluf_(acc[mi][ni][r]));
;     });
	v_lshlrev_b32_e32 v64, 16, v64
	v_fma_f32 v68, -v66, v67, 1.0
	v_fmac_f32_e32 v67, v68, v67
	v_div_scale_f32 v68, vcc, v48, v65, v48
	v_mul_f32_e32 v69, v68, v67
	v_fma_f32 v70, -v66, v69, v68
	v_fmac_f32_e32 v69, v70, v67
	v_fma_f32 v66, -v66, v69, v68
	v_div_fmas_f32 v66, v66, v67, v69
	v_div_fixup_f32 v48, v66, v65, v48
	v_mul_f32_e32 v48, v48, v64
	v_mul_f32_e32 v64, 0xbfb8aa3b, v49
	v_exp_f32_e32 v64, v64
	v_cvt_pk_bf16_f32 v48, v48, s0
	ds_write_b16 v128, v48 offset:17408
	ds_read_u16 v48, v128 offset:17680
	v_add_f32_e32 v64, 1.0, v64
	v_div_scale_f32 v65, s[6:7], v64, v64, v49
	v_rcp_f32_e32 v66, v65
	s_waitcnt lgkmcnt(0)
	v_lshlrev_b32_e32 v48, 16, v48
	v_fma_f32 v67, -v65, v66, 1.0
	v_fmac_f32_e32 v66, v67, v66
	v_div_scale_f32 v67, vcc, v49, v64, v49
	v_mul_f32_e32 v68, v67, v66
	v_fma_f32 v69, -v65, v68, v67
	v_fmac_f32_e32 v68, v69, v66
	v_fma_f32 v65, -v65, v68, v67
	v_div_fmas_f32 v65, v65, v66, v68
	v_div_fixup_f32 v49, v65, v64, v49
	v_mul_f32_e32 v48, v49, v48
	v_mul_f32_e32 v49, 0xbfb8aa3b, v50
	v_exp_f32_e32 v49, v49
	v_cvt_pk_bf16_f32 v48, v48, s0
	ds_write_b16 v128, v48 offset:17680
	ds_read_u16 v48, v128 offset:17952
	v_add_f32_e32 v49, 1.0, v49
	v_div_scale_f32 v64, s[6:7], v49, v49, v50
	v_rcp_f32_e32 v65, v64
	s_waitcnt lgkmcnt(0)
	v_lshlrev_b32_e32 v48, 16, v48
	v_fma_f32 v66, -v64, v65, 1.0
	v_fmac_f32_e32 v65, v66, v65
	v_div_scale_f32 v66, vcc, v50, v49, v50
	v_mul_f32_e32 v67, v66, v65
	v_fma_f32 v68, -v64, v67, v66
	v_fmac_f32_e32 v67, v68, v65
	v_fma_f32 v64, -v64, v67, v66
	v_div_fmas_f32 v64, v64, v65, v67
	v_div_fixup_f32 v49, v64, v49, v50
	v_mul_f32_e32 v48, v49, v48
	v_mul_f32_e32 v49, 0xbfb8aa3b, v51
	v_exp_f32_e32 v49, v49
	v_cvt_pk_bf16_f32 v48, v48, s0
	ds_write_b16 v128, v48 offset:17952
	ds_read_u16 v48, v128 offset:18224
	v_add_f32_e32 v49, 1.0, v49
	v_div_scale_f32 v50, s[6:7], v49, v49, v51
	v_rcp_f32_e32 v64, v50
	s_waitcnt lgkmcnt(0)
	v_lshlrev_b32_e32 v48, 16, v48
	v_fma_f32 v65, -v50, v64, 1.0
	v_fmac_f32_e32 v64, v65, v64
	v_div_scale_f32 v65, vcc, v51, v49, v51
	v_mul_f32_e32 v66, v65, v64
	v_fma_f32 v67, -v50, v66, v65
	v_fmac_f32_e32 v66, v67, v64
	v_fma_f32 v50, -v50, v66, v65
	v_div_fmas_f32 v50, v50, v64, v66
	v_div_fixup_f32 v49, v50, v49, v51
	v_mul_f32_e32 v48, v49, v48
	v_mul_f32_e32 v49, 0xbfb8aa3b, v52
	v_exp_f32_e32 v49, v49
	v_cvt_pk_bf16_f32 v48, v48, s0
	ds_write_b16 v128, v48 offset:18224
	ds_read_u16 v48, v128 offset:19584
	v_add_f32_e32 v49, 1.0, v49
	v_div_scale_f32 v50, s[6:7], v49, v49, v52
	v_rcp_f32_e32 v51, v50
	s_waitcnt lgkmcnt(0)
	v_lshlrev_b32_e32 v48, 16, v48
	v_fma_f32 v64, -v50, v51, 1.0
	v_fmac_f32_e32 v51, v64, v51
	v_div_scale_f32 v64, vcc, v52, v49, v52
	v_mul_f32_e32 v65, v64, v51
	v_fma_f32 v66, -v50, v65, v64
	v_fmac_f32_e32 v65, v66, v51
	v_fma_f32 v50, -v50, v65, v64
	v_div_fmas_f32 v50, v50, v51, v65
	v_div_fixup_f32 v49, v50, v49, v52
	v_mul_f32_e32 v48, v49, v48
	v_mul_f32_e32 v49, 0xbfb8aa3b, v53
	v_exp_f32_e32 v49, v49
	v_cvt_pk_bf16_f32 v48, v48, s0
	ds_write_b16 v128, v48 offset:19584
	ds_read_u16 v48, v128 offset:19856
	v_add_f32_e32 v49, 1.0, v49
	v_div_scale_f32 v50, s[6:7], v49, v49, v53
	v_rcp_f32_e32 v51, v50
	s_waitcnt lgkmcnt(0)
	v_lshlrev_b32_e32 v48, 16, v48
	v_fma_f32 v52, -v50, v51, 1.0
	v_fmac_f32_e32 v51, v52, v51
	v_div_scale_f32 v52, vcc, v53, v49, v53
	v_mul_f32_e32 v64, v52, v51
	v_fma_f32 v65, -v50, v64, v52
	v_fmac_f32_e32 v64, v65, v51
	v_fma_f32 v50, -v50, v64, v52
	v_div_fmas_f32 v50, v50, v51, v64
	v_div_fixup_f32 v49, v50, v49, v53
	v_mul_f32_e32 v48, v49, v48
	v_mul_f32_e32 v49, 0xbfb8aa3b, v54
	v_exp_f32_e32 v49, v49
	v_cvt_pk_bf16_f32 v48, v48, s0
	ds_write_b16 v128, v48 offset:19856
	ds_read_u16 v48, v128 offset:20128
	v_add_f32_e32 v49, 1.0, v49
	v_div_scale_f32 v50, s[6:7], v49, v49, v54
	v_rcp_f32_e32 v51, v50
	s_waitcnt lgkmcnt(0)
	v_lshlrev_b32_e32 v48, 16, v48
	v_fma_f32 v52, -v50, v51, 1.0
	v_fmac_f32_e32 v51, v52, v51
	v_div_scale_f32 v52, vcc, v54, v49, v54
	v_mul_f32_e32 v53, v52, v51
	v_fma_f32 v64, -v50, v53, v52
	v_fmac_f32_e32 v53, v64, v51
	v_fma_f32 v50, -v50, v53, v52
	v_div_fmas_f32 v50, v50, v51, v53
	v_div_fixup_f32 v49, v50, v49, v54
	v_mul_f32_e32 v48, v49, v48
	v_mul_f32_e32 v49, 0xbfb8aa3b, v55
	v_exp_f32_e32 v49, v49
	v_cvt_pk_bf16_f32 v48, v48, s0
	ds_write_b16 v128, v48 offset:20128
	ds_read_u16 v48, v128 offset:20400
	v_add_f32_e32 v49, 1.0, v49
	v_div_scale_f32 v50, s[6:7], v49, v49, v55
	v_rcp_f32_e32 v51, v50
	s_waitcnt lgkmcnt(0)
	v_lshlrev_b32_e32 v48, 16, v48
	v_fma_f32 v52, -v50, v51, 1.0
	v_fmac_f32_e32 v51, v52, v51
	v_div_scale_f32 v52, vcc, v55, v49, v55
	v_mul_f32_e32 v53, v52, v51
	v_fma_f32 v54, -v50, v53, v52
	v_fmac_f32_e32 v53, v54, v51
	v_fma_f32 v50, -v50, v53, v52
	v_div_fmas_f32 v50, v50, v51, v53
	v_div_fixup_f32 v49, v50, v49, v55
	v_mul_f32_e32 v48, v49, v48
	v_mul_f32_e32 v49, 0xbfb8aa3b, v56
	v_exp_f32_e32 v49, v49
	v_cvt_pk_bf16_f32 v48, v48, s0
	ds_write_b16 v128, v48 offset:20400
	ds_read_u16 v48, v128 offset:21760
	v_add_f32_e32 v49, 1.0, v49
	v_div_scale_f32 v50, s[6:7], v49, v49, v56
	v_rcp_f32_e32 v51, v50
	s_waitcnt lgkmcnt(0)
	v_lshlrev_b32_e32 v48, 16, v48
	v_fma_f32 v52, -v50, v51, 1.0
	v_fmac_f32_e32 v51, v52, v51
	v_div_scale_f32 v52, vcc, v56, v49, v56
	v_mul_f32_e32 v53, v52, v51
	v_fma_f32 v54, -v50, v53, v52
	v_fmac_f32_e32 v53, v54, v51
	v_fma_f32 v50, -v50, v53, v52
	v_div_fmas_f32 v50, v50, v51, v53
	v_div_fixup_f32 v49, v50, v49, v56
	v_mul_f32_e32 v48, v49, v48
	v_mul_f32_e32 v49, 0xbfb8aa3b, v57
	v_exp_f32_e32 v49, v49
	v_cvt_pk_bf16_f32 v48, v48, s0
	ds_write_b16 v128, v48 offset:21760
	ds_read_u16 v48, v128 offset:22032
	v_add_f32_e32 v49, 1.0, v49
	v_div_scale_f32 v50, s[6:7], v49, v49, v57
	v_rcp_f32_e32 v51, v50
	s_waitcnt lgkmcnt(0)
; DEV u16 f2bf(float f) { return (u16)(pk2bf(f, 0.f) & 0xffffu); }
; DEV float bf2f(u16 h) { return __uint_as_float(((unsigned)h) << 16); }
; DEV float siluf_(float x) { return x / (1.0f + __expf(-x)); }
; template <int MI>
; DEV void p4_tile(const Params& p, int l, int m0, int nt, unsigned char* smem) {
;     ...
;     acc_foreach_t<MI>([&](int mi, int ni, int r, int row, int col) __attribute__((always_inline)) {
;       sC[row * LDC + col] = f2bf(bf2f(sC[row * LDC + col]) * siluf_(acc[mi][ni][r]));
;     });
	v_lshlrev_b32_e32 v48, 16, v48
	v_fma_f32 v52, -v50, v51, 1.0
	v_fmac_f32_e32 v51, v52, v51
	v_div_scale_f32 v52, vcc, v57, v49, v57
	v_mul_f32_e32 v53, v52, v51
	v_fma_f32 v54, -v50, v53, v52
	v_fmac_f32_e32 v53, v54, v51
	v_fma_f32 v50, -v50, v53, v52
	v_div_fmas_f32 v50, v50, v51, v53
	v_div_fixup_f32 v49, v50, v49, v57
	v_mul_f32_e32 v48, v49, v48
	v_mul_f32_e32 v49, 0xbfb8aa3b, v58
	v_exp_f32_e32 v49, v49
	v_cvt_pk_bf16_f32 v48, v48, s0
	ds_write_b16 v128, v48 offset:22032
	ds_read_u16 v48, v128 offset:22304
	v_add_f32_e32 v49, 1.0, v49
	v_div_scale_f32 v50, s[6:7], v49, v49, v58
	v_rcp_f32_e32 v51, v50
	s_waitcnt lgkmcnt(0)
	v_lshlrev_b32_e32 v48, 16, v48
	v_fma_f32 v52, -v50, v51, 1.0
	v_fmac_f32_e32 v51, v52, v51
	v_div_scale_f32 v52, vcc, v58, v49, v58
	v_mul_f32_e32 v53, v52, v51
	v_fma_f32 v54, -v50, v53, v52
	v_fmac_f32_e32 v53, v54, v51
	v_fma_f32 v50, -v50, v53, v52
	v_div_fmas_f32 v50, v50, v51, v53
	v_div_fixup_f32 v49, v50, v49, v58
	v_mul_f32_e32 v48, v49, v48
	v_mul_f32_e32 v49, 0xbfb8aa3b, v59
	v_exp_f32_e32 v49, v49
	v_cvt_pk_bf16_f32 v48, v48, s0
	ds_write_b16 v128, v48 offset:22304
	ds_read_u16 v48, v128 offset:22576
	v_add_f32_e32 v49, 1.0, v49
	v_div_scale_f32 v50, s[6:7], v49, v49, v59
	v_rcp_f32_e32 v51, v50
	s_waitcnt lgkmcnt(0)
	v_lshlrev_b32_e32 v48, 16, v48
	v_fma_f32 v52, -v50, v51, 1.0
	v_fmac_f32_e32 v51, v52, v51
	v_div_scale_f32 v52, vcc, v59, v49, v59
	v_mul_f32_e32 v53, v52, v51
	v_fma_f32 v54, -v50, v53, v52
	v_fmac_f32_e32 v53, v54, v51
	v_fma_f32 v50, -v50, v53, v52
	v_div_fmas_f32 v50, v50, v51, v53
	v_div_fixup_f32 v49, v50, v49, v59
	v_mul_f32_e32 v48, v49, v48
	v_mul_f32_e32 v49, 0xbfb8aa3b, v60
	v_exp_f32_e32 v49, v49
	v_cvt_pk_bf16_f32 v48, v48, s0
	ds_write_b16 v128, v48 offset:22576
	ds_read_u16 v48, v128 offset:23936
	v_add_f32_e32 v49, 1.0, v49
	v_div_scale_f32 v50, s[6:7], v49, v49, v60
	v_rcp_f32_e32 v51, v50
	s_waitcnt lgkmcnt(0)
	v_lshlrev_b32_e32 v48, 16, v48
	v_fma_f32 v52, -v50, v51, 1.0
	v_fmac_f32_e32 v51, v52, v51
	v_div_scale_f32 v52, vcc, v60, v49, v60
	v_mul_f32_e32 v53, v52, v51
	v_fma_f32 v54, -v50, v53, v52
	v_fmac_f32_e32 v53, v54, v51
	v_fma_f32 v50, -v50, v53, v52
	v_div_fmas_f32 v50, v50, v51, v53
	v_div_fixup_f32 v49, v50, v49, v60
	v_mul_f32_e32 v48, v49, v48
	v_mul_f32_e32 v49, 0xbfb8aa3b, v61
	v_exp_f32_e32 v49, v49
	v_cvt_pk_bf16_f32 v48, v48, s0
	ds_write_b16 v128, v48 offset:23936
	ds_read_u16 v48, v128 offset:24208
	v_add_f32_e32 v49, 1.0, v49
	v_div_scale_f32 v50, s[6:7], v49, v49, v61
	v_rcp_f32_e32 v51, v50
	s_waitcnt lgkmcnt(0)
	v_lshlrev_b32_e32 v48, 16, v48
	v_fma_f32 v52, -v50, v51, 1.0
	v_fmac_f32_e32 v51, v52, v51
	v_div_scale_f32 v52, vcc, v61, v49, v61
	v_mul_f32_e32 v53, v52, v51
	v_fma_f32 v54, -v50, v53, v52
	v_fmac_f32_e32 v53, v54, v51
	v_fma_f32 v50, -v50, v53, v52
	v_div_fmas_f32 v50, v50, v51, v53
	v_div_fixup_f32 v49, v50, v49, v61
	v_mul_f32_e32 v48, v49, v48
	v_mul_f32_e32 v49, 0xbfb8aa3b, v62
	v_exp_f32_e32 v49, v49
	v_cvt_pk_bf16_f32 v48, v48, s0
	ds_write_b16 v128, v48 offset:24208
	ds_read_u16 v48, v128 offset:24480
	v_add_f32_e32 v49, 1.0, v49
	v_div_scale_f32 v50, s[6:7], v49, v49, v62
	v_rcp_f32_e32 v51, v50
	s_waitcnt lgkmcnt(0)
	v_lshlrev_b32_e32 v48, 16, v48
	v_fma_f32 v52, -v50, v51, 1.0
	v_fmac_f32_e32 v51, v52, v51
	v_div_scale_f32 v52, vcc, v62, v49, v62
	v_mul_f32_e32 v53, v52, v51
	v_fma_f32 v54, -v50, v53, v52
	v_fmac_f32_e32 v53, v54, v51
	v_fma_f32 v50, -v50, v53, v52
	v_div_fmas_f32 v50, v50, v51, v53
	v_div_fixup_f32 v49, v50, v49, v62
	v_mul_f32_e32 v48, v49, v48
	v_mul_f32_e32 v49, 0xbfb8aa3b, v63
	v_exp_f32_e32 v49, v49
	v_cvt_pk_bf16_f32 v48, v48, s0
	ds_write_b16 v128, v48 offset:24480
	ds_read_u16 v48, v128 offset:24752
	v_add_f32_e32 v49, 1.0, v49
	v_div_scale_f32 v50, s[6:7], v49, v49, v63
	v_rcp_f32_e32 v51, v50
	s_waitcnt lgkmcnt(0)
	v_lshlrev_b32_e32 v48, 16, v48
	v_fma_f32 v52, -v50, v51, 1.0
	v_fmac_f32_e32 v51, v52, v51
	v_div_scale_f32 v52, vcc, v63, v49, v63
	v_mul_f32_e32 v53, v52, v51
	v_fma_f32 v54, -v50, v53, v52
	v_fmac_f32_e32 v53, v54, v51
	v_fma_f32 v50, -v50, v53, v52
	v_div_fmas_f32 v50, v50, v51, v53
	v_div_fixup_f32 v49, v50, v49, v63
	v_mul_f32_e32 v48, v49, v48
	v_mul_f32_e32 v49, 0xbfb8aa3b, v32
	v_exp_f32_e32 v49, v49
	v_cvt_pk_bf16_f32 v48, v48, s0
	ds_write_b16 v128, v48 offset:24752
	ds_read_u16 v48, v128 offset:17472
	v_add_f32_e32 v49, 1.0, v49
	v_div_scale_f32 v50, s[6:7], v49, v49, v32
	v_rcp_f32_e32 v51, v50
	s_waitcnt lgkmcnt(0)
	v_lshlrev_b32_e32 v48, 16, v48
	v_fma_f32 v52, -v50, v51, 1.0
	v_fmac_f32_e32 v51, v52, v51
	v_div_scale_f32 v52, vcc, v32, v49, v32
	v_mul_f32_e32 v53, v52, v51
	v_fma_f32 v54, -v50, v53, v52
	v_fmac_f32_e32 v53, v54, v51
	v_fma_f32 v50, -v50, v53, v52
	v_div_fmas_f32 v50, v50, v51, v53
	v_div_fixup_f32 v32, v50, v49, v32
	v_mul_f32_e32 v32, v32, v48
	v_mul_f32_e32 v48, 0xbfb8aa3b, v33
	v_exp_f32_e32 v48, v48
	v_cvt_pk_bf16_f32 v32, v32, s0
	ds_write_b16 v128, v32 offset:17472
	ds_read_u16 v32, v128 offset:17744
	v_add_f32_e32 v48, 1.0, v48
	v_div_scale_f32 v49, s[6:7], v48, v48, v33
	v_rcp_f32_e32 v50, v49
	s_waitcnt lgkmcnt(0)
	v_lshlrev_b32_e32 v32, 16, v32
	v_fma_f32 v51, -v49, v50, 1.0
	v_fmac_f32_e32 v50, v51, v50
	v_div_scale_f32 v51, vcc, v33, v48, v33
	v_mul_f32_e32 v52, v51, v50
	v_fma_f32 v53, -v49, v52, v51
	v_fmac_f32_e32 v52, v53, v50
	v_fma_f32 v49, -v49, v52, v51
	v_div_fmas_f32 v49, v49, v50, v52
	v_div_fixup_f32 v33, v49, v48, v33
	v_mul_f32_e32 v32, v33, v32
	v_mul_f32_e32 v33, 0xbfb8aa3b, v34
	v_exp_f32_e32 v33, v33
	v_cvt_pk_bf16_f32 v32, v32, s0
	ds_write_b16 v128, v32 offset:17744
	ds_read_u16 v32, v128 offset:18016
	v_add_f32_e32 v33, 1.0, v33
	v_div_scale_f32 v48, s[6:7], v33, v33, v34
	v_rcp_f32_e32 v49, v48
	s_waitcnt lgkmcnt(0)
; DEV u16 f2bf(float f) { return (u16)(pk2bf(f, 0.f) & 0xffffu); }
; DEV float bf2f(u16 h) { return __uint_as_float(((unsigned)h) << 16); }
; DEV float siluf_(float x) { return x / (1.0f + __expf(-x)); }
; template <int MI>
; DEV void p4_tile(const Params& p, int l, int m0, int nt, unsigned char* smem) {
;     ...
;     acc_foreach_t<MI>([&](int mi, int ni, int r, int row, int col) __attribute__((always_inline)) {
;       sC[row * LDC + col] = f2bf(bf2f(sC[row * LDC + col]) * siluf_(acc[mi][ni][r]));
;     });
	v_lshlrev_b32_e32 v32, 16, v32
	v_fma_f32 v50, -v48, v49, 1.0
	v_fmac_f32_e32 v49, v50, v49
	v_div_scale_f32 v50, vcc, v34, v33, v34
	v_mul_f32_e32 v51, v50, v49
	v_fma_f32 v52, -v48, v51, v50
	v_fmac_f32_e32 v51, v52, v49
	v_fma_f32 v48, -v48, v51, v50
	v_div_fmas_f32 v48, v48, v49, v51
	v_div_fixup_f32 v33, v48, v33, v34
	v_mul_f32_e32 v32, v33, v32
	v_mul_f32_e32 v33, 0xbfb8aa3b, v35
	v_exp_f32_e32 v33, v33
	v_cvt_pk_bf16_f32 v32, v32, s0
	ds_write_b16 v128, v32 offset:18016
	ds_read_u16 v32, v128 offset:18288
	v_add_f32_e32 v33, 1.0, v33
	v_div_scale_f32 v34, s[6:7], v33, v33, v35
	v_rcp_f32_e32 v48, v34
	s_waitcnt lgkmcnt(0)
	v_lshlrev_b32_e32 v32, 16, v32
	v_fma_f32 v49, -v34, v48, 1.0
	v_fmac_f32_e32 v48, v49, v48
	v_div_scale_f32 v49, vcc, v35, v33, v35
	v_mul_f32_e32 v50, v49, v48
	v_fma_f32 v51, -v34, v50, v49
	v_fmac_f32_e32 v50, v51, v48
	v_fma_f32 v34, -v34, v50, v49
	v_div_fmas_f32 v34, v34, v48, v50
	v_div_fixup_f32 v33, v34, v33, v35
	v_mul_f32_e32 v32, v33, v32
	v_mul_f32_e32 v33, 0xbfb8aa3b, v36
	v_exp_f32_e32 v33, v33
	v_cvt_pk_bf16_f32 v32, v32, s0
	ds_write_b16 v128, v32 offset:18288
	ds_read_u16 v32, v128 offset:19648
	v_add_f32_e32 v33, 1.0, v33
	v_div_scale_f32 v34, s[6:7], v33, v33, v36
	v_rcp_f32_e32 v35, v34
	s_waitcnt lgkmcnt(0)
	v_lshlrev_b32_e32 v32, 16, v32
	v_fma_f32 v48, -v34, v35, 1.0
	v_fmac_f32_e32 v35, v48, v35
	v_div_scale_f32 v48, vcc, v36, v33, v36
	v_mul_f32_e32 v49, v48, v35
	v_fma_f32 v50, -v34, v49, v48
	v_fmac_f32_e32 v49, v50, v35
	v_fma_f32 v34, -v34, v49, v48
	v_div_fmas_f32 v34, v34, v35, v49
	v_div_fixup_f32 v33, v34, v33, v36
	v_mul_f32_e32 v32, v33, v32
	v_mul_f32_e32 v33, 0xbfb8aa3b, v37
	v_exp_f32_e32 v33, v33
	v_cvt_pk_bf16_f32 v32, v32, s0
	ds_write_b16 v128, v32 offset:19648
	ds_read_u16 v32, v128 offset:19920
	v_add_f32_e32 v33, 1.0, v33
	v_div_scale_f32 v34, s[6:7], v33, v33, v37
	v_rcp_f32_e32 v35, v34
	s_waitcnt lgkmcnt(0)
	v_lshlrev_b32_e32 v32, 16, v32
	v_fma_f32 v36, -v34, v35, 1.0
	v_fmac_f32_e32 v35, v36, v35
	v_div_scale_f32 v36, vcc, v37, v33, v37
	v_mul_f32_e32 v48, v36, v35
	v_fma_f32 v49, -v34, v48, v36
	v_fmac_f32_e32 v48, v49, v35
	v_fma_f32 v34, -v34, v48, v36
	v_div_fmas_f32 v34, v34, v35, v48
	v_div_fixup_f32 v33, v34, v33, v37
	v_mul_f32_e32 v32, v33, v32
	v_mul_f32_e32 v33, 0xbfb8aa3b, v38
	v_exp_f32_e32 v33, v33
	v_cvt_pk_bf16_f32 v32, v32, s0
	ds_write_b16 v128, v32 offset:19920
	ds_read_u16 v32, v128 offset:20192
	v_add_f32_e32 v33, 1.0, v33
	v_div_scale_f32 v34, s[6:7], v33, v33, v38
	v_rcp_f32_e32 v35, v34
	s_waitcnt lgkmcnt(0)
	v_lshlrev_b32_e32 v32, 16, v32
	v_fma_f32 v36, -v34, v35, 1.0
	v_fmac_f32_e32 v35, v36, v35
	v_div_scale_f32 v36, vcc, v38, v33, v38
	v_mul_f32_e32 v37, v36, v35
	v_fma_f32 v48, -v34, v37, v36
	v_fmac_f32_e32 v37, v48, v35
	v_fma_f32 v34, -v34, v37, v36
	v_div_fmas_f32 v34, v34, v35, v37
	v_div_fixup_f32 v33, v34, v33, v38
	v_mul_f32_e32 v32, v33, v32
	v_mul_f32_e32 v33, 0xbfb8aa3b, v39
	v_exp_f32_e32 v33, v33
	v_cvt_pk_bf16_f32 v32, v32, s0
	ds_write_b16 v128, v32 offset:20192
	ds_read_u16 v32, v128 offset:20464
	v_add_f32_e32 v33, 1.0, v33
	v_div_scale_f32 v34, s[6:7], v33, v33, v39
	v_rcp_f32_e32 v35, v34
	s_waitcnt lgkmcnt(0)
	v_lshlrev_b32_e32 v32, 16, v32
	v_fma_f32 v36, -v34, v35, 1.0
	v_fmac_f32_e32 v35, v36, v35
	v_div_scale_f32 v36, vcc, v39, v33, v39
	v_mul_f32_e32 v37, v36, v35
	v_fma_f32 v38, -v34, v37, v36
	v_fmac_f32_e32 v37, v38, v35
	v_fma_f32 v34, -v34, v37, v36
	v_div_fmas_f32 v34, v34, v35, v37
	v_div_fixup_f32 v33, v34, v33, v39
	v_mul_f32_e32 v32, v33, v32
	v_mul_f32_e32 v33, 0xbfb8aa3b, v40
	v_exp_f32_e32 v33, v33
	v_cvt_pk_bf16_f32 v32, v32, s0
	ds_write_b16 v128, v32 offset:20464
	ds_read_u16 v32, v128 offset:21824
	v_add_f32_e32 v33, 1.0, v33
	v_div_scale_f32 v34, s[6:7], v33, v33, v40
	v_rcp_f32_e32 v35, v34
	s_waitcnt lgkmcnt(0)
	v_lshlrev_b32_e32 v32, 16, v32
	v_fma_f32 v36, -v34, v35, 1.0
	v_fmac_f32_e32 v35, v36, v35
	v_div_scale_f32 v36, vcc, v40, v33, v40
	v_mul_f32_e32 v37, v36, v35
	v_fma_f32 v38, -v34, v37, v36
	v_fmac_f32_e32 v37, v38, v35
	v_fma_f32 v34, -v34, v37, v36
	v_div_fmas_f32 v34, v34, v35, v37
	v_div_fixup_f32 v33, v34, v33, v40
	v_mul_f32_e32 v32, v33, v32
	v_mul_f32_e32 v33, 0xbfb8aa3b, v41
	v_exp_f32_e32 v33, v33
	v_cvt_pk_bf16_f32 v32, v32, s0
	ds_write_b16 v128, v32 offset:21824
	ds_read_u16 v32, v128 offset:22096
	v_add_f32_e32 v33, 1.0, v33
	v_div_scale_f32 v34, s[6:7], v33, v33, v41
	v_rcp_f32_e32 v35, v34
	s_waitcnt lgkmcnt(0)
	v_lshlrev_b32_e32 v32, 16, v32
	v_fma_f32 v36, -v34, v35, 1.0
	v_fmac_f32_e32 v35, v36, v35
	v_div_scale_f32 v36, vcc, v41, v33, v41
	v_mul_f32_e32 v37, v36, v35
	v_fma_f32 v38, -v34, v37, v36
	v_fmac_f32_e32 v37, v38, v35
	v_fma_f32 v34, -v34, v37, v36
	v_div_fmas_f32 v34, v34, v35, v37
	v_div_fixup_f32 v33, v34, v33, v41
	v_mul_f32_e32 v32, v33, v32
	v_mul_f32_e32 v33, 0xbfb8aa3b, v42
	v_exp_f32_e32 v33, v33
	v_cvt_pk_bf16_f32 v32, v32, s0
	ds_write_b16 v128, v32 offset:22096
	ds_read_u16 v32, v128 offset:22368
	v_add_f32_e32 v33, 1.0, v33
	v_div_scale_f32 v34, s[6:7], v33, v33, v42
	v_rcp_f32_e32 v35, v34
	s_waitcnt lgkmcnt(0)
	v_lshlrev_b32_e32 v32, 16, v32
	v_fma_f32 v36, -v34, v35, 1.0
	v_fmac_f32_e32 v35, v36, v35
	v_div_scale_f32 v36, vcc, v42, v33, v42
	v_mul_f32_e32 v37, v36, v35
	v_fma_f32 v38, -v34, v37, v36
	v_fmac_f32_e32 v37, v38, v35
	v_fma_f32 v34, -v34, v37, v36
	v_div_fmas_f32 v34, v34, v35, v37
	v_div_fixup_f32 v33, v34, v33, v42
	v_mul_f32_e32 v32, v33, v32
	v_mul_f32_e32 v33, 0xbfb8aa3b, v43
	v_exp_f32_e32 v33, v33
	v_cvt_pk_bf16_f32 v32, v32, s0
	ds_write_b16 v128, v32 offset:22368
	ds_read_u16 v32, v128 offset:22640
	v_add_f32_e32 v33, 1.0, v33
	v_div_scale_f32 v34, s[6:7], v33, v33, v43
	v_rcp_f32_e32 v35, v34
	s_waitcnt lgkmcnt(0)
; DEV u16 f2bf(float f) { return (u16)(pk2bf(f, 0.f) & 0xffffu); }
; DEV float bf2f(u16 h) { return __uint_as_float(((unsigned)h) << 16); }
; DEV float siluf_(float x) { return x / (1.0f + __expf(-x)); }
; template <int MI>
; DEV void p4_tile(const Params& p, int l, int m0, int nt, unsigned char* smem) {
;     ...
;     acc_foreach_t<MI>([&](int mi, int ni, int r, int row, int col) __attribute__((always_inline)) {
;       sC[row * LDC + col] = f2bf(bf2f(sC[row * LDC + col]) * siluf_(acc[mi][ni][r]));
;     });
	v_lshlrev_b32_e32 v32, 16, v32
	v_fma_f32 v36, -v34, v35, 1.0
	v_fmac_f32_e32 v35, v36, v35
	v_div_scale_f32 v36, vcc, v43, v33, v43
	v_mul_f32_e32 v37, v36, v35
	v_fma_f32 v38, -v34, v37, v36
	v_fmac_f32_e32 v37, v38, v35
	v_fma_f32 v34, -v34, v37, v36
	v_div_fmas_f32 v34, v34, v35, v37
	v_div_fixup_f32 v33, v34, v33, v43
	v_mul_f32_e32 v32, v33, v32
	v_mul_f32_e32 v33, 0xbfb8aa3b, v44
	v_exp_f32_e32 v33, v33
	v_cvt_pk_bf16_f32 v32, v32, s0
	ds_write_b16 v128, v32 offset:22640
	ds_read_u16 v32, v128 offset:24000
	v_add_f32_e32 v33, 1.0, v33
	v_div_scale_f32 v34, s[6:7], v33, v33, v44
	v_rcp_f32_e32 v35, v34
	s_waitcnt lgkmcnt(0)
	v_lshlrev_b32_e32 v32, 16, v32
	v_fma_f32 v36, -v34, v35, 1.0
	v_fmac_f32_e32 v35, v36, v35
	v_div_scale_f32 v36, vcc, v44, v33, v44
	v_mul_f32_e32 v37, v36, v35
	v_fma_f32 v38, -v34, v37, v36
	v_fmac_f32_e32 v37, v38, v35
	v_fma_f32 v34, -v34, v37, v36
	v_div_fmas_f32 v34, v34, v35, v37
	v_div_fixup_f32 v33, v34, v33, v44
	v_mul_f32_e32 v32, v33, v32
	v_mul_f32_e32 v33, 0xbfb8aa3b, v45
	v_exp_f32_e32 v33, v33
	v_cvt_pk_bf16_f32 v32, v32, s0
	ds_write_b16 v128, v32 offset:24000
	ds_read_u16 v32, v128 offset:24272
	v_add_f32_e32 v33, 1.0, v33
	v_div_scale_f32 v34, s[6:7], v33, v33, v45
	v_rcp_f32_e32 v35, v34
	s_waitcnt lgkmcnt(0)
	v_lshlrev_b32_e32 v32, 16, v32
	v_fma_f32 v36, -v34, v35, 1.0
	v_fmac_f32_e32 v35, v36, v35
	v_div_scale_f32 v36, vcc, v45, v33, v45
	v_mul_f32_e32 v37, v36, v35
	v_fma_f32 v38, -v34, v37, v36
	v_fmac_f32_e32 v37, v38, v35
	v_fma_f32 v34, -v34, v37, v36
	v_div_fmas_f32 v34, v34, v35, v37
	v_div_fixup_f32 v33, v34, v33, v45
	v_mul_f32_e32 v32, v33, v32
	v_mul_f32_e32 v33, 0xbfb8aa3b, v46
	v_exp_f32_e32 v33, v33
	v_cvt_pk_bf16_f32 v32, v32, s0
	ds_write_b16 v128, v32 offset:24272
	ds_read_u16 v32, v128 offset:24544
	v_add_f32_e32 v33, 1.0, v33
	v_div_scale_f32 v34, s[6:7], v33, v33, v46
	v_rcp_f32_e32 v35, v34
	s_waitcnt lgkmcnt(0)
	v_lshlrev_b32_e32 v32, 16, v32
	v_fma_f32 v36, -v34, v35, 1.0
	v_fmac_f32_e32 v35, v36, v35
	v_div_scale_f32 v36, vcc, v46, v33, v46
	v_mul_f32_e32 v37, v36, v35
	v_fma_f32 v38, -v34, v37, v36
	v_fmac_f32_e32 v37, v38, v35
	v_fma_f32 v34, -v34, v37, v36
	v_div_fmas_f32 v34, v34, v35, v37
	v_div_fixup_f32 v33, v34, v33, v46
	v_mul_f32_e32 v32, v33, v32
	v_mul_f32_e32 v33, 0xbfb8aa3b, v47
	v_exp_f32_e32 v33, v33
	v_cvt_pk_bf16_f32 v32, v32, s0
	ds_write_b16 v128, v32 offset:24544
	ds_read_u16 v32, v128 offset:24816
	v_add_f32_e32 v33, 1.0, v33
	v_div_scale_f32 v34, s[6:7], v33, v33, v47
	v_rcp_f32_e32 v35, v34
	s_waitcnt lgkmcnt(0)
	v_lshlrev_b32_e32 v32, 16, v32
	v_fma_f32 v36, -v34, v35, 1.0
	v_fmac_f32_e32 v35, v36, v35
	v_div_scale_f32 v36, vcc, v47, v33, v47
	v_mul_f32_e32 v37, v36, v35
	v_fma_f32 v38, -v34, v37, v36
	v_fmac_f32_e32 v37, v38, v35
	v_fma_f32 v34, -v34, v37, v36
	v_div_fmas_f32 v34, v34, v35, v37
	v_div_fixup_f32 v33, v34, v33, v47
	v_mul_f32_e32 v32, v33, v32
	v_mul_f32_e32 v33, 0xbfb8aa3b, v16
	v_exp_f32_e32 v33, v33
	v_cvt_pk_bf16_f32 v32, v32, s0
	ds_write_b16 v128, v32 offset:24816
	ds_read_u16 v32, v128 offset:26112
	v_add_f32_e32 v33, 1.0, v33
	v_div_scale_f32 v34, s[6:7], v33, v33, v16
	v_rcp_f32_e32 v35, v34
	s_waitcnt lgkmcnt(0)
	v_lshlrev_b32_e32 v32, 16, v32
	v_fma_f32 v36, -v34, v35, 1.0
	v_fmac_f32_e32 v35, v36, v35
	v_div_scale_f32 v36, vcc, v16, v33, v16
	v_mul_f32_e32 v37, v36, v35
	v_fma_f32 v38, -v34, v37, v36
	v_fmac_f32_e32 v37, v38, v35
	v_fma_f32 v34, -v34, v37, v36
	v_div_fmas_f32 v34, v34, v35, v37
	v_div_fixup_f32 v16, v34, v33, v16
	v_mul_f32_e32 v16, v16, v32
	v_mul_f32_e32 v32, 0xbfb8aa3b, v17
	v_exp_f32_e32 v32, v32
	v_cvt_pk_bf16_f32 v16, v16, s0
	ds_write_b16 v128, v16 offset:26112
	ds_read_u16 v16, v128 offset:26384
	v_add_f32_e32 v32, 1.0, v32
	v_div_scale_f32 v33, s[6:7], v32, v32, v17
	v_rcp_f32_e32 v34, v33
	s_waitcnt lgkmcnt(0)
	v_lshlrev_b32_e32 v16, 16, v16
	v_fma_f32 v35, -v33, v34, 1.0
	v_fmac_f32_e32 v34, v35, v34
	v_div_scale_f32 v35, vcc, v17, v32, v17
	v_mul_f32_e32 v36, v35, v34
	v_fma_f32 v37, -v33, v36, v35
	v_fmac_f32_e32 v36, v37, v34
	v_fma_f32 v33, -v33, v36, v35
	v_div_fmas_f32 v33, v33, v34, v36
	v_div_fixup_f32 v17, v33, v32, v17
	v_mul_f32_e32 v16, v17, v16
	v_mul_f32_e32 v17, 0xbfb8aa3b, v18
	v_exp_f32_e32 v17, v17
	v_cvt_pk_bf16_f32 v16, v16, s0
	ds_write_b16 v128, v16 offset:26384
	ds_read_u16 v16, v128 offset:26656
	v_add_f32_e32 v17, 1.0, v17
	v_div_scale_f32 v32, s[6:7], v17, v17, v18
	v_rcp_f32_e32 v33, v32
	s_waitcnt lgkmcnt(0)
	v_lshlrev_b32_e32 v16, 16, v16
	v_fma_f32 v34, -v32, v33, 1.0
	v_fmac_f32_e32 v33, v34, v33
	v_div_scale_f32 v34, vcc, v18, v17, v18
	v_mul_f32_e32 v35, v34, v33
	v_fma_f32 v36, -v32, v35, v34
	v_fmac_f32_e32 v35, v36, v33
	v_fma_f32 v32, -v32, v35, v34
	v_div_fmas_f32 v32, v32, v33, v35
	v_div_fixup_f32 v17, v32, v17, v18
	v_mul_f32_e32 v16, v17, v16
	v_mul_f32_e32 v17, 0xbfb8aa3b, v19
	v_exp_f32_e32 v17, v17
	v_cvt_pk_bf16_f32 v16, v16, s0
	ds_write_b16 v128, v16 offset:26656
	ds_read_u16 v16, v128 offset:26928
	v_add_f32_e32 v17, 1.0, v17
	v_div_scale_f32 v18, s[6:7], v17, v17, v19
	v_rcp_f32_e32 v32, v18
	s_waitcnt lgkmcnt(0)
	v_lshlrev_b32_e32 v16, 16, v16
	v_fma_f32 v33, -v18, v32, 1.0
	v_fmac_f32_e32 v32, v33, v32
	v_div_scale_f32 v33, vcc, v19, v17, v19
	v_mul_f32_e32 v34, v33, v32
	v_fma_f32 v35, -v18, v34, v33
	v_fmac_f32_e32 v34, v35, v32
	v_fma_f32 v18, -v18, v34, v33
	v_div_fmas_f32 v18, v18, v32, v34
	v_div_fixup_f32 v17, v18, v17, v19
	v_mul_f32_e32 v16, v17, v16
	v_mul_f32_e32 v17, 0xbfb8aa3b, v20
	v_exp_f32_e32 v17, v17
	v_cvt_pk_bf16_f32 v16, v16, s0
	ds_write_b16 v128, v16 offset:26928
	ds_read_u16 v16, v128 offset:28288
	v_add_f32_e32 v17, 1.0, v17
	v_div_scale_f32 v18, s[6:7], v17, v17, v20
	v_rcp_f32_e32 v19, v18
	s_waitcnt lgkmcnt(0)
; DEV u16 f2bf(float f) { return (u16)(pk2bf(f, 0.f) & 0xffffu); }
; DEV float bf2f(u16 h) { return __uint_as_float(((unsigned)h) << 16); }
; DEV float siluf_(float x) { return x / (1.0f + __expf(-x)); }
; template <int MI>
; DEV void p4_tile(const Params& p, int l, int m0, int nt, unsigned char* smem) {
;     ...
;     acc_foreach_t<MI>([&](int mi, int ni, int r, int row, int col) __attribute__((always_inline)) {
;       sC[row * LDC + col] = f2bf(bf2f(sC[row * LDC + col]) * siluf_(acc[mi][ni][r]));
;     });
	v_lshlrev_b32_e32 v16, 16, v16
	v_fma_f32 v32, -v18, v19, 1.0
	v_fmac_f32_e32 v19, v32, v19
	v_div_scale_f32 v32, vcc, v20, v17, v20
	v_mul_f32_e32 v33, v32, v19
	v_fma_f32 v34, -v18, v33, v32
	v_fmac_f32_e32 v33, v34, v19
	v_fma_f32 v18, -v18, v33, v32
	v_div_fmas_f32 v18, v18, v19, v33
	v_div_fixup_f32 v17, v18, v17, v20
	v_mul_f32_e32 v16, v17, v16
	v_mul_f32_e32 v17, 0xbfb8aa3b, v21
	v_exp_f32_e32 v17, v17
	v_cvt_pk_bf16_f32 v16, v16, s0
	ds_write_b16 v128, v16 offset:28288
	ds_read_u16 v16, v128 offset:28560
	v_add_f32_e32 v17, 1.0, v17
	v_div_scale_f32 v18, s[6:7], v17, v17, v21
	v_rcp_f32_e32 v19, v18
	s_waitcnt lgkmcnt(0)
	v_lshlrev_b32_e32 v16, 16, v16
	v_fma_f32 v20, -v18, v19, 1.0
	v_fmac_f32_e32 v19, v20, v19
	v_div_scale_f32 v20, vcc, v21, v17, v21
	v_mul_f32_e32 v32, v20, v19
	v_fma_f32 v33, -v18, v32, v20
	v_fmac_f32_e32 v32, v33, v19
	v_fma_f32 v18, -v18, v32, v20
	v_div_fmas_f32 v18, v18, v19, v32
	v_div_fixup_f32 v17, v18, v17, v21
	v_mul_f32_e32 v16, v17, v16
	v_mul_f32_e32 v17, 0xbfb8aa3b, v22
	v_exp_f32_e32 v17, v17
	v_cvt_pk_bf16_f32 v16, v16, s0
	ds_write_b16 v128, v16 offset:28560
	ds_read_u16 v16, v128 offset:28832
	v_add_f32_e32 v17, 1.0, v17
	v_div_scale_f32 v18, s[6:7], v17, v17, v22
	v_rcp_f32_e32 v19, v18
	s_waitcnt lgkmcnt(0)
	v_lshlrev_b32_e32 v16, 16, v16
	v_fma_f32 v20, -v18, v19, 1.0
	v_fmac_f32_e32 v19, v20, v19
	v_div_scale_f32 v20, vcc, v22, v17, v22
	v_mul_f32_e32 v21, v20, v19
	v_fma_f32 v32, -v18, v21, v20
	v_fmac_f32_e32 v21, v32, v19
	v_fma_f32 v18, -v18, v21, v20
	v_div_fmas_f32 v18, v18, v19, v21
	v_div_fixup_f32 v17, v18, v17, v22
	v_mul_f32_e32 v16, v17, v16
	v_mul_f32_e32 v17, 0xbfb8aa3b, v23
	v_exp_f32_e32 v17, v17
	v_cvt_pk_bf16_f32 v16, v16, s0
	ds_write_b16 v128, v16 offset:28832
	ds_read_u16 v16, v128 offset:29104
	v_add_f32_e32 v17, 1.0, v17
	v_div_scale_f32 v18, s[6:7], v17, v17, v23
	v_rcp_f32_e32 v19, v18
	s_waitcnt lgkmcnt(0)
	v_lshlrev_b32_e32 v16, 16, v16
	v_fma_f32 v20, -v18, v19, 1.0
	v_fmac_f32_e32 v19, v20, v19
	v_div_scale_f32 v20, vcc, v23, v17, v23
	v_mul_f32_e32 v21, v20, v19
	v_fma_f32 v22, -v18, v21, v20
	v_fmac_f32_e32 v21, v22, v19
	v_fma_f32 v18, -v18, v21, v20
	v_div_fmas_f32 v18, v18, v19, v21
	v_div_fixup_f32 v17, v18, v17, v23
	v_mul_f32_e32 v16, v17, v16
	v_mul_f32_e32 v17, 0xbfb8aa3b, v24
	v_exp_f32_e32 v17, v17
	v_cvt_pk_bf16_f32 v16, v16, s0
	ds_write_b16 v128, v16 offset:29104
	ds_read_u16 v16, v128 offset:30464
	v_add_f32_e32 v17, 1.0, v17
	v_div_scale_f32 v18, s[6:7], v17, v17, v24
	v_rcp_f32_e32 v19, v18
	s_waitcnt lgkmcnt(0)
	v_lshlrev_b32_e32 v16, 16, v16
	v_fma_f32 v20, -v18, v19, 1.0
	v_fmac_f32_e32 v19, v20, v19
	v_div_scale_f32 v20, vcc, v24, v17, v24
	v_mul_f32_e32 v21, v20, v19
	v_fma_f32 v22, -v18, v21, v20
	v_fmac_f32_e32 v21, v22, v19
	v_fma_f32 v18, -v18, v21, v20
	v_div_fmas_f32 v18, v18, v19, v21
	v_div_fixup_f32 v17, v18, v17, v24
	v_mul_f32_e32 v16, v17, v16
	v_mul_f32_e32 v17, 0xbfb8aa3b, v25
	v_exp_f32_e32 v17, v17
	v_cvt_pk_bf16_f32 v16, v16, s0
	ds_write_b16 v128, v16 offset:30464
	ds_read_u16 v16, v128 offset:30736
	v_add_f32_e32 v17, 1.0, v17
	v_div_scale_f32 v18, s[6:7], v17, v17, v25
	v_rcp_f32_e32 v19, v18
	s_waitcnt lgkmcnt(0)
	v_lshlrev_b32_e32 v16, 16, v16
	v_fma_f32 v20, -v18, v19, 1.0
	v_fmac_f32_e32 v19, v20, v19
	v_div_scale_f32 v20, vcc, v25, v17, v25
	v_mul_f32_e32 v21, v20, v19
	v_fma_f32 v22, -v18, v21, v20
	v_fmac_f32_e32 v21, v22, v19
	v_fma_f32 v18, -v18, v21, v20
	v_div_fmas_f32 v18, v18, v19, v21
	v_div_fixup_f32 v17, v18, v17, v25
	v_mul_f32_e32 v16, v17, v16
	v_mul_f32_e32 v17, 0xbfb8aa3b, v26
	v_exp_f32_e32 v17, v17
	v_cvt_pk_bf16_f32 v16, v16, s0
	ds_write_b16 v128, v16 offset:30736
	ds_read_u16 v16, v128 offset:31008
	v_add_f32_e32 v17, 1.0, v17
	v_div_scale_f32 v18, s[6:7], v17, v17, v26
	v_rcp_f32_e32 v19, v18
	s_waitcnt lgkmcnt(0)
	v_lshlrev_b32_e32 v16, 16, v16
	v_fma_f32 v20, -v18, v19, 1.0
	v_fmac_f32_e32 v19, v20, v19
	v_div_scale_f32 v20, vcc, v26, v17, v26
	v_mul_f32_e32 v21, v20, v19
	v_fma_f32 v22, -v18, v21, v20
	v_fmac_f32_e32 v21, v22, v19
	v_fma_f32 v18, -v18, v21, v20
	v_div_fmas_f32 v18, v18, v19, v21
	v_div_fixup_f32 v17, v18, v17, v26
	v_mul_f32_e32 v16, v17, v16
	v_mul_f32_e32 v17, 0xbfb8aa3b, v27
	v_exp_f32_e32 v17, v17
	v_cvt_pk_bf16_f32 v16, v16, s0
	ds_write_b16 v128, v16 offset:31008
	ds_read_u16 v16, v128 offset:31280
	v_add_f32_e32 v17, 1.0, v17
	v_div_scale_f32 v18, s[6:7], v17, v17, v27
	v_rcp_f32_e32 v19, v18
	s_waitcnt lgkmcnt(0)
	v_lshlrev_b32_e32 v16, 16, v16
	v_fma_f32 v20, -v18, v19, 1.0
	v_fmac_f32_e32 v19, v20, v19
	v_div_scale_f32 v20, vcc, v27, v17, v27
	v_mul_f32_e32 v21, v20, v19
	v_fma_f32 v22, -v18, v21, v20
	v_fmac_f32_e32 v21, v22, v19
	v_fma_f32 v18, -v18, v21, v20
	v_div_fmas_f32 v18, v18, v19, v21
	v_div_fixup_f32 v17, v18, v17, v27
	v_mul_f32_e32 v16, v17, v16
	v_mul_f32_e32 v17, 0xbfb8aa3b, v28
	v_exp_f32_e32 v17, v17
	v_cvt_pk_bf16_f32 v16, v16, s0
	ds_write_b16 v128, v16 offset:31280
	ds_read_u16 v16, v128 offset:32640
	v_add_f32_e32 v17, 1.0, v17
	v_div_scale_f32 v18, s[6:7], v17, v17, v28
	v_rcp_f32_e32 v19, v18
	s_waitcnt lgkmcnt(0)
	v_lshlrev_b32_e32 v16, 16, v16
	v_fma_f32 v20, -v18, v19, 1.0
	v_fmac_f32_e32 v19, v20, v19
	v_div_scale_f32 v20, vcc, v28, v17, v28
	v_mul_f32_e32 v21, v20, v19
	v_fma_f32 v22, -v18, v21, v20
	v_fmac_f32_e32 v21, v22, v19
	v_fma_f32 v18, -v18, v21, v20
	v_div_fmas_f32 v18, v18, v19, v21
	v_div_fixup_f32 v17, v18, v17, v28
	v_mul_f32_e32 v16, v17, v16
	v_mul_f32_e32 v17, 0xbfb8aa3b, v29
	v_exp_f32_e32 v17, v17
	v_cvt_pk_bf16_f32 v16, v16, s0
	ds_write_b16 v128, v16 offset:32640
	ds_read_u16 v16, v128 offset:32912
	v_add_f32_e32 v17, 1.0, v17
	v_div_scale_f32 v18, s[6:7], v17, v17, v29
	v_rcp_f32_e32 v19, v18
	s_waitcnt lgkmcnt(0)
; DEV u16 f2bf(float f) { return (u16)(pk2bf(f, 0.f) & 0xffffu); }
; DEV float bf2f(u16 h) { return __uint_as_float(((unsigned)h) << 16); }
; DEV float siluf_(float x) { return x / (1.0f + __expf(-x)); }
; template <int MI>
; DEV void p4_tile(const Params& p, int l, int m0, int nt, unsigned char* smem) {
;     ...
;     acc_foreach_t<MI>([&](int mi, int ni, int r, int row, int col) __attribute__((always_inline)) {
;       sC[row * LDC + col] = f2bf(bf2f(sC[row * LDC + col]) * siluf_(acc[mi][ni][r]));
;     });
	v_lshlrev_b32_e32 v16, 16, v16
	v_fma_f32 v20, -v18, v19, 1.0
	v_fmac_f32_e32 v19, v20, v19
	v_div_scale_f32 v20, vcc, v29, v17, v29
	v_mul_f32_e32 v21, v20, v19
	v_fma_f32 v22, -v18, v21, v20
	v_fmac_f32_e32 v21, v22, v19
	v_fma_f32 v18, -v18, v21, v20
	v_div_fmas_f32 v18, v18, v19, v21
	v_div_fixup_f32 v17, v18, v17, v29
	v_mul_f32_e32 v16, v17, v16
	v_mul_f32_e32 v17, 0xbfb8aa3b, v30
	v_exp_f32_e32 v17, v17
	v_cvt_pk_bf16_f32 v16, v16, s0
	ds_write_b16 v128, v16 offset:32912
	ds_read_u16 v16, v128 offset:33184
	v_add_f32_e32 v17, 1.0, v17
	v_div_scale_f32 v18, s[6:7], v17, v17, v30
	v_rcp_f32_e32 v19, v18
	s_waitcnt lgkmcnt(0)
	v_lshlrev_b32_e32 v16, 16, v16
	v_fma_f32 v20, -v18, v19, 1.0
	v_fmac_f32_e32 v19, v20, v19
	v_div_scale_f32 v20, vcc, v30, v17, v30
	v_mul_f32_e32 v21, v20, v19
	v_fma_f32 v22, -v18, v21, v20
	v_fmac_f32_e32 v21, v22, v19
	v_fma_f32 v18, -v18, v21, v20
	v_div_fmas_f32 v18, v18, v19, v21
	v_div_fixup_f32 v17, v18, v17, v30
	v_mul_f32_e32 v16, v17, v16
	v_mul_f32_e32 v17, 0xbfb8aa3b, v31
	v_exp_f32_e32 v17, v17
	v_cvt_pk_bf16_f32 v16, v16, s0
	ds_write_b16 v128, v16 offset:33184
	ds_read_u16 v16, v128 offset:33456
	v_add_f32_e32 v17, 1.0, v17
	v_div_scale_f32 v18, s[6:7], v17, v17, v31
	v_rcp_f32_e32 v19, v18
	s_waitcnt lgkmcnt(0)
	v_lshlrev_b32_e32 v16, 16, v16
	v_fma_f32 v20, -v18, v19, 1.0
	v_fmac_f32_e32 v19, v20, v19
	v_div_scale_f32 v20, vcc, v31, v17, v31
	v_mul_f32_e32 v21, v20, v19
	v_fma_f32 v22, -v18, v21, v20
	v_fmac_f32_e32 v21, v22, v19
	v_fma_f32 v18, -v18, v21, v20
	v_div_fmas_f32 v18, v18, v19, v21
	v_div_fixup_f32 v17, v18, v17, v31
	v_mul_f32_e32 v16, v17, v16
	v_mul_f32_e32 v17, 0xbfb8aa3b, v0
	v_exp_f32_e32 v17, v17
	v_cvt_pk_bf16_f32 v16, v16, s0
	ds_write_b16 v128, v16 offset:33456
	ds_read_u16 v16, v128 offset:26176
	v_add_f32_e32 v17, 1.0, v17
	v_div_scale_f32 v18, s[6:7], v17, v17, v0
	v_rcp_f32_e32 v19, v18
	s_waitcnt lgkmcnt(0)
	v_lshlrev_b32_e32 v16, 16, v16
	v_fma_f32 v20, -v18, v19, 1.0
	v_fmac_f32_e32 v19, v20, v19
	v_div_scale_f32 v20, vcc, v0, v17, v0
	v_mul_f32_e32 v21, v20, v19
	v_fma_f32 v22, -v18, v21, v20
	v_fmac_f32_e32 v21, v22, v19
	v_fma_f32 v18, -v18, v21, v20
	v_div_fmas_f32 v18, v18, v19, v21
	v_div_fixup_f32 v0, v18, v17, v0
	v_mul_f32_e32 v0, v0, v16
	v_mul_f32_e32 v16, 0xbfb8aa3b, v1
	v_exp_f32_e32 v16, v16
	v_cvt_pk_bf16_f32 v0, v0, s0
	ds_write_b16 v128, v0 offset:26176
	ds_read_u16 v0, v128 offset:26448
	v_add_f32_e32 v16, 1.0, v16
	v_div_scale_f32 v17, s[6:7], v16, v16, v1
	v_rcp_f32_e32 v18, v17
	s_waitcnt lgkmcnt(0)
	v_lshlrev_b32_e32 v0, 16, v0
	v_fma_f32 v19, -v17, v18, 1.0
	v_fmac_f32_e32 v18, v19, v18
	v_div_scale_f32 v19, vcc, v1, v16, v1
	v_mul_f32_e32 v20, v19, v18
	v_fma_f32 v21, -v17, v20, v19
	v_fmac_f32_e32 v20, v21, v18
	v_fma_f32 v17, -v17, v20, v19
	v_div_fmas_f32 v17, v17, v18, v20
	v_div_fixup_f32 v1, v17, v16, v1
	v_mul_f32_e32 v0, v1, v0
	v_mul_f32_e32 v1, 0xbfb8aa3b, v2
	v_exp_f32_e32 v1, v1
	v_cvt_pk_bf16_f32 v0, v0, s0
	ds_write_b16 v128, v0 offset:26448
	ds_read_u16 v0, v128 offset:26720
	v_add_f32_e32 v1, 1.0, v1
	v_div_scale_f32 v16, s[6:7], v1, v1, v2
	v_rcp_f32_e32 v17, v16
	s_waitcnt lgkmcnt(0)
	v_lshlrev_b32_e32 v0, 16, v0
	v_fma_f32 v18, -v16, v17, 1.0
	v_fmac_f32_e32 v17, v18, v17
	v_div_scale_f32 v18, vcc, v2, v1, v2
	v_mul_f32_e32 v19, v18, v17
	v_fma_f32 v20, -v16, v19, v18
	v_fmac_f32_e32 v19, v20, v17
	v_fma_f32 v16, -v16, v19, v18
	v_div_fmas_f32 v16, v16, v17, v19
	v_div_fixup_f32 v1, v16, v1, v2
	v_mul_f32_e32 v0, v1, v0
	v_mul_f32_e32 v1, 0xbfb8aa3b, v3
	v_exp_f32_e32 v1, v1
	v_cvt_pk_bf16_f32 v0, v0, s0
	ds_write_b16 v128, v0 offset:26720
	ds_read_u16 v0, v128 offset:26992
	v_add_f32_e32 v1, 1.0, v1
	v_div_scale_f32 v2, s[6:7], v1, v1, v3
	v_rcp_f32_e32 v16, v2
	s_waitcnt lgkmcnt(0)
	v_lshlrev_b32_e32 v0, 16, v0
	v_fma_f32 v17, -v2, v16, 1.0
	v_fmac_f32_e32 v16, v17, v16
	v_div_scale_f32 v17, vcc, v3, v1, v3
	v_mul_f32_e32 v18, v17, v16
	v_fma_f32 v19, -v2, v18, v17
	v_fmac_f32_e32 v18, v19, v16
	v_fma_f32 v2, -v2, v18, v17
	v_div_fmas_f32 v2, v2, v16, v18
	v_div_fixup_f32 v1, v2, v1, v3
	v_mul_f32_e32 v0, v1, v0
	v_mul_f32_e32 v1, 0xbfb8aa3b, v4
	v_exp_f32_e32 v1, v1
	v_cvt_pk_bf16_f32 v0, v0, s0
	ds_write_b16 v128, v0 offset:26992
	ds_read_u16 v0, v128 offset:28352
	v_add_f32_e32 v1, 1.0, v1
	v_div_scale_f32 v2, s[6:7], v1, v1, v4
	v_rcp_f32_e32 v3, v2
	s_waitcnt lgkmcnt(0)
	v_lshlrev_b32_e32 v0, 16, v0
	v_fma_f32 v16, -v2, v3, 1.0
	v_fmac_f32_e32 v3, v16, v3
	v_div_scale_f32 v16, vcc, v4, v1, v4
	v_mul_f32_e32 v17, v16, v3
	v_fma_f32 v18, -v2, v17, v16
	v_fmac_f32_e32 v17, v18, v3
	v_fma_f32 v2, -v2, v17, v16
	v_div_fmas_f32 v2, v2, v3, v17
	v_div_fixup_f32 v1, v2, v1, v4
	v_mul_f32_e32 v0, v1, v0
	v_mul_f32_e32 v1, 0xbfb8aa3b, v5
	v_exp_f32_e32 v1, v1
	v_cvt_pk_bf16_f32 v0, v0, s0
	ds_write_b16 v128, v0 offset:28352
	ds_read_u16 v0, v128 offset:28624
	v_add_f32_e32 v1, 1.0, v1
	v_div_scale_f32 v2, s[6:7], v1, v1, v5
	v_rcp_f32_e32 v3, v2
	s_waitcnt lgkmcnt(0)
	v_lshlrev_b32_e32 v0, 16, v0
	v_fma_f32 v4, -v2, v3, 1.0
	v_fmac_f32_e32 v3, v4, v3
	v_div_scale_f32 v4, vcc, v5, v1, v5
	v_mul_f32_e32 v16, v4, v3
	v_fma_f32 v17, -v2, v16, v4
	v_fmac_f32_e32 v16, v17, v3
	v_fma_f32 v2, -v2, v16, v4
	v_div_fmas_f32 v2, v2, v3, v16
	v_div_fixup_f32 v1, v2, v1, v5
	v_mul_f32_e32 v0, v1, v0
	v_mul_f32_e32 v1, 0xbfb8aa3b, v6
	v_exp_f32_e32 v1, v1
	v_cvt_pk_bf16_f32 v0, v0, s0
	ds_write_b16 v128, v0 offset:28624
	ds_read_u16 v0, v128 offset:28896
	v_add_f32_e32 v1, 1.0, v1
	v_div_scale_f32 v2, s[6:7], v1, v1, v6
	v_rcp_f32_e32 v3, v2
	s_waitcnt lgkmcnt(0)
; DEV u16 f2bf(float f) { return (u16)(pk2bf(f, 0.f) & 0xffffu); }
; DEV float bf2f(u16 h) { return __uint_as_float(((unsigned)h) << 16); }
; DEV float siluf_(float x) { return x / (1.0f + __expf(-x)); }
; template <int MI>
; DEV void tile_store_t(unsigned char* smem, u16* dst, size_t ldd) {
;   const u16* sC = (const u16*)smem;
;   __syncthreads();
; template <int MI>
; DEV void p4_tile(const Params& p, int l, int m0, int nt, unsigned char* smem) {
;     ...
;     acc_foreach_t<MI>([&](int mi, int ni, int r, int row, int col) __attribute__((always_inline)) {
;       sC[row * LDC + col] = f2bf(bf2f(sC[row * LDC + col]) * siluf_(acc[mi][ni][r]));
;     });
;     tile_store_t<MI>(smem, YA + (size_t)m0 * 1024 + n0, 1024);
	v_lshlrev_b32_e32 v0, 16, v0
	v_fma_f32 v4, -v2, v3, 1.0
	v_fmac_f32_e32 v3, v4, v3
	v_div_scale_f32 v4, vcc, v6, v1, v6
	v_mul_f32_e32 v5, v4, v3
	v_fma_f32 v16, -v2, v5, v4
	v_fmac_f32_e32 v5, v16, v3
	v_fma_f32 v2, -v2, v5, v4
	v_div_fmas_f32 v2, v2, v3, v5
	v_div_fixup_f32 v1, v2, v1, v6
	v_mul_f32_e32 v0, v1, v0
	v_mul_f32_e32 v1, 0xbfb8aa3b, v7
	v_exp_f32_e32 v1, v1
	v_cvt_pk_bf16_f32 v0, v0, s0
	ds_write_b16 v128, v0 offset:28896
	ds_read_u16 v0, v128 offset:29168
	v_add_f32_e32 v1, 1.0, v1
	v_div_scale_f32 v2, s[6:7], v1, v1, v7
	v_rcp_f32_e32 v3, v2
	s_waitcnt lgkmcnt(0)
	v_lshlrev_b32_e32 v0, 16, v0
	v_fma_f32 v4, -v2, v3, 1.0
	v_fmac_f32_e32 v3, v4, v3
	v_div_scale_f32 v4, vcc, v7, v1, v7
	v_mul_f32_e32 v5, v4, v3
	v_fma_f32 v6, -v2, v5, v4
	v_fmac_f32_e32 v5, v6, v3
	v_fma_f32 v2, -v2, v5, v4
	v_div_fmas_f32 v2, v2, v3, v5
	v_div_fixup_f32 v1, v2, v1, v7
	v_mul_f32_e32 v0, v1, v0
	v_mul_f32_e32 v1, 0xbfb8aa3b, v8
	v_exp_f32_e32 v1, v1
	v_cvt_pk_bf16_f32 v0, v0, s0
	ds_write_b16 v128, v0 offset:29168
	ds_read_u16 v0, v128 offset:30528
	v_add_f32_e32 v1, 1.0, v1
	v_div_scale_f32 v2, s[6:7], v1, v1, v8
	v_rcp_f32_e32 v3, v2
	s_waitcnt lgkmcnt(0)
	v_lshlrev_b32_e32 v0, 16, v0
	v_fma_f32 v4, -v2, v3, 1.0
	v_fmac_f32_e32 v3, v4, v3
	v_div_scale_f32 v4, vcc, v8, v1, v8
	v_mul_f32_e32 v5, v4, v3
	v_fma_f32 v6, -v2, v5, v4
	v_fmac_f32_e32 v5, v6, v3
	v_fma_f32 v2, -v2, v5, v4
	v_div_fmas_f32 v2, v2, v3, v5
	v_div_fixup_f32 v1, v2, v1, v8
	v_mul_f32_e32 v0, v1, v0
	v_mul_f32_e32 v1, 0xbfb8aa3b, v9
	v_exp_f32_e32 v1, v1
	v_cvt_pk_bf16_f32 v0, v0, s0
	ds_write_b16 v128, v0 offset:30528
	ds_read_u16 v0, v128 offset:30800
	v_add_f32_e32 v1, 1.0, v1
	v_div_scale_f32 v2, s[6:7], v1, v1, v9
	v_rcp_f32_e32 v3, v2
	s_waitcnt lgkmcnt(0)
	v_lshlrev_b32_e32 v0, 16, v0
	v_fma_f32 v4, -v2, v3, 1.0
	v_fmac_f32_e32 v3, v4, v3
	v_div_scale_f32 v4, vcc, v9, v1, v9
	v_mul_f32_e32 v5, v4, v3
	v_fma_f32 v6, -v2, v5, v4
	v_fmac_f32_e32 v5, v6, v3
	v_fma_f32 v2, -v2, v5, v4
	v_div_fmas_f32 v2, v2, v3, v5
	v_div_fixup_f32 v1, v2, v1, v9
	v_mul_f32_e32 v0, v1, v0
	v_mul_f32_e32 v1, 0xbfb8aa3b, v10
	v_exp_f32_e32 v1, v1
	v_cvt_pk_bf16_f32 v0, v0, s0
	ds_write_b16 v128, v0 offset:30800
	ds_read_u16 v0, v128 offset:31072
	v_add_f32_e32 v1, 1.0, v1
	v_div_scale_f32 v2, s[6:7], v1, v1, v10
	v_rcp_f32_e32 v3, v2
	s_waitcnt lgkmcnt(0)
	v_lshlrev_b32_e32 v0, 16, v0
	v_fma_f32 v4, -v2, v3, 1.0
	v_fmac_f32_e32 v3, v4, v3
	v_div_scale_f32 v4, vcc, v10, v1, v10
	v_mul_f32_e32 v5, v4, v3
	v_fma_f32 v6, -v2, v5, v4
	v_fmac_f32_e32 v5, v6, v3
	v_fma_f32 v2, -v2, v5, v4
	v_div_fmas_f32 v2, v2, v3, v5
	v_div_fixup_f32 v1, v2, v1, v10
	v_mul_f32_e32 v0, v1, v0
	v_mul_f32_e32 v1, 0xbfb8aa3b, v11
	v_exp_f32_e32 v1, v1
	v_cvt_pk_bf16_f32 v0, v0, s0
	ds_write_b16 v128, v0 offset:31072
	ds_read_u16 v0, v128 offset:31344
	v_add_f32_e32 v1, 1.0, v1
	v_div_scale_f32 v2, s[6:7], v1, v1, v11
	v_rcp_f32_e32 v3, v2
	s_waitcnt lgkmcnt(0)
	v_lshlrev_b32_e32 v0, 16, v0
	v_fma_f32 v4, -v2, v3, 1.0
	v_fmac_f32_e32 v3, v4, v3
	v_div_scale_f32 v4, vcc, v11, v1, v11
	v_mul_f32_e32 v5, v4, v3
	v_fma_f32 v6, -v2, v5, v4
	v_fmac_f32_e32 v5, v6, v3
	v_fma_f32 v2, -v2, v5, v4
	v_div_fmas_f32 v2, v2, v3, v5
	v_div_fixup_f32 v1, v2, v1, v11
	v_mul_f32_e32 v0, v1, v0
	v_mul_f32_e32 v1, 0xbfb8aa3b, v12
	v_exp_f32_e32 v1, v1
	v_cvt_pk_bf16_f32 v0, v0, s0
	ds_write_b16 v128, v0 offset:31344
	ds_read_u16 v0, v128 offset:32704
	v_add_f32_e32 v1, 1.0, v1
	v_div_scale_f32 v2, s[6:7], v1, v1, v12
	v_rcp_f32_e32 v3, v2
	s_waitcnt lgkmcnt(0)
	v_lshlrev_b32_e32 v0, 16, v0
	v_fma_f32 v4, -v2, v3, 1.0
	v_fmac_f32_e32 v3, v4, v3
	v_div_scale_f32 v4, vcc, v12, v1, v12
	v_mul_f32_e32 v5, v4, v3
	v_fma_f32 v6, -v2, v5, v4
	v_fmac_f32_e32 v5, v6, v3
	v_fma_f32 v2, -v2, v5, v4
	v_div_fmas_f32 v2, v2, v3, v5
	v_div_fixup_f32 v1, v2, v1, v12
	v_mul_f32_e32 v0, v1, v0
	v_mul_f32_e32 v1, 0xbfb8aa3b, v13
	v_exp_f32_e32 v1, v1
	v_cvt_pk_bf16_f32 v0, v0, s0
	ds_write_b16 v128, v0 offset:32704
	ds_read_u16 v0, v128 offset:32976
	v_add_f32_e32 v1, 1.0, v1
	v_div_scale_f32 v2, s[6:7], v1, v1, v13
	v_rcp_f32_e32 v3, v2
	s_waitcnt lgkmcnt(0)
	v_lshlrev_b32_e32 v0, 16, v0
	v_fma_f32 v4, -v2, v3, 1.0
	v_fmac_f32_e32 v3, v4, v3
	v_div_scale_f32 v4, vcc, v13, v1, v13
	v_mul_f32_e32 v5, v4, v3
	v_fma_f32 v6, -v2, v5, v4
	v_fmac_f32_e32 v5, v6, v3
	v_fma_f32 v2, -v2, v5, v4
	v_div_fmas_f32 v2, v2, v3, v5
	v_div_fixup_f32 v1, v2, v1, v13
	v_mul_f32_e32 v0, v1, v0
	v_mul_f32_e32 v1, 0xbfb8aa3b, v14
	v_exp_f32_e32 v1, v1
	v_cvt_pk_bf16_f32 v0, v0, s0
	ds_write_b16 v128, v0 offset:32976
	ds_read_u16 v0, v128 offset:33248
	v_add_f32_e32 v1, 1.0, v1
	v_div_scale_f32 v2, s[6:7], v1, v1, v14
	v_rcp_f32_e32 v3, v2
	s_waitcnt lgkmcnt(0)
	v_lshlrev_b32_e32 v0, 16, v0
	v_fma_f32 v4, -v2, v3, 1.0
	v_fmac_f32_e32 v3, v4, v3
	v_div_scale_f32 v4, vcc, v14, v1, v14
	v_mul_f32_e32 v5, v4, v3
	v_fma_f32 v6, -v2, v5, v4
	v_fmac_f32_e32 v5, v6, v3
	v_fma_f32 v2, -v2, v5, v4
	v_div_fmas_f32 v2, v2, v3, v5
	v_div_fixup_f32 v1, v2, v1, v14
	v_mul_f32_e32 v0, v1, v0
	v_mul_f32_e32 v1, 0xbfb8aa3b, v15
	v_exp_f32_e32 v1, v1
	v_cvt_pk_bf16_f32 v0, v0, s0
	ds_write_b16 v128, v0 offset:33248
	ds_read_u16 v0, v128 offset:33520
	v_add_f32_e32 v1, 1.0, v1
	v_div_scale_f32 v2, s[6:7], v1, v1, v15
	v_rcp_f32_e32 v3, v2
	s_waitcnt lgkmcnt(0)
	v_lshlrev_b32_e32 v0, 16, v0
	s_mov_b64 s[6:7], 0
	v_fma_f32 v4, -v2, v3, 1.0
	v_fmac_f32_e32 v3, v4, v3
	v_div_scale_f32 v4, vcc, v15, v1, v15
	v_mul_f32_e32 v5, v4, v3
	v_fma_f32 v6, -v2, v5, v4
	v_fmac_f32_e32 v5, v6, v3
	v_fma_f32 v2, -v2, v5, v4
	v_div_fmas_f32 v2, v2, v3, v5
	v_div_fixup_f32 v1, v2, v1, v15
	v_mul_f32_e32 v0, v1, v0
	v_cvt_pk_bf16_f32 v0, v0, s0
	ds_write_b16 v128, v0 offset:33520
	v_mov_b32_e32 v0, v232
	s_waitcnt lgkmcnt(0)
	s_barrier
